# early2 + tail priority 2 + faster wake, plus half of the LDS-DMA loads switched to the saddr form (SGPR base + 32-bit VGPR offset): 8 fewer 64-bit VALU adds per K-iteration in the load segments
# baseline (speedup 1.0000x reference)
; #define PG8_STAGE(bufoff, gbase, voff) do { _Pragma("unroll") for (int _i = 0; _i < 2; ++_i) \
;         __builtin_amdgcn_global_load_lds((const unsigned*)((const char*)(gbase) + (voff)[_i]), (PG8_LAS unsigned*)(lds + (bufoff) + ldsw + _i * 8192), 16, 0, 0); } while (0)
; #define PG8_LDA(dst, b, h) do { _Pragma("unroll") for (int m = 0; m < 4; ++m) _Pragma("unroll") for (int k = 0; k < 2; ++k) dst[m][k] = *(const PG8_LAS bf16x8*)(lds + PG8_SA(b, h) + aoff + m * 2048 + k * 1024); } while (0)
; #define PG8_LDB(dst, b, h) do { _Pragma("unroll") for (int n = 0; n < 2; ++n) _Pragma("unroll") for (int k = 0; k < 2; ++k) dst[n][k] = *(const PG8_LAS bf16x8*)(lds + PG8_SB(b, h) + boff + n * 2048 + k * 1024); } while (0)
; #define PG8_MMA(ai, bj, At, Bt) do { __builtin_amdgcn_s_setprio(1); _Pragma("unroll") for (int m = 0; m < 4; ++m) _Pragma("unroll") for (int n = 0; n < 2; ++n) _Pragma("unroll") for (int k = 0; k < 2; ++k) \
;         acc[ai][bj][m][n] = __builtin_amdgcn_mfma_f32_16x16x32_bf16(Bt[n][k], At[m][k], acc[ai][bj][m][n], 0, 0, 0); __builtin_amdgcn_s_setprio(0); } while (0)
; #define PG8_WAIT_V(n) asm volatile("s_waitcnt vmcnt(" #n ")" ::: "memory")
; #define PG8_WAIT_L(n) asm volatile("s_waitcnt lgkmcnt(" #n ")" ::: "memory")
; #define PG8_BAR __builtin_amdgcn_s_barrier()
; template <class Epi, class Sched, bool ALIGN_EPI = false, bool SP2 = false>
; __device__ __forceinline__ void gemm_phase(PG8_LAS unsigned char* lds, const Gemm g, const Sched& S, const Epi& E) {
;     ...
;             const bool last = (t == nt - 2);
;             const char* a1 = cA + (size_t)(t + 1) * kstep;
;             const char* a2 = last ? nA : cA + (size_t)(t + 2) * kstep; const char* b2 = last ? nB : cB + (size_t)(t + 2) * kstep;
;             const char* a3 = a2 + kstep; const char* b3 = b2 + kstep;
;             if constexpr (SP2) {
;             PG8_LDB(B0, 0, 0); PG8_LDB(B1, 0, 1); PG8_SCHED; PG8_LDA(At, 0, 0); PG8_STAGE(PG8_SA(1, 1), a1 + hstep, voffA);
;             PG8_WAIT_V(8); PG8_WAIT_L(0); PG8_BAR; PG8_MMA(0, 0, At, B0); PG8_MMA(0, 1, At, B1); PG8_BAR; PG8_SCHED;
;             PG8_LDA(At, 0, 1); PG8_STAGE(PG8_SB(0, 0), b2, voffB); PG8_STAGE(PG8_SB(0, 1), b2 + hstep, voffB); PG8_STAGE(PG8_SA(0, 0), a2, voffA);
;             PG8_WAIT_V(8); PG8_WAIT_L(0); PG8_BAR; PG8_MMA(1, 0, At, B0); PG8_MMA(1, 1, At, B1); PG8_BAR; PG8_SCHED;
.LBB0_200:
	ds_read_b128 v[148:151], v164
	ds_read_b128 v[152:155], v164 offset:1024
	ds_read_b128 v[156:159], v164 offset:2048
	ds_read_b128 v[168:171], v164 offset:3072
	ds_read_b128 v[172:175], v165
	ds_read_b128 v[176:179], v165 offset:1024
	ds_read_b128 v[180:183], v165 offset:2048
	ds_read_b128 v[184:187], v165 offset:3072
	s_add_u32 s52, s70, 0xfff80080
	s_addc_u32 s53, s71, -1
	s_cmp_eq_u32 s93, 28
	s_cselect_b32 s75, s39, s53
	s_cselect_b32 s74, s69, s52
	s_cselect_b32 s73, s35, s92
	s_cselect_b32 s72, s90, s91
	s_add_i32 m0, s33, 0xc000
	ds_read_b128 v[188:191], v166
	ds_read_b128 v[192:195], v166 offset:1024
	ds_read_b128 v[196:199], v166 offset:2048
	ds_read_b128 v[200:203], v166 offset:3072
	ds_read_b128 v[204:207], v166 offset:4096
	ds_read_b128 v[208:211], v166 offset:5120
	ds_read_b128 v[212:215], v166 offset:6144
	ds_read_b128 v[216:219], v166 offset:7168
	global_load_lds_dwordx4 v138, s[70:71]
	s_add_i32 m0, s33, 0xe000
	s_nop 0
	global_load_lds_dwordx4 v140, s[70:71]
	s_waitcnt vmcnt(8)
	s_waitcnt lgkmcnt(0)
	s_setprio 1
	s_barrier
	v_mfma_f32_16x16x32_bf16 v[124:127], v[148:151], v[188:191], v[124:127]
	v_mfma_f32_16x16x32_bf16 v[120:123], v[156:159], v[188:191], v[120:123]
	v_mfma_f32_16x16x32_bf16 v[116:119], v[148:151], v[196:199], v[116:119]
	v_mfma_f32_16x16x32_bf16 v[108:111], v[156:159], v[196:199], v[108:111]
	v_mfma_f32_16x16x32_bf16 v[100:103], v[148:151], v[204:207], v[100:103]
	v_mfma_f32_16x16x32_bf16 v[92:95], v[156:159], v[204:207], v[92:95]
	v_mfma_f32_16x16x32_bf16 v[84:87], v[148:151], v[212:215], v[84:87]
	v_mfma_f32_16x16x32_bf16 v[76:79], v[156:159], v[212:215], v[76:79]
	v_mfma_f32_16x16x32_bf16 v[124:127], v[152:155], v[192:195], v[124:127]
	v_mfma_f32_16x16x32_bf16 v[120:123], v[168:171], v[192:195], v[120:123]
	v_mfma_f32_16x16x32_bf16 v[116:119], v[152:155], v[200:203], v[116:119]
	v_mfma_f32_16x16x32_bf16 v[108:111], v[168:171], v[200:203], v[108:111]
	v_mfma_f32_16x16x32_bf16 v[100:103], v[152:155], v[208:211], v[100:103]
	v_mfma_f32_16x16x32_bf16 v[92:95], v[168:171], v[208:211], v[92:95]
	v_mfma_f32_16x16x32_bf16 v[84:87], v[152:155], v[216:219], v[84:87]
	v_mfma_f32_16x16x32_bf16 v[76:79], v[168:171], v[216:219], v[76:79]
	s_setprio 0
	s_setprio 1
	v_mfma_f32_16x16x32_bf16 v[112:115], v[172:175], v[188:191], v[112:115]
	v_mfma_f32_16x16x32_bf16 v[104:107], v[180:183], v[188:191], v[104:107]
	v_mfma_f32_16x16x32_bf16 v[96:99], v[172:175], v[196:199], v[96:99]
	v_mfma_f32_16x16x32_bf16 v[88:91], v[180:183], v[196:199], v[88:91]
	v_mfma_f32_16x16x32_bf16 v[80:83], v[172:175], v[204:207], v[80:83]
	v_mfma_f32_16x16x32_bf16 v[72:75], v[180:183], v[204:207], v[72:75]
	v_mfma_f32_16x16x32_bf16 v[68:71], v[172:175], v[212:215], v[68:71]
	v_mfma_f32_16x16x32_bf16 v[64:67], v[180:183], v[212:215], v[64:67]
	v_mfma_f32_16x16x32_bf16 v[112:115], v[176:179], v[192:195], v[112:115]
	v_mfma_f32_16x16x32_bf16 v[104:107], v[184:187], v[192:195], v[104:107]
	v_mfma_f32_16x16x32_bf16 v[96:99], v[176:179], v[200:203], v[96:99]
	v_mfma_f32_16x16x32_bf16 v[88:91], v[184:187], v[200:203], v[88:91]
	v_mfma_f32_16x16x32_bf16 v[80:83], v[176:179], v[208:211], v[80:83]
	v_mfma_f32_16x16x32_bf16 v[72:75], v[184:187], v[208:211], v[72:75]
	s_setprio 2
	s_barrier
	v_mfma_f32_16x16x32_bf16 v[68:71], v[176:179], v[216:219], v[68:71]
	v_mfma_f32_16x16x32_bf16 v[64:67], v[184:187], v[216:219], v[64:67]
	s_setprio 0
	s_add_i32 s52, s84, s3
	v_lshl_add_u64 v[220:221], s[72:73], 0, v[132:133]
	s_mov_b32 m0, s52
	ds_read_b128 v[188:191], v166 offset:16384
	ds_read_b128 v[192:195], v166 offset:17408
	ds_read_b128 v[196:199], v166 offset:18432
	ds_read_b128 v[200:203], v166 offset:19456
	ds_read_b128 v[204:207], v166 offset:20480
	ds_read_b128 v[208:211], v166 offset:21504
	ds_read_b128 v[212:215], v166 offset:22528
	ds_read_b128 v[216:219], v166 offset:23552
	global_load_lds_dwordx4 v[220:221], off
	s_add_i32 m0, s52, 0x2000
	s_add_u32 s96, s72, 0x80000
	v_lshl_add_u64 v[222:223], s[72:73], 0, v[128:129]
	s_addc_u32 s97, s73, 0
	s_add_i32 s52, s85, s3
	global_load_lds_dwordx4 v[222:223], off
	s_mov_b32 m0, s52
	v_lshl_add_u64 v[226:227], s[74:75], 0, v[130:131]
	global_load_lds_dwordx4 v132, s[96:97]
	s_add_i32 m0, s52, 0x2000
	s_nop 0
	global_load_lds_dwordx4 v128, s[96:97]
	v_lshl_add_u64 v[224:225], s[74:75], 0, v[134:135]
	s_mov_b32 m0, s33
	s_nop 0
	global_load_lds_dwordx4 v[224:225], off
	s_mov_b32 m0, s76
	s_nop 0
	global_load_lds_dwordx4 v[226:227], off
	s_waitcnt vmcnt(8)
	s_waitcnt lgkmcnt(0)
	s_setprio 1
	s_barrier
	v_mfma_f32_16x16x32_bf16 v[60:63], v[148:151], v[188:191], v[60:63]
	v_mfma_f32_16x16x32_bf16 v[56:59], v[156:159], v[188:191], v[56:59]
	v_mfma_f32_16x16x32_bf16 v[52:55], v[148:151], v[196:199], v[52:55]
	v_mfma_f32_16x16x32_bf16 v[44:47], v[156:159], v[196:199], v[44:47]
	v_mfma_f32_16x16x32_bf16 v[36:39], v[148:151], v[204:207], v[36:39]
	v_mfma_f32_16x16x32_bf16 v[28:31], v[156:159], v[204:207], v[28:31]
	v_mfma_f32_16x16x32_bf16 v[20:23], v[148:151], v[212:215], v[20:23]
	v_mfma_f32_16x16x32_bf16 v[12:15], v[156:159], v[212:215], v[12:15]
	v_mfma_f32_16x16x32_bf16 v[60:63], v[152:155], v[192:195], v[60:63]
	v_mfma_f32_16x16x32_bf16 v[56:59], v[168:171], v[192:195], v[56:59]
	v_mfma_f32_16x16x32_bf16 v[52:55], v[152:155], v[200:203], v[52:55]
	v_mfma_f32_16x16x32_bf16 v[44:47], v[168:171], v[200:203], v[44:47]
	v_mfma_f32_16x16x32_bf16 v[36:39], v[152:155], v[208:211], v[36:39]
	v_mfma_f32_16x16x32_bf16 v[28:31], v[168:171], v[208:211], v[28:31]
	v_mfma_f32_16x16x32_bf16 v[20:23], v[152:155], v[216:219], v[20:23]
	v_mfma_f32_16x16x32_bf16 v[12:15], v[168:171], v[216:219], v[12:15]
	s_setprio 0
	s_setprio 1
	v_mfma_f32_16x16x32_bf16 v[48:51], v[172:175], v[188:191], v[48:51]
	v_mfma_f32_16x16x32_bf16 v[40:43], v[180:183], v[188:191], v[40:43]
	v_mfma_f32_16x16x32_bf16 v[32:35], v[172:175], v[196:199], v[32:35]
	v_mfma_f32_16x16x32_bf16 v[24:27], v[180:183], v[196:199], v[24:27]
	v_mfma_f32_16x16x32_bf16 v[16:19], v[172:175], v[204:207], v[16:19]
	v_mfma_f32_16x16x32_bf16 v[8:11], v[180:183], v[204:207], v[8:11]
	v_mfma_f32_16x16x32_bf16 v[4:7], v[172:175], v[212:215], v[4:7]
	v_mfma_f32_16x16x32_bf16 v[0:3], v[180:183], v[212:215], v[0:3]
	v_mfma_f32_16x16x32_bf16 v[48:51], v[176:179], v[192:195], v[48:51]
	v_mfma_f32_16x16x32_bf16 v[40:43], v[184:187], v[192:195], v[40:43]
	v_mfma_f32_16x16x32_bf16 v[32:35], v[176:179], v[200:203], v[32:35]
	v_mfma_f32_16x16x32_bf16 v[24:27], v[184:187], v[200:203], v[24:27]
	v_mfma_f32_16x16x32_bf16 v[16:19], v[176:179], v[208:211], v[16:19]
	v_mfma_f32_16x16x32_bf16 v[8:11], v[184:187], v[208:211], v[8:11]
	s_setprio 2
	s_barrier
; #define PG8_STAGE(bufoff, gbase, voff) do { _Pragma("unroll") for (int _i = 0; _i < 2; ++_i) \
;         __builtin_amdgcn_global_load_lds((const unsigned*)((const char*)(gbase) + (voff)[_i]), (PG8_LAS unsigned*)(lds + (bufoff) + ldsw + _i * 8192), 16, 0, 0); } while (0)
; #define PG8_LDA(dst, b, h) do { _Pragma("unroll") for (int m = 0; m < 4; ++m) _Pragma("unroll") for (int k = 0; k < 2; ++k) dst[m][k] = *(const PG8_LAS bf16x8*)(lds + PG8_SA(b, h) + aoff + m * 2048 + k * 1024); } while (0)
; #define PG8_LDB(dst, b, h) do { _Pragma("unroll") for (int n = 0; n < 2; ++n) _Pragma("unroll") for (int k = 0; k < 2; ++k) dst[n][k] = *(const PG8_LAS bf16x8*)(lds + PG8_SB(b, h) + boff + n * 2048 + k * 1024); } while (0)
; #define PG8_MMA(ai, bj, At, Bt) do { __builtin_amdgcn_s_setprio(1); _Pragma("unroll") for (int m = 0; m < 4; ++m) _Pragma("unroll") for (int n = 0; n < 2; ++n) _Pragma("unroll") for (int k = 0; k < 2; ++k) \
;         acc[ai][bj][m][n] = __builtin_amdgcn_mfma_f32_16x16x32_bf16(Bt[n][k], At[m][k], acc[ai][bj][m][n], 0, 0, 0); __builtin_amdgcn_s_setprio(0); } while (0)
; #define PG8_WAIT_V(n) asm volatile("s_waitcnt vmcnt(" #n ")" ::: "memory")
; #define PG8_WAIT_L(n) asm volatile("s_waitcnt lgkmcnt(" #n ")" ::: "memory")
; #define PG8_BAR __builtin_amdgcn_s_barrier()
; #define PG8_SCHED __builtin_amdgcn_sched_barrier(0)
; template <class Epi, class Sched, bool ALIGN_EPI = false, bool SP2 = false>
; __device__ __forceinline__ void gemm_phase(PG8_LAS unsigned char* lds, const Gemm g, const Sched& S, const Epi& E) {
;     ...
;             PG8_WAIT_V(8); PG8_WAIT_L(0); PG8_BAR; PG8_MMA(1, 0, At, B0); PG8_MMA(1, 1, At, B1); PG8_BAR; PG8_SCHED;
;             PG8_LDB(B0, 1, 0); PG8_LDB(B1, 1, 1); PG8_SCHED; PG8_LDA(At, 1, 0); PG8_STAGE(PG8_SA(0, 1), a2 + hstep, voffA);
;             PG8_WAIT_V(8); PG8_WAIT_L(0); PG8_BAR; PG8_MMA(0, 0, At, B0); PG8_MMA(0, 1, At, B1); PG8_BAR; PG8_SCHED;
	v_mfma_f32_16x16x32_bf16 v[4:7], v[176:179], v[216:219], v[4:7]
	v_mfma_f32_16x16x32_bf16 v[0:3], v[184:187], v[216:219], v[0:3]
	s_setprio 0
	s_add_i32 s52, 0, 0x18000
	v_add_u32_e32 v136, s52, v161
	s_add_i32 s53, 0, 0x1c000
	ds_read_b128 v[148:151], v136
	ds_read_b128 v[152:155], v136 offset:1024
	ds_read_b128 v[156:159], v136 offset:2048
	ds_read_b128 v[168:171], v136 offset:3072
	v_add_u32_e32 v136, s53, v161
	ds_read_b128 v[172:175], v136
	ds_read_b128 v[176:179], v136 offset:1024
	ds_read_b128 v[180:183], v136 offset:2048
	ds_read_b128 v[184:187], v136 offset:3072
	s_add_u32 s74, s74, 0x80000
	s_addc_u32 s75, s75, 0
	s_mov_b32 m0, s77
	ds_read_b128 v[188:191], v166 offset:32768
	ds_read_b128 v[192:195], v166 offset:33792
	ds_read_b128 v[196:199], v166 offset:34816
	ds_read_b128 v[200:203], v166 offset:35840
	ds_read_b128 v[204:207], v166 offset:36864
	ds_read_b128 v[208:211], v166 offset:37888
	ds_read_b128 v[212:215], v166 offset:38912
	ds_read_b128 v[216:219], v166 offset:39936
	global_load_lds_dwordx4 v134, s[74:75]
	s_mov_b32 m0, s78
	s_nop 0
	global_load_lds_dwordx4 v130, s[74:75]
	s_waitcnt vmcnt(8)
	s_waitcnt lgkmcnt(0)
	s_setprio 1
	s_barrier
	v_mfma_f32_16x16x32_bf16 v[124:127], v[148:151], v[188:191], v[124:127]
	v_mfma_f32_16x16x32_bf16 v[120:123], v[156:159], v[188:191], v[120:123]
	v_mfma_f32_16x16x32_bf16 v[116:119], v[148:151], v[196:199], v[116:119]
	v_mfma_f32_16x16x32_bf16 v[108:111], v[156:159], v[196:199], v[108:111]
	v_mfma_f32_16x16x32_bf16 v[100:103], v[148:151], v[204:207], v[100:103]
	v_mfma_f32_16x16x32_bf16 v[92:95], v[156:159], v[204:207], v[92:95]
	v_mfma_f32_16x16x32_bf16 v[84:87], v[148:151], v[212:215], v[84:87]
	v_mfma_f32_16x16x32_bf16 v[76:79], v[156:159], v[212:215], v[76:79]
	v_mfma_f32_16x16x32_bf16 v[124:127], v[152:155], v[192:195], v[124:127]
	v_mfma_f32_16x16x32_bf16 v[120:123], v[168:171], v[192:195], v[120:123]
	v_mfma_f32_16x16x32_bf16 v[116:119], v[152:155], v[200:203], v[116:119]
	v_mfma_f32_16x16x32_bf16 v[108:111], v[168:171], v[200:203], v[108:111]
	v_mfma_f32_16x16x32_bf16 v[100:103], v[152:155], v[208:211], v[100:103]
	v_mfma_f32_16x16x32_bf16 v[92:95], v[168:171], v[208:211], v[92:95]
	v_mfma_f32_16x16x32_bf16 v[84:87], v[152:155], v[216:219], v[84:87]
	v_mfma_f32_16x16x32_bf16 v[76:79], v[168:171], v[216:219], v[76:79]
	s_setprio 0
	s_setprio 1
	v_mfma_f32_16x16x32_bf16 v[112:115], v[172:175], v[188:191], v[112:115]
	v_mfma_f32_16x16x32_bf16 v[104:107], v[180:183], v[188:191], v[104:107]
	v_mfma_f32_16x16x32_bf16 v[96:99], v[172:175], v[196:199], v[96:99]
	v_mfma_f32_16x16x32_bf16 v[88:91], v[180:183], v[196:199], v[88:91]
	v_mfma_f32_16x16x32_bf16 v[80:83], v[172:175], v[204:207], v[80:83]
	v_mfma_f32_16x16x32_bf16 v[72:75], v[180:183], v[204:207], v[72:75]
	v_mfma_f32_16x16x32_bf16 v[68:71], v[172:175], v[212:215], v[68:71]
	v_mfma_f32_16x16x32_bf16 v[64:67], v[180:183], v[212:215], v[64:67]
	v_mfma_f32_16x16x32_bf16 v[112:115], v[176:179], v[192:195], v[112:115]
	v_mfma_f32_16x16x32_bf16 v[104:107], v[184:187], v[192:195], v[104:107]
	v_mfma_f32_16x16x32_bf16 v[96:99], v[176:179], v[200:203], v[96:99]
	v_mfma_f32_16x16x32_bf16 v[88:91], v[184:187], v[200:203], v[88:91]
	v_mfma_f32_16x16x32_bf16 v[80:83], v[176:179], v[208:211], v[80:83]
	v_mfma_f32_16x16x32_bf16 v[72:75], v[184:187], v[208:211], v[72:75]
	s_setprio 2
	s_barrier
; #define PG8_STAGE(bufoff, gbase, voff) do { _Pragma("unroll") for (int _i = 0; _i < 2; ++_i) \
;         __builtin_amdgcn_global_load_lds((const unsigned*)((const char*)(gbase) + (voff)[_i]), (PG8_LAS unsigned*)(lds + (bufoff) + ldsw + _i * 8192), 16, 0, 0); } while (0)
; #define PG8_LDA(dst, b, h) do { _Pragma("unroll") for (int m = 0; m < 4; ++m) _Pragma("unroll") for (int k = 0; k < 2; ++k) dst[m][k] = *(const PG8_LAS bf16x8*)(lds + PG8_SA(b, h) + aoff + m * 2048 + k * 1024); } while (0)
; #define PG8_MMA(ai, bj, At, Bt) do { __builtin_amdgcn_s_setprio(1); _Pragma("unroll") for (int m = 0; m < 4; ++m) _Pragma("unroll") for (int n = 0; n < 2; ++n) _Pragma("unroll") for (int k = 0; k < 2; ++k) \
;         acc[ai][bj][m][n] = __builtin_amdgcn_mfma_f32_16x16x32_bf16(Bt[n][k], At[m][k], acc[ai][bj][m][n], 0, 0, 0); __builtin_amdgcn_s_setprio(0); } while (0)
; #define PG8_WAIT_V(n) asm volatile("s_waitcnt vmcnt(" #n ")" ::: "memory")
; #define PG8_WAIT_L(n) asm volatile("s_waitcnt lgkmcnt(" #n ")" ::: "memory")
; #define PG8_BAR __builtin_amdgcn_s_barrier()
; #define PG8_SCHED __builtin_amdgcn_sched_barrier(0)
; template <class Epi, class Sched, bool ALIGN_EPI = false, bool SP2 = false>
; __device__ __forceinline__ void gemm_phase(PG8_LAS unsigned char* lds, const Gemm g, const Sched& S, const Epi& E) {
;     ...
;             PG8_WAIT_V(8); PG8_WAIT_L(0); PG8_BAR; PG8_MMA(0, 0, At, B0); PG8_MMA(0, 1, At, B1); PG8_BAR; PG8_SCHED;
;             PG8_LDA(At, 1, 1); PG8_STAGE(PG8_SB(1, 0), b3, voffB); PG8_STAGE(PG8_SB(1, 1), b3 + hstep, voffB); PG8_STAGE(PG8_SA(1, 0), a3, voffA);
;             PG8_WAIT_V(8); PG8_WAIT_L(0); PG8_BAR; PG8_MMA(1, 0, At, B0); PG8_MMA(1, 1, At, B1); PG8_BAR; PG8_SCHED;
;     ...
;         if constexpr (ALIGN_EPI) { if (wr == 0) PG8_BAR; }
	v_mfma_f32_16x16x32_bf16 v[68:71], v[176:179], v[216:219], v[68:71]
	v_mfma_f32_16x16x32_bf16 v[64:67], v[184:187], v[216:219], v[64:67]
	s_setprio 0
	s_add_i32 s52, s52, s3
	v_lshl_add_u64 v[220:221], v[220:221], 0, s[12:13]
	s_mov_b32 m0, s52
	ds_read_b128 v[188:191], v166 offset:49152
	ds_read_b128 v[192:195], v166 offset:50176
	ds_read_b128 v[196:199], v166 offset:51200
	ds_read_b128 v[200:203], v166 offset:52224
	ds_read_b128 v[204:207], v166 offset:53248
	ds_read_b128 v[208:211], v166 offset:54272
	ds_read_b128 v[212:215], v166 offset:55296
	ds_read_b128 v[216:219], v166 offset:56320
	global_load_lds_dwordx4 v[220:221], off
	s_add_i32 m0, s52, 0x2000
	s_add_u32 s72, s72, 0x80080
	v_lshl_add_u64 v[220:221], v[222:223], 0, s[12:13]
	s_addc_u32 s73, s73, 0
	s_add_i32 s52, s53, s3
	global_load_lds_dwordx4 v[220:221], off
	s_mov_b32 m0, s52
	s_nop 0
	global_load_lds_dwordx4 v132, s[72:73]
	s_add_i32 m0, s52, 0x2000
	s_nop 0
	global_load_lds_dwordx4 v128, s[72:73]
	v_lshl_add_u64 v[220:221], v[224:225], 0, s[12:13]
	s_mov_b32 m0, s80
	s_nop 0
	global_load_lds_dwordx4 v[220:221], off
	v_lshl_add_u64 v[220:221], v[226:227], 0, s[12:13]
	s_mov_b32 m0, s81
	s_nop 0
	global_load_lds_dwordx4 v[220:221], off
	s_waitcnt vmcnt(8)
	s_waitcnt lgkmcnt(0)
	s_setprio 1
	s_barrier
	v_mfma_f32_16x16x32_bf16 v[60:63], v[148:151], v[188:191], v[60:63]
	v_mfma_f32_16x16x32_bf16 v[56:59], v[156:159], v[188:191], v[56:59]
	v_mfma_f32_16x16x32_bf16 v[52:55], v[148:151], v[196:199], v[52:55]
	v_mfma_f32_16x16x32_bf16 v[44:47], v[156:159], v[196:199], v[44:47]
	v_mfma_f32_16x16x32_bf16 v[36:39], v[148:151], v[204:207], v[36:39]
	v_mfma_f32_16x16x32_bf16 v[28:31], v[156:159], v[204:207], v[28:31]
	v_mfma_f32_16x16x32_bf16 v[20:23], v[148:151], v[212:215], v[20:23]
	v_mfma_f32_16x16x32_bf16 v[12:15], v[156:159], v[212:215], v[12:15]
	v_mfma_f32_16x16x32_bf16 v[60:63], v[152:155], v[192:195], v[60:63]
	v_mfma_f32_16x16x32_bf16 v[56:59], v[168:171], v[192:195], v[56:59]
	v_mfma_f32_16x16x32_bf16 v[52:55], v[152:155], v[200:203], v[52:55]
	v_mfma_f32_16x16x32_bf16 v[44:47], v[168:171], v[200:203], v[44:47]
	v_mfma_f32_16x16x32_bf16 v[36:39], v[152:155], v[208:211], v[36:39]
	v_mfma_f32_16x16x32_bf16 v[28:31], v[168:171], v[208:211], v[28:31]
	v_mfma_f32_16x16x32_bf16 v[20:23], v[152:155], v[216:219], v[20:23]
	v_mfma_f32_16x16x32_bf16 v[12:15], v[168:171], v[216:219], v[12:15]
	s_setprio 0
	s_setprio 1
	v_mfma_f32_16x16x32_bf16 v[48:51], v[172:175], v[188:191], v[48:51]
	v_mfma_f32_16x16x32_bf16 v[40:43], v[180:183], v[188:191], v[40:43]
	v_mfma_f32_16x16x32_bf16 v[32:35], v[172:175], v[196:199], v[32:35]
	v_mfma_f32_16x16x32_bf16 v[24:27], v[180:183], v[196:199], v[24:27]
	v_mfma_f32_16x16x32_bf16 v[16:19], v[172:175], v[204:207], v[16:19]
	v_mfma_f32_16x16x32_bf16 v[8:11], v[180:183], v[204:207], v[8:11]
	v_mfma_f32_16x16x32_bf16 v[4:7], v[172:175], v[212:215], v[4:7]
	v_mfma_f32_16x16x32_bf16 v[0:3], v[180:183], v[212:215], v[0:3]
	v_mfma_f32_16x16x32_bf16 v[48:51], v[176:179], v[192:195], v[48:51]
	v_mfma_f32_16x16x32_bf16 v[40:43], v[184:187], v[192:195], v[40:43]
	v_mfma_f32_16x16x32_bf16 v[32:35], v[176:179], v[200:203], v[32:35]
	v_mfma_f32_16x16x32_bf16 v[24:27], v[184:187], v[200:203], v[24:27]
	v_mfma_f32_16x16x32_bf16 v[16:19], v[176:179], v[208:211], v[16:19]
	v_mfma_f32_16x16x32_bf16 v[8:11], v[184:187], v[208:211], v[8:11]
	s_setprio 2
	s_barrier
	v_mfma_f32_16x16x32_bf16 v[4:7], v[176:179], v[216:219], v[4:7]
	v_mfma_f32_16x16x32_bf16 v[0:3], v[184:187], v[216:219], v[0:3]
	s_setprio 0
	s_add_i32 s93, s93, 2
	s_add_u32 s70, s70, 0x100
	s_addc_u32 s71, s71, 0
	s_add_u32 s91, s91, 0x100
	s_addc_u32 s92, s92, 0
	s_cmp_gt_u32 s93, 29
	s_cbranch_scc0 .LBB0_200
	s_and_b64 vcc, exec, s[14:15]
	s_cbranch_vccz .LBB0_203
	s_barrier

; #define PG8_STAGE(bufoff, gbase, voff) do { _Pragma("unroll") for (int _i = 0; _i < 2; ++_i) \
;         __builtin_amdgcn_global_load_lds((const unsigned*)((const char*)(gbase) + (voff)[_i]), (PG8_LAS unsigned*)(lds + (bufoff) + ldsw + _i * 8192), 16, 0, 0); } while (0)
; #define PG8_LDA(dst, b, h) do { _Pragma("unroll") for (int m = 0; m < 4; ++m) _Pragma("unroll") for (int k = 0; k < 2; ++k) dst[m][k] = *(const PG8_LAS bf16x8*)(lds + PG8_SA(b, h) + aoff + m * 2048 + k * 1024); } while (0)
; #define PG8_LDB(dst, b, h) do { _Pragma("unroll") for (int n = 0; n < 2; ++n) _Pragma("unroll") for (int k = 0; k < 2; ++k) dst[n][k] = *(const PG8_LAS bf16x8*)(lds + PG8_SB(b, h) + boff + n * 2048 + k * 1024); } while (0)
; #define PG8_MMA(ai, bj, At, Bt) do { __builtin_amdgcn_s_setprio(1); _Pragma("unroll") for (int m = 0; m < 4; ++m) _Pragma("unroll") for (int n = 0; n < 2; ++n) _Pragma("unroll") for (int k = 0; k < 2; ++k) \
;         acc[ai][bj][m][n] = __builtin_amdgcn_mfma_f32_16x16x32_bf16(Bt[n][k], At[m][k], acc[ai][bj][m][n], 0, 0, 0); __builtin_amdgcn_s_setprio(0); } while (0)
; #define PG8_WAIT_V(n) asm volatile("s_waitcnt vmcnt(" #n ")" ::: "memory")
; #define PG8_WAIT_L(n) asm volatile("s_waitcnt lgkmcnt(" #n ")" ::: "memory")
; #define PG8_BAR __builtin_amdgcn_s_barrier()
; template <class Epi, class Sched, bool ALIGN_EPI = false, bool SP2 = false>
; __device__ __forceinline__ void gemm_phase(PG8_LAS unsigned char* lds, const Gemm g, const Sched& S, const Epi& E) {
;     ...
;             const bool last = (t == nt - 2);
;             const char* a1 = cA + (size_t)(t + 1) * kstep;
;             const char* a2 = last ? nA : cA + (size_t)(t + 2) * kstep; const char* b2 = last ? nB : cB + (size_t)(t + 2) * kstep;
;             const char* a3 = a2 + kstep; const char* b3 = b2 + kstep;
;             if constexpr (SP2) {
;             PG8_LDB(B0, 0, 0); PG8_LDB(B1, 0, 1); PG8_SCHED; PG8_LDA(At, 0, 0); PG8_STAGE(PG8_SA(1, 1), a1 + hstep, voffA);
;             PG8_WAIT_V(8); PG8_WAIT_L(0); PG8_BAR; PG8_MMA(0, 0, At, B0); PG8_MMA(0, 1, At, B1); PG8_BAR; PG8_SCHED;
;             PG8_LDA(At, 0, 1); PG8_STAGE(PG8_SB(0, 0), b2, voffB); PG8_STAGE(PG8_SB(0, 1), b2 + hstep, voffB); PG8_STAGE(PG8_SA(0, 0), a2, voffA);
;             PG8_WAIT_V(8); PG8_WAIT_L(0); PG8_BAR; PG8_MMA(1, 0, At, B0); PG8_MMA(1, 1, At, B1); PG8_BAR; PG8_SCHED;
.LBB0_374:
	ds_read_b128 v[128:131], v230
	ds_read_b128 v[132:135], v230 offset:1024
	ds_read_b128 v[158:161], v230 offset:2048
	ds_read_b128 v[162:165], v230 offset:3072
	ds_read_b128 v[166:169], v231
	ds_read_b128 v[170:173], v231 offset:1024
	ds_read_b128 v[174:177], v231 offset:2048
	ds_read_b128 v[178:181], v231 offset:3072
	s_add_u32 s52, s76, 0xfff80080
	s_addc_u32 s53, s77, -1
	s_cmp_eq_u32 vcc_hi, 28
	s_cselect_b32 s81, s11, s53
	s_cselect_b32 s80, s55, s52
	s_cselect_b32 s79, s51, vcc_lo
	s_cselect_b32 s78, s73, s75
	s_add_i32 m0, s28, 0xc000
	ds_read_b128 v[182:185], v232
	ds_read_b128 v[186:189], v232 offset:1024
	ds_read_b128 v[190:193], v232 offset:2048
	ds_read_b128 v[194:197], v232 offset:3072
	ds_read_b128 v[198:201], v232 offset:4096
	ds_read_b128 v[202:205], v232 offset:5120
	ds_read_b128 v[206:209], v232 offset:6144
	ds_read_b128 v[210:213], v232 offset:7168
	global_load_lds_dwordx4 v150, s[76:77]
	s_add_i32 m0, s28, 0xe000
	s_nop 0
	global_load_lds_dwordx4 v152, s[76:77]
	s_waitcnt vmcnt(8)
	s_waitcnt lgkmcnt(0)
	s_setprio 1
	s_barrier
	v_mfma_f32_16x16x32_bf16 v[124:127], v[128:131], v[182:185], v[124:127]
	v_mfma_f32_16x16x32_bf16 v[120:123], v[158:161], v[182:185], v[120:123]
	v_mfma_f32_16x16x32_bf16 v[116:119], v[128:131], v[190:193], v[116:119]
	v_mfma_f32_16x16x32_bf16 v[112:115], v[158:161], v[190:193], v[112:115]
	v_mfma_f32_16x16x32_bf16 v[108:111], v[128:131], v[198:201], v[108:111]
	v_mfma_f32_16x16x32_bf16 v[104:107], v[158:161], v[198:201], v[104:107]
	v_mfma_f32_16x16x32_bf16 v[100:103], v[128:131], v[206:209], v[100:103]
	v_mfma_f32_16x16x32_bf16 v[96:99], v[158:161], v[206:209], v[96:99]
	v_mfma_f32_16x16x32_bf16 v[124:127], v[132:135], v[186:189], v[124:127]
	v_mfma_f32_16x16x32_bf16 v[120:123], v[162:165], v[186:189], v[120:123]
	v_mfma_f32_16x16x32_bf16 v[116:119], v[132:135], v[194:197], v[116:119]
	v_mfma_f32_16x16x32_bf16 v[112:115], v[162:165], v[194:197], v[112:115]
	v_mfma_f32_16x16x32_bf16 v[108:111], v[132:135], v[202:205], v[108:111]
	v_mfma_f32_16x16x32_bf16 v[104:107], v[162:165], v[202:205], v[104:107]
	v_mfma_f32_16x16x32_bf16 v[100:103], v[132:135], v[210:213], v[100:103]
	v_mfma_f32_16x16x32_bf16 v[96:99], v[162:165], v[210:213], v[96:99]
	s_setprio 0
	s_setprio 1
	v_mfma_f32_16x16x32_bf16 v[60:63], v[166:169], v[182:185], v[60:63]
	v_mfma_f32_16x16x32_bf16 v[56:59], v[174:177], v[182:185], v[56:59]
	v_mfma_f32_16x16x32_bf16 v[52:55], v[166:169], v[190:193], v[52:55]
	v_mfma_f32_16x16x32_bf16 v[48:51], v[174:177], v[190:193], v[48:51]
	v_mfma_f32_16x16x32_bf16 v[44:47], v[166:169], v[198:201], v[44:47]
	v_mfma_f32_16x16x32_bf16 v[40:43], v[174:177], v[198:201], v[40:43]
	v_mfma_f32_16x16x32_bf16 v[36:39], v[166:169], v[206:209], v[36:39]
	v_mfma_f32_16x16x32_bf16 v[32:35], v[174:177], v[206:209], v[32:35]
	v_mfma_f32_16x16x32_bf16 v[60:63], v[170:173], v[186:189], v[60:63]
	v_mfma_f32_16x16x32_bf16 v[56:59], v[178:181], v[186:189], v[56:59]
	v_mfma_f32_16x16x32_bf16 v[52:55], v[170:173], v[194:197], v[52:55]
	v_mfma_f32_16x16x32_bf16 v[48:51], v[178:181], v[194:197], v[48:51]
	v_mfma_f32_16x16x32_bf16 v[44:47], v[170:173], v[202:205], v[44:47]
	v_mfma_f32_16x16x32_bf16 v[40:43], v[178:181], v[202:205], v[40:43]
	s_setprio 2
	s_barrier
	v_mfma_f32_16x16x32_bf16 v[36:39], v[170:173], v[210:213], v[36:39]
	v_mfma_f32_16x16x32_bf16 v[32:35], v[178:181], v[210:213], v[32:35]
	s_setprio 0
	s_add_i32 s52, s93, s3
	v_lshl_add_u64 v[214:215], s[78:79], 0, v[138:139]
	s_mov_b32 m0, s52
	ds_read_b128 v[182:185], v232 offset:16384
	ds_read_b128 v[186:189], v232 offset:17408
	ds_read_b128 v[190:193], v232 offset:18432
	ds_read_b128 v[194:197], v232 offset:19456
	ds_read_b128 v[198:201], v232 offset:20480
	ds_read_b128 v[202:205], v232 offset:21504
	ds_read_b128 v[206:209], v232 offset:22528
	ds_read_b128 v[210:213], v232 offset:23552
	global_load_lds_dwordx4 v[214:215], off
	s_add_i32 m0, s52, 0x2000
	s_add_u32 s52, s78, 0x80000
	v_lshl_add_u64 v[216:217], s[78:79], 0, v[142:143]
	s_addc_u32 s53, s79, 0
	s_add_i32 s56, s10, s3
	global_load_lds_dwordx4 v[216:217], off
	s_mov_b32 m0, s56
	v_lshl_add_u64 v[220:221], s[80:81], 0, v[140:141]
	global_load_lds_dwordx4 v138, s[52:53]
	s_add_i32 m0, s56, 0x2000
	s_nop 0
	global_load_lds_dwordx4 v142, s[52:53]
	v_lshl_add_u64 v[218:219], s[80:81], 0, v[136:137]
	s_mov_b32 m0, s28
	s_nop 0
	global_load_lds_dwordx4 v[218:219], off
	s_mov_b32 m0, s29
	s_nop 0
	global_load_lds_dwordx4 v[220:221], off
	s_waitcnt vmcnt(8)
	s_waitcnt lgkmcnt(0)
	s_setprio 1
	s_barrier
	v_mfma_f32_16x16x32_bf16 v[92:95], v[128:131], v[182:185], v[92:95]
	v_mfma_f32_16x16x32_bf16 v[88:91], v[158:161], v[182:185], v[88:91]
	v_mfma_f32_16x16x32_bf16 v[84:87], v[128:131], v[190:193], v[84:87]
	v_mfma_f32_16x16x32_bf16 v[80:83], v[158:161], v[190:193], v[80:83]
	v_mfma_f32_16x16x32_bf16 v[76:79], v[128:131], v[198:201], v[76:79]
	v_mfma_f32_16x16x32_bf16 v[72:75], v[158:161], v[198:201], v[72:75]
	v_mfma_f32_16x16x32_bf16 v[68:71], v[128:131], v[206:209], v[68:71]
	v_mfma_f32_16x16x32_bf16 v[64:67], v[158:161], v[206:209], v[64:67]
	v_mfma_f32_16x16x32_bf16 v[92:95], v[132:135], v[186:189], v[92:95]
	v_mfma_f32_16x16x32_bf16 v[88:91], v[162:165], v[186:189], v[88:91]
	v_mfma_f32_16x16x32_bf16 v[84:87], v[132:135], v[194:197], v[84:87]
	v_mfma_f32_16x16x32_bf16 v[80:83], v[162:165], v[194:197], v[80:83]
	v_mfma_f32_16x16x32_bf16 v[76:79], v[132:135], v[202:205], v[76:79]
	v_mfma_f32_16x16x32_bf16 v[72:75], v[162:165], v[202:205], v[72:75]
	v_mfma_f32_16x16x32_bf16 v[68:71], v[132:135], v[210:213], v[68:71]
	v_mfma_f32_16x16x32_bf16 v[64:67], v[162:165], v[210:213], v[64:67]
	s_setprio 0
	s_setprio 1
	v_mfma_f32_16x16x32_bf16 v[28:31], v[166:169], v[182:185], v[28:31]
	v_mfma_f32_16x16x32_bf16 v[24:27], v[174:177], v[182:185], v[24:27]
	v_mfma_f32_16x16x32_bf16 v[20:23], v[166:169], v[190:193], v[20:23]
	v_mfma_f32_16x16x32_bf16 v[16:19], v[174:177], v[190:193], v[16:19]
	v_mfma_f32_16x16x32_bf16 v[12:15], v[166:169], v[198:201], v[12:15]
	v_mfma_f32_16x16x32_bf16 v[8:11], v[174:177], v[198:201], v[8:11]
	v_mfma_f32_16x16x32_bf16 v[4:7], v[166:169], v[206:209], v[4:7]
	v_mfma_f32_16x16x32_bf16 v[0:3], v[174:177], v[206:209], v[0:3]
	v_mfma_f32_16x16x32_bf16 v[28:31], v[170:173], v[186:189], v[28:31]
	v_mfma_f32_16x16x32_bf16 v[24:27], v[178:181], v[186:189], v[24:27]
	v_mfma_f32_16x16x32_bf16 v[20:23], v[170:173], v[194:197], v[20:23]
	v_mfma_f32_16x16x32_bf16 v[16:19], v[178:181], v[194:197], v[16:19]
	v_mfma_f32_16x16x32_bf16 v[12:15], v[170:173], v[202:205], v[12:15]
	v_mfma_f32_16x16x32_bf16 v[8:11], v[178:181], v[202:205], v[8:11]
	s_setprio 2
	s_barrier
; #define PG8_STAGE(bufoff, gbase, voff) do { _Pragma("unroll") for (int _i = 0; _i < 2; ++_i) \
;         __builtin_amdgcn_global_load_lds((const unsigned*)((const char*)(gbase) + (voff)[_i]), (PG8_LAS unsigned*)(lds + (bufoff) + ldsw + _i * 8192), 16, 0, 0); } while (0)
; #define PG8_LDA(dst, b, h) do { _Pragma("unroll") for (int m = 0; m < 4; ++m) _Pragma("unroll") for (int k = 0; k < 2; ++k) dst[m][k] = *(const PG8_LAS bf16x8*)(lds + PG8_SA(b, h) + aoff + m * 2048 + k * 1024); } while (0)
; #define PG8_LDB(dst, b, h) do { _Pragma("unroll") for (int n = 0; n < 2; ++n) _Pragma("unroll") for (int k = 0; k < 2; ++k) dst[n][k] = *(const PG8_LAS bf16x8*)(lds + PG8_SB(b, h) + boff + n * 2048 + k * 1024); } while (0)
; #define PG8_MMA(ai, bj, At, Bt) do { __builtin_amdgcn_s_setprio(1); _Pragma("unroll") for (int m = 0; m < 4; ++m) _Pragma("unroll") for (int n = 0; n < 2; ++n) _Pragma("unroll") for (int k = 0; k < 2; ++k) \
;         acc[ai][bj][m][n] = __builtin_amdgcn_mfma_f32_16x16x32_bf16(Bt[n][k], At[m][k], acc[ai][bj][m][n], 0, 0, 0); __builtin_amdgcn_s_setprio(0); } while (0)
; #define PG8_WAIT_V(n) asm volatile("s_waitcnt vmcnt(" #n ")" ::: "memory")
; #define PG8_WAIT_L(n) asm volatile("s_waitcnt lgkmcnt(" #n ")" ::: "memory")
; #define PG8_BAR __builtin_amdgcn_s_barrier()
; #define PG8_SCHED __builtin_amdgcn_sched_barrier(0)
; template <class Epi, class Sched, bool ALIGN_EPI = false, bool SP2 = false>
; __device__ __forceinline__ void gemm_phase(PG8_LAS unsigned char* lds, const Gemm g, const Sched& S, const Epi& E) {
;     ...
;             PG8_LDB(B0, 1, 0); PG8_LDB(B1, 1, 1); PG8_SCHED; PG8_LDA(At, 1, 0); PG8_STAGE(PG8_SA(0, 1), a2 + hstep, voffA);
;             PG8_WAIT_V(8); PG8_WAIT_L(0); PG8_BAR; PG8_MMA(0, 0, At, B0); PG8_MMA(0, 1, At, B1); PG8_BAR; PG8_SCHED;
	v_mfma_f32_16x16x32_bf16 v[4:7], v[170:173], v[210:213], v[4:7]
	v_mfma_f32_16x16x32_bf16 v[0:3], v[178:181], v[210:213], v[0:3]
	s_setprio 0
	s_add_i32 s56, 0, 0x18000
	s_add_i32 s57, 0, 0x1c000
	v_add_u32_e32 v162, s56, v228
	v_add_u32_e32 v178, s57, v228
	ds_read_b128 v[128:131], v162
	ds_read_b128 v[132:135], v162 offset:1024
	ds_read_b128 v[158:161], v162 offset:2048
	ds_read_b128 v[162:165], v162 offset:3072
	ds_read_b128 v[166:169], v178
	ds_read_b128 v[170:173], v178 offset:1024
	ds_read_b128 v[174:177], v178 offset:2048
	ds_read_b128 v[178:181], v178 offset:3072
	s_add_u32 s52, s80, 0x80000
	s_addc_u32 s53, s81, 0
	s_mov_b32 m0, s33
	ds_read_b128 v[182:185], v232 offset:32768
	ds_read_b128 v[186:189], v232 offset:33792
	ds_read_b128 v[190:193], v232 offset:34816
	ds_read_b128 v[194:197], v232 offset:35840
	ds_read_b128 v[198:201], v232 offset:36864
	ds_read_b128 v[202:205], v232 offset:37888
	ds_read_b128 v[206:209], v232 offset:38912
	ds_read_b128 v[210:213], v232 offset:39936
	global_load_lds_dwordx4 v136, s[52:53]
	s_mov_b32 m0, s38
	s_nop 0
	global_load_lds_dwordx4 v140, s[52:53]
	s_waitcnt vmcnt(8)
	s_waitcnt lgkmcnt(0)
	s_setprio 1
	s_barrier
	v_mfma_f32_16x16x32_bf16 v[124:127], v[128:131], v[182:185], v[124:127]
	v_mfma_f32_16x16x32_bf16 v[120:123], v[158:161], v[182:185], v[120:123]
	v_mfma_f32_16x16x32_bf16 v[116:119], v[128:131], v[190:193], v[116:119]
	v_mfma_f32_16x16x32_bf16 v[112:115], v[158:161], v[190:193], v[112:115]
	v_mfma_f32_16x16x32_bf16 v[108:111], v[128:131], v[198:201], v[108:111]
	v_mfma_f32_16x16x32_bf16 v[104:107], v[158:161], v[198:201], v[104:107]
	v_mfma_f32_16x16x32_bf16 v[100:103], v[128:131], v[206:209], v[100:103]
	v_mfma_f32_16x16x32_bf16 v[96:99], v[158:161], v[206:209], v[96:99]
	v_mfma_f32_16x16x32_bf16 v[124:127], v[132:135], v[186:189], v[124:127]
	v_mfma_f32_16x16x32_bf16 v[120:123], v[162:165], v[186:189], v[120:123]
	v_mfma_f32_16x16x32_bf16 v[116:119], v[132:135], v[194:197], v[116:119]
	v_mfma_f32_16x16x32_bf16 v[112:115], v[162:165], v[194:197], v[112:115]
	v_mfma_f32_16x16x32_bf16 v[108:111], v[132:135], v[202:205], v[108:111]
	v_mfma_f32_16x16x32_bf16 v[104:107], v[162:165], v[202:205], v[104:107]
	v_mfma_f32_16x16x32_bf16 v[100:103], v[132:135], v[210:213], v[100:103]
	v_mfma_f32_16x16x32_bf16 v[96:99], v[162:165], v[210:213], v[96:99]
	s_setprio 0
	s_setprio 1
	v_mfma_f32_16x16x32_bf16 v[60:63], v[166:169], v[182:185], v[60:63]
	v_mfma_f32_16x16x32_bf16 v[56:59], v[174:177], v[182:185], v[56:59]
	v_mfma_f32_16x16x32_bf16 v[52:55], v[166:169], v[190:193], v[52:55]
	v_mfma_f32_16x16x32_bf16 v[48:51], v[174:177], v[190:193], v[48:51]
	v_mfma_f32_16x16x32_bf16 v[44:47], v[166:169], v[198:201], v[44:47]
	v_mfma_f32_16x16x32_bf16 v[40:43], v[174:177], v[198:201], v[40:43]
	v_mfma_f32_16x16x32_bf16 v[36:39], v[166:169], v[206:209], v[36:39]
	v_mfma_f32_16x16x32_bf16 v[32:35], v[174:177], v[206:209], v[32:35]
	v_mfma_f32_16x16x32_bf16 v[60:63], v[170:173], v[186:189], v[60:63]
	v_mfma_f32_16x16x32_bf16 v[56:59], v[178:181], v[186:189], v[56:59]
	v_mfma_f32_16x16x32_bf16 v[52:55], v[170:173], v[194:197], v[52:55]
	v_mfma_f32_16x16x32_bf16 v[48:51], v[178:181], v[194:197], v[48:51]
	v_mfma_f32_16x16x32_bf16 v[44:47], v[170:173], v[202:205], v[44:47]
	v_mfma_f32_16x16x32_bf16 v[40:43], v[178:181], v[202:205], v[40:43]
	s_setprio 2
	s_barrier
; #define PG8_STAGE(bufoff, gbase, voff) do { _Pragma("unroll") for (int _i = 0; _i < 2; ++_i) \
;         __builtin_amdgcn_global_load_lds((const unsigned*)((const char*)(gbase) + (voff)[_i]), (PG8_LAS unsigned*)(lds + (bufoff) + ldsw + _i * 8192), 16, 0, 0); } while (0)
; #define PG8_LDA(dst, b, h) do { _Pragma("unroll") for (int m = 0; m < 4; ++m) _Pragma("unroll") for (int k = 0; k < 2; ++k) dst[m][k] = *(const PG8_LAS bf16x8*)(lds + PG8_SA(b, h) + aoff + m * 2048 + k * 1024); } while (0)
; #define PG8_MMA(ai, bj, At, Bt) do { __builtin_amdgcn_s_setprio(1); _Pragma("unroll") for (int m = 0; m < 4; ++m) _Pragma("unroll") for (int n = 0; n < 2; ++n) _Pragma("unroll") for (int k = 0; k < 2; ++k) \
;         acc[ai][bj][m][n] = __builtin_amdgcn_mfma_f32_16x16x32_bf16(Bt[n][k], At[m][k], acc[ai][bj][m][n], 0, 0, 0); __builtin_amdgcn_s_setprio(0); } while (0)
; #define PG8_WAIT_V(n) asm volatile("s_waitcnt vmcnt(" #n ")" ::: "memory")
; #define PG8_WAIT_L(n) asm volatile("s_waitcnt lgkmcnt(" #n ")" ::: "memory")
; #define PG8_BAR __builtin_amdgcn_s_barrier()
; #define PG8_SCHED __builtin_amdgcn_sched_barrier(0)
; template <class Epi, class Sched, bool ALIGN_EPI = false, bool SP2 = false>
; __device__ __forceinline__ void gemm_phase(PG8_LAS unsigned char* lds, const Gemm g, const Sched& S, const Epi& E) {
;     ...
;             PG8_LDA(At, 1, 1); PG8_STAGE(PG8_SB(1, 0), b3, voffB); PG8_STAGE(PG8_SB(1, 1), b3 + hstep, voffB); PG8_STAGE(PG8_SA(1, 0), a3, voffA);
;             PG8_WAIT_V(8); PG8_WAIT_L(0); PG8_BAR; PG8_MMA(1, 0, At, B0); PG8_MMA(1, 1, At, B1); PG8_BAR; PG8_SCHED;
;     ...
;         if constexpr (ALIGN_EPI) { if (wr == 0) PG8_BAR; }
	v_mfma_f32_16x16x32_bf16 v[36:39], v[170:173], v[210:213], v[36:39]
	v_mfma_f32_16x16x32_bf16 v[32:35], v[178:181], v[210:213], v[32:35]
	s_setprio 0
	s_add_i32 s52, s56, s3
	v_lshl_add_u64 v[214:215], v[214:215], 0, s[14:15]
	s_mov_b32 m0, s52
	ds_read_b128 v[182:185], v232 offset:49152
	ds_read_b128 v[186:189], v232 offset:50176
	ds_read_b128 v[190:193], v232 offset:51200
	ds_read_b128 v[194:197], v232 offset:52224
	ds_read_b128 v[198:201], v232 offset:53248
	ds_read_b128 v[202:205], v232 offset:54272
	ds_read_b128 v[206:209], v232 offset:55296
	ds_read_b128 v[210:213], v232 offset:56320
	global_load_lds_dwordx4 v[214:215], off
	s_add_i32 m0, s52, 0x2000
	s_add_u32 s52, s78, 0x80080
	v_lshl_add_u64 v[214:215], v[216:217], 0, s[14:15]
	s_addc_u32 s53, s79, 0
	s_add_i32 s56, s57, s3
	global_load_lds_dwordx4 v[214:215], off
	s_mov_b32 m0, s56
	s_nop 0
	global_load_lds_dwordx4 v138, s[52:53]
	s_add_i32 m0, s56, 0x2000
	s_nop 0
	global_load_lds_dwordx4 v142, s[52:53]
	v_lshl_add_u64 v[214:215], v[218:219], 0, s[14:15]
	s_mov_b32 m0, s88
	s_nop 0
	global_load_lds_dwordx4 v[214:215], off
	v_lshl_add_u64 v[214:215], v[220:221], 0, s[14:15]
	s_mov_b32 m0, s89
	s_nop 0
	global_load_lds_dwordx4 v[214:215], off
	s_waitcnt vmcnt(8)
	s_waitcnt lgkmcnt(0)
	s_setprio 1
	s_barrier
	v_mfma_f32_16x16x32_bf16 v[92:95], v[128:131], v[182:185], v[92:95]
	v_mfma_f32_16x16x32_bf16 v[88:91], v[158:161], v[182:185], v[88:91]
	v_mfma_f32_16x16x32_bf16 v[84:87], v[128:131], v[190:193], v[84:87]
	v_mfma_f32_16x16x32_bf16 v[80:83], v[158:161], v[190:193], v[80:83]
	v_mfma_f32_16x16x32_bf16 v[76:79], v[128:131], v[198:201], v[76:79]
	v_mfma_f32_16x16x32_bf16 v[72:75], v[158:161], v[198:201], v[72:75]
	v_mfma_f32_16x16x32_bf16 v[68:71], v[128:131], v[206:209], v[68:71]
	v_mfma_f32_16x16x32_bf16 v[64:67], v[158:161], v[206:209], v[64:67]
	v_mfma_f32_16x16x32_bf16 v[92:95], v[132:135], v[186:189], v[92:95]
	v_mfma_f32_16x16x32_bf16 v[88:91], v[162:165], v[186:189], v[88:91]
	v_mfma_f32_16x16x32_bf16 v[84:87], v[132:135], v[194:197], v[84:87]
	v_mfma_f32_16x16x32_bf16 v[80:83], v[162:165], v[194:197], v[80:83]
	v_mfma_f32_16x16x32_bf16 v[76:79], v[132:135], v[202:205], v[76:79]
	v_mfma_f32_16x16x32_bf16 v[72:75], v[162:165], v[202:205], v[72:75]
	v_mfma_f32_16x16x32_bf16 v[68:71], v[132:135], v[210:213], v[68:71]
	v_mfma_f32_16x16x32_bf16 v[64:67], v[162:165], v[210:213], v[64:67]
	s_setprio 0
	s_setprio 1
	v_mfma_f32_16x16x32_bf16 v[28:31], v[166:169], v[182:185], v[28:31]
	v_mfma_f32_16x16x32_bf16 v[24:27], v[174:177], v[182:185], v[24:27]
	v_mfma_f32_16x16x32_bf16 v[20:23], v[166:169], v[190:193], v[20:23]
	v_mfma_f32_16x16x32_bf16 v[16:19], v[174:177], v[190:193], v[16:19]
	v_mfma_f32_16x16x32_bf16 v[12:15], v[166:169], v[198:201], v[12:15]
	v_mfma_f32_16x16x32_bf16 v[8:11], v[174:177], v[198:201], v[8:11]
	v_mfma_f32_16x16x32_bf16 v[4:7], v[166:169], v[206:209], v[4:7]
	v_mfma_f32_16x16x32_bf16 v[0:3], v[174:177], v[206:209], v[0:3]
	v_mfma_f32_16x16x32_bf16 v[28:31], v[170:173], v[186:189], v[28:31]
	v_mfma_f32_16x16x32_bf16 v[24:27], v[178:181], v[186:189], v[24:27]
	v_mfma_f32_16x16x32_bf16 v[20:23], v[170:173], v[194:197], v[20:23]
	v_mfma_f32_16x16x32_bf16 v[16:19], v[178:181], v[194:197], v[16:19]
	v_mfma_f32_16x16x32_bf16 v[12:15], v[170:173], v[202:205], v[12:15]
	v_mfma_f32_16x16x32_bf16 v[8:11], v[178:181], v[202:205], v[8:11]
	s_setprio 2
	s_barrier
	v_mfma_f32_16x16x32_bf16 v[4:7], v[170:173], v[210:213], v[4:7]
	v_mfma_f32_16x16x32_bf16 v[0:3], v[178:181], v[210:213], v[0:3]
	s_setprio 0
	s_add_i32 vcc_hi, vcc_hi, 2
	s_add_u32 s76, s76, 0x100
	s_addc_u32 s77, s77, 0
	s_add_u32 s75, s75, 0x100
	s_addc_u32 vcc_lo, vcc_lo, 0
	s_cmp_gt_u32 vcc_hi, 29
	s_cbranch_scc0 .LBB0_374
	s_and_b64 vcc, exec, s[48:49]
	s_cbranch_vccz .LBB0_377
	s_barrier

; #define PG8_STAGE(bufoff, gbase, voff) do { _Pragma("unroll") for (int _i = 0; _i < 2; ++_i) \
;         __builtin_amdgcn_global_load_lds((const unsigned*)((const char*)(gbase) + (voff)[_i]), (PG8_LAS unsigned*)(lds + (bufoff) + ldsw + _i * 8192), 16, 0, 0); } while (0)
; #define PG8_LDA(dst, b, h) do { _Pragma("unroll") for (int m = 0; m < 4; ++m) _Pragma("unroll") for (int k = 0; k < 2; ++k) dst[m][k] = *(const PG8_LAS bf16x8*)(lds + PG8_SA(b, h) + aoff + m * 2048 + k * 1024); } while (0)
; #define PG8_LDB(dst, b, h) do { _Pragma("unroll") for (int n = 0; n < 2; ++n) _Pragma("unroll") for (int k = 0; k < 2; ++k) dst[n][k] = *(const PG8_LAS bf16x8*)(lds + PG8_SB(b, h) + boff + n * 2048 + k * 1024); } while (0)
; #define PG8_MMA(ai, bj, At, Bt) do { __builtin_amdgcn_s_setprio(1); _Pragma("unroll") for (int m = 0; m < 4; ++m) _Pragma("unroll") for (int n = 0; n < 2; ++n) _Pragma("unroll") for (int k = 0; k < 2; ++k) \
;         acc[ai][bj][m][n] = __builtin_amdgcn_mfma_f32_16x16x32_bf16(Bt[n][k], At[m][k], acc[ai][bj][m][n], 0, 0, 0); __builtin_amdgcn_s_setprio(0); } while (0)
; #define PG8_WAIT_V(n) asm volatile("s_waitcnt vmcnt(" #n ")" ::: "memory")
; #define PG8_WAIT_L(n) asm volatile("s_waitcnt lgkmcnt(" #n ")" ::: "memory")
; #define PG8_BAR __builtin_amdgcn_s_barrier()
; template <class Epi, class Sched, bool ALIGN_EPI = false, bool SP2 = false>
; __device__ __forceinline__ void gemm_phase(PG8_LAS unsigned char* lds, const Gemm g, const Sched& S, const Epi& E) {
;     ...
;             const bool last = (t == nt - 2);
;             const char* a1 = cA + (size_t)(t + 1) * kstep;
;             const char* a2 = last ? nA : cA + (size_t)(t + 2) * kstep; const char* b2 = last ? nB : cB + (size_t)(t + 2) * kstep;
;             const char* a3 = a2 + kstep; const char* b3 = b2 + kstep;
;             if constexpr (SP2) {
;             PG8_LDB(B0, 0, 0); PG8_LDB(B1, 0, 1); PG8_SCHED; PG8_LDA(At, 0, 0); PG8_STAGE(PG8_SA(1, 1), a1 + hstep, voffA);
;             PG8_WAIT_V(8); PG8_WAIT_L(0); PG8_BAR; PG8_MMA(0, 0, At, B0); PG8_MMA(0, 1, At, B1); PG8_BAR; PG8_SCHED;
;             PG8_LDA(At, 0, 1); PG8_STAGE(PG8_SB(0, 0), b2, voffB); PG8_STAGE(PG8_SB(0, 1), b2 + hstep, voffB); PG8_STAGE(PG8_SA(0, 0), a2, voffA);
;             PG8_WAIT_V(8); PG8_WAIT_L(0); PG8_BAR; PG8_MMA(1, 0, At, B0); PG8_MMA(1, 1, At, B1); PG8_BAR; PG8_SCHED;
.LBB0_410:
	ds_read_b128 v[166:169], v145
	ds_read_b128 v[170:173], v145 offset:1024
	ds_read_b128 v[174:177], v145 offset:2048
	ds_read_b128 v[178:181], v145 offset:3072
	ds_read_b128 v[182:185], v149
	ds_read_b128 v[186:189], v149 offset:1024
	ds_read_b128 v[190:193], v149 offset:2048
	ds_read_b128 v[194:197], v149 offset:3072
	s_add_u32 s52, s74, 0xfff80080
	s_addc_u32 s53, s75, -1
	s_cmp_eq_u32 s51, 4
	s_cselect_b32 s79, s55, s53
	s_cselect_b32 s78, s54, s52
	s_cselect_b32 s77, s69, s49
	s_cselect_b32 s76, s68, s37
	s_mov_b32 m0, s80
	ds_read_b128 v[198:201], v164
	ds_read_b128 v[202:205], v164 offset:1024
	ds_read_b128 v[206:209], v164 offset:2048
	ds_read_b128 v[210:213], v164 offset:3072
	ds_read_b128 v[214:217], v164 offset:4096
	ds_read_b128 v[218:221], v164 offset:5120
	ds_read_b128 v[222:225], v164 offset:6144
	ds_read_b128 v[226:229], v164 offset:7168
	global_load_lds_dwordx4 v160, s[74:75]
	s_mov_b32 m0, s81
	s_nop 0
	global_load_lds_dwordx4 v162, s[74:75]
	s_waitcnt vmcnt(8)
	s_waitcnt lgkmcnt(0)
	s_setprio 1
	s_barrier
	v_mfma_f32_16x16x32_bf16 v[124:127], v[166:169], v[198:201], v[124:127]
	v_mfma_f32_16x16x32_bf16 v[120:123], v[174:177], v[198:201], v[120:123]
	v_mfma_f32_16x16x32_bf16 v[116:119], v[166:169], v[206:209], v[116:119]
	v_mfma_f32_16x16x32_bf16 v[108:111], v[174:177], v[206:209], v[108:111]
	v_mfma_f32_16x16x32_bf16 v[100:103], v[166:169], v[214:217], v[100:103]
	v_mfma_f32_16x16x32_bf16 v[92:95], v[174:177], v[214:217], v[92:95]
	v_mfma_f32_16x16x32_bf16 v[84:87], v[166:169], v[222:225], v[84:87]
	v_mfma_f32_16x16x32_bf16 v[76:79], v[174:177], v[222:225], v[76:79]
	v_mfma_f32_16x16x32_bf16 v[124:127], v[170:173], v[202:205], v[124:127]
	v_mfma_f32_16x16x32_bf16 v[120:123], v[178:181], v[202:205], v[120:123]
	v_mfma_f32_16x16x32_bf16 v[116:119], v[170:173], v[210:213], v[116:119]
	v_mfma_f32_16x16x32_bf16 v[108:111], v[178:181], v[210:213], v[108:111]
	v_mfma_f32_16x16x32_bf16 v[100:103], v[170:173], v[218:221], v[100:103]
	v_mfma_f32_16x16x32_bf16 v[92:95], v[178:181], v[218:221], v[92:95]
	v_mfma_f32_16x16x32_bf16 v[84:87], v[170:173], v[226:229], v[84:87]
	v_mfma_f32_16x16x32_bf16 v[76:79], v[178:181], v[226:229], v[76:79]
	s_setprio 0
	s_setprio 1
	v_mfma_f32_16x16x32_bf16 v[112:115], v[182:185], v[198:201], v[112:115]
	v_mfma_f32_16x16x32_bf16 v[104:107], v[190:193], v[198:201], v[104:107]
	v_mfma_f32_16x16x32_bf16 v[96:99], v[182:185], v[206:209], v[96:99]
	v_mfma_f32_16x16x32_bf16 v[88:91], v[190:193], v[206:209], v[88:91]
	v_mfma_f32_16x16x32_bf16 v[80:83], v[182:185], v[214:217], v[80:83]
	v_mfma_f32_16x16x32_bf16 v[72:75], v[190:193], v[214:217], v[72:75]
	v_mfma_f32_16x16x32_bf16 v[68:71], v[182:185], v[222:225], v[68:71]
	v_mfma_f32_16x16x32_bf16 v[64:67], v[190:193], v[222:225], v[64:67]
	v_mfma_f32_16x16x32_bf16 v[112:115], v[186:189], v[202:205], v[112:115]
	v_mfma_f32_16x16x32_bf16 v[104:107], v[194:197], v[202:205], v[104:107]
	v_mfma_f32_16x16x32_bf16 v[96:99], v[186:189], v[210:213], v[96:99]
	v_mfma_f32_16x16x32_bf16 v[88:91], v[194:197], v[210:213], v[88:91]
	v_mfma_f32_16x16x32_bf16 v[80:83], v[186:189], v[218:221], v[80:83]
	v_mfma_f32_16x16x32_bf16 v[72:75], v[194:197], v[218:221], v[72:75]
	s_setprio 2
	s_barrier
	v_mfma_f32_16x16x32_bf16 v[68:71], v[186:189], v[226:229], v[68:71]
	v_mfma_f32_16x16x32_bf16 v[64:67], v[194:197], v[226:229], v[64:67]
	s_setprio 0
	s_mov_b32 m0, s84
	v_lshl_add_u64 v[230:231], s[76:77], 0, v[138:139]
	s_add_u32 s52, s76, 0x80000
	ds_read_b128 v[198:201], v164 offset:16384
	ds_read_b128 v[202:205], v164 offset:17408
	ds_read_b128 v[206:209], v164 offset:18432
	ds_read_b128 v[210:213], v164 offset:19456
	ds_read_b128 v[214:217], v164 offset:20480
	ds_read_b128 v[218:221], v164 offset:21504
	ds_read_b128 v[222:225], v164 offset:22528
	ds_read_b128 v[226:229], v164 offset:23552
	global_load_lds_dwordx4 v[230:231], off
	v_lshl_add_u64 v[232:233], s[76:77], 0, v[142:143]
	s_mov_b32 m0, s85
	s_addc_u32 s53, s77, 0
	global_load_lds_dwordx4 v[232:233], off
	s_mov_b32 m0, s86
	v_lshl_add_u64 v[236:237], s[78:79], 0, v[140:141]
	global_load_lds_dwordx4 v138, s[52:53]
	s_mov_b32 m0, s87
	s_nop 0
	global_load_lds_dwordx4 v142, s[52:53]
	v_lshl_add_u64 v[234:235], s[78:79], 0, v[136:137]
	s_mov_b32 m0, s10
	s_nop 0
	global_load_lds_dwordx4 v[234:235], off
	s_mov_b32 m0, s11
	s_nop 0
	global_load_lds_dwordx4 v[236:237], off
	s_waitcnt vmcnt(8)
	s_waitcnt lgkmcnt(0)
	s_setprio 1
	s_barrier
	v_mfma_f32_16x16x32_bf16 v[60:63], v[166:169], v[198:201], v[60:63]
	v_mfma_f32_16x16x32_bf16 v[56:59], v[174:177], v[198:201], v[56:59]
	v_mfma_f32_16x16x32_bf16 v[52:55], v[166:169], v[206:209], v[52:55]
	v_mfma_f32_16x16x32_bf16 v[44:47], v[174:177], v[206:209], v[44:47]
	v_mfma_f32_16x16x32_bf16 v[36:39], v[166:169], v[214:217], v[36:39]
	v_mfma_f32_16x16x32_bf16 v[28:31], v[174:177], v[214:217], v[28:31]
	v_mfma_f32_16x16x32_bf16 v[20:23], v[166:169], v[222:225], v[20:23]
	v_mfma_f32_16x16x32_bf16 v[12:15], v[174:177], v[222:225], v[12:15]
	v_mfma_f32_16x16x32_bf16 v[60:63], v[170:173], v[202:205], v[60:63]
	v_mfma_f32_16x16x32_bf16 v[56:59], v[178:181], v[202:205], v[56:59]
	v_mfma_f32_16x16x32_bf16 v[52:55], v[170:173], v[210:213], v[52:55]
	v_mfma_f32_16x16x32_bf16 v[44:47], v[178:181], v[210:213], v[44:47]
	v_mfma_f32_16x16x32_bf16 v[36:39], v[170:173], v[218:221], v[36:39]
	v_mfma_f32_16x16x32_bf16 v[28:31], v[178:181], v[218:221], v[28:31]
	v_mfma_f32_16x16x32_bf16 v[20:23], v[170:173], v[226:229], v[20:23]
	v_mfma_f32_16x16x32_bf16 v[12:15], v[178:181], v[226:229], v[12:15]
	s_setprio 0
	s_setprio 1
	v_mfma_f32_16x16x32_bf16 v[48:51], v[182:185], v[198:201], v[48:51]
	v_mfma_f32_16x16x32_bf16 v[40:43], v[190:193], v[198:201], v[40:43]
	v_mfma_f32_16x16x32_bf16 v[32:35], v[182:185], v[206:209], v[32:35]
	v_mfma_f32_16x16x32_bf16 v[24:27], v[190:193], v[206:209], v[24:27]
	v_mfma_f32_16x16x32_bf16 v[16:19], v[182:185], v[214:217], v[16:19]
	v_mfma_f32_16x16x32_bf16 v[8:11], v[190:193], v[214:217], v[8:11]
	v_mfma_f32_16x16x32_bf16 v[4:7], v[182:185], v[222:225], v[4:7]
	v_mfma_f32_16x16x32_bf16 v[0:3], v[190:193], v[222:225], v[0:3]
	v_mfma_f32_16x16x32_bf16 v[48:51], v[186:189], v[202:205], v[48:51]
	v_mfma_f32_16x16x32_bf16 v[40:43], v[194:197], v[202:205], v[40:43]
	v_mfma_f32_16x16x32_bf16 v[32:35], v[186:189], v[210:213], v[32:35]
	v_mfma_f32_16x16x32_bf16 v[24:27], v[194:197], v[210:213], v[24:27]
	v_mfma_f32_16x16x32_bf16 v[16:19], v[186:189], v[218:221], v[16:19]
	v_mfma_f32_16x16x32_bf16 v[8:11], v[194:197], v[218:221], v[8:11]
	s_setprio 2
	s_barrier
; #define PG8_STAGE(bufoff, gbase, voff) do { _Pragma("unroll") for (int _i = 0; _i < 2; ++_i) \
;         __builtin_amdgcn_global_load_lds((const unsigned*)((const char*)(gbase) + (voff)[_i]), (PG8_LAS unsigned*)(lds + (bufoff) + ldsw + _i * 8192), 16, 0, 0); } while (0)
; #define PG8_LDA(dst, b, h) do { _Pragma("unroll") for (int m = 0; m < 4; ++m) _Pragma("unroll") for (int k = 0; k < 2; ++k) dst[m][k] = *(const PG8_LAS bf16x8*)(lds + PG8_SA(b, h) + aoff + m * 2048 + k * 1024); } while (0)
; #define PG8_LDB(dst, b, h) do { _Pragma("unroll") for (int n = 0; n < 2; ++n) _Pragma("unroll") for (int k = 0; k < 2; ++k) dst[n][k] = *(const PG8_LAS bf16x8*)(lds + PG8_SB(b, h) + boff + n * 2048 + k * 1024); } while (0)
; #define PG8_MMA(ai, bj, At, Bt) do { __builtin_amdgcn_s_setprio(1); _Pragma("unroll") for (int m = 0; m < 4; ++m) _Pragma("unroll") for (int n = 0; n < 2; ++n) _Pragma("unroll") for (int k = 0; k < 2; ++k) \
;         acc[ai][bj][m][n] = __builtin_amdgcn_mfma_f32_16x16x32_bf16(Bt[n][k], At[m][k], acc[ai][bj][m][n], 0, 0, 0); __builtin_amdgcn_s_setprio(0); } while (0)
; #define PG8_WAIT_V(n) asm volatile("s_waitcnt vmcnt(" #n ")" ::: "memory")
; #define PG8_WAIT_L(n) asm volatile("s_waitcnt lgkmcnt(" #n ")" ::: "memory")
; #define PG8_BAR __builtin_amdgcn_s_barrier()
; #define PG8_SCHED __builtin_amdgcn_sched_barrier(0)
; template <class Epi, class Sched, bool ALIGN_EPI = false, bool SP2 = false>
; __device__ __forceinline__ void gemm_phase(PG8_LAS unsigned char* lds, const Gemm g, const Sched& S, const Epi& E) {
;     ...
;             PG8_LDB(B0, 1, 0); PG8_LDB(B1, 1, 1); PG8_SCHED; PG8_LDA(At, 1, 0); PG8_STAGE(PG8_SA(0, 1), a2 + hstep, voffA);
;             PG8_WAIT_V(8); PG8_WAIT_L(0); PG8_BAR; PG8_MMA(0, 0, At, B0); PG8_MMA(0, 1, At, B1); PG8_BAR; PG8_SCHED;
;             PG8_LDA(At, 1, 1); PG8_STAGE(PG8_SB(1, 0), b3, voffB); PG8_STAGE(PG8_SB(1, 1), b3 + hstep, voffB); PG8_STAGE(PG8_SA(1, 0), a3, voffA);
;             PG8_WAIT_V(8); PG8_WAIT_L(0); PG8_BAR; PG8_MMA(1, 0, At, B0); PG8_MMA(1, 1, At, B1); PG8_BAR; PG8_SCHED;
	v_mfma_f32_16x16x32_bf16 v[4:7], v[186:189], v[226:229], v[4:7]
	v_mfma_f32_16x16x32_bf16 v[0:3], v[194:197], v[226:229], v[0:3]
	s_setprio 0
	ds_read_b128 v[166:169], v148
	ds_read_b128 v[170:173], v148 offset:1024
	ds_read_b128 v[174:177], v148 offset:2048
	ds_read_b128 v[178:181], v148 offset:3072
	ds_read_b128 v[182:185], v165
	ds_read_b128 v[186:189], v165 offset:1024
	ds_read_b128 v[190:193], v165 offset:2048
	ds_read_b128 v[194:197], v165 offset:3072
	s_add_u32 s52, s78, 0x80000
	s_addc_u32 s53, s79, 0
	s_mov_b32 m0, s28
	ds_read_b128 v[198:201], v164 offset:32768
	ds_read_b128 v[202:205], v164 offset:33792
	ds_read_b128 v[206:209], v164 offset:34816
	ds_read_b128 v[210:213], v164 offset:35840
	ds_read_b128 v[214:217], v164 offset:36864
	ds_read_b128 v[218:221], v164 offset:37888
	ds_read_b128 v[222:225], v164 offset:38912
	ds_read_b128 v[226:229], v164 offset:39936
	global_load_lds_dwordx4 v136, s[52:53]
	s_mov_b32 m0, s29
	s_nop 0
	global_load_lds_dwordx4 v140, s[52:53]
	s_waitcnt vmcnt(8)
	s_waitcnt lgkmcnt(0)
	s_setprio 1
	s_barrier
	v_mfma_f32_16x16x32_bf16 v[124:127], v[166:169], v[198:201], v[124:127]
	v_mfma_f32_16x16x32_bf16 v[120:123], v[174:177], v[198:201], v[120:123]
	v_mfma_f32_16x16x32_bf16 v[116:119], v[166:169], v[206:209], v[116:119]
	v_mfma_f32_16x16x32_bf16 v[108:111], v[174:177], v[206:209], v[108:111]
	v_mfma_f32_16x16x32_bf16 v[100:103], v[166:169], v[214:217], v[100:103]
	v_mfma_f32_16x16x32_bf16 v[92:95], v[174:177], v[214:217], v[92:95]
	v_mfma_f32_16x16x32_bf16 v[84:87], v[166:169], v[222:225], v[84:87]
	v_mfma_f32_16x16x32_bf16 v[76:79], v[174:177], v[222:225], v[76:79]
	v_mfma_f32_16x16x32_bf16 v[124:127], v[170:173], v[202:205], v[124:127]
	v_mfma_f32_16x16x32_bf16 v[120:123], v[178:181], v[202:205], v[120:123]
	v_mfma_f32_16x16x32_bf16 v[116:119], v[170:173], v[210:213], v[116:119]
	v_mfma_f32_16x16x32_bf16 v[108:111], v[178:181], v[210:213], v[108:111]
	v_mfma_f32_16x16x32_bf16 v[100:103], v[170:173], v[218:221], v[100:103]
	v_mfma_f32_16x16x32_bf16 v[92:95], v[178:181], v[218:221], v[92:95]
	v_mfma_f32_16x16x32_bf16 v[84:87], v[170:173], v[226:229], v[84:87]
	v_mfma_f32_16x16x32_bf16 v[76:79], v[178:181], v[226:229], v[76:79]
	s_setprio 0
	s_setprio 1
	v_mfma_f32_16x16x32_bf16 v[112:115], v[182:185], v[198:201], v[112:115]
	v_mfma_f32_16x16x32_bf16 v[104:107], v[190:193], v[198:201], v[104:107]
	v_mfma_f32_16x16x32_bf16 v[96:99], v[182:185], v[206:209], v[96:99]
	v_mfma_f32_16x16x32_bf16 v[88:91], v[190:193], v[206:209], v[88:91]
	v_mfma_f32_16x16x32_bf16 v[80:83], v[182:185], v[214:217], v[80:83]
	v_mfma_f32_16x16x32_bf16 v[72:75], v[190:193], v[214:217], v[72:75]
	v_mfma_f32_16x16x32_bf16 v[68:71], v[182:185], v[222:225], v[68:71]
	v_mfma_f32_16x16x32_bf16 v[64:67], v[190:193], v[222:225], v[64:67]
	v_mfma_f32_16x16x32_bf16 v[112:115], v[186:189], v[202:205], v[112:115]
	v_mfma_f32_16x16x32_bf16 v[104:107], v[194:197], v[202:205], v[104:107]
	v_mfma_f32_16x16x32_bf16 v[96:99], v[186:189], v[210:213], v[96:99]
	v_mfma_f32_16x16x32_bf16 v[88:91], v[194:197], v[210:213], v[88:91]
	v_mfma_f32_16x16x32_bf16 v[80:83], v[186:189], v[218:221], v[80:83]
	v_mfma_f32_16x16x32_bf16 v[72:75], v[194:197], v[218:221], v[72:75]
	s_setprio 2
	s_barrier
	v_mfma_f32_16x16x32_bf16 v[68:71], v[186:189], v[226:229], v[68:71]
	v_mfma_f32_16x16x32_bf16 v[64:67], v[194:197], v[226:229], v[64:67]
	s_setprio 0
	s_mov_b32 m0, s89
	v_lshl_add_u64 v[230:231], v[230:231], 0, s[12:13]
	ds_read_b128 v[198:201], v164 offset:49152
	ds_read_b128 v[202:205], v164 offset:50176
	ds_read_b128 v[206:209], v164 offset:51200
	ds_read_b128 v[210:213], v164 offset:52224
	ds_read_b128 v[214:217], v164 offset:53248
	ds_read_b128 v[218:221], v164 offset:54272
	ds_read_b128 v[222:225], v164 offset:55296
	ds_read_b128 v[226:229], v164 offset:56320
	global_load_lds_dwordx4 v[230:231], off
	s_add_i32 m0, s89, 0x2000
	s_add_u32 s52, s76, 0x80080
	v_lshl_add_u64 v[230:231], v[232:233], 0, s[12:13]
	s_addc_u32 s53, s77, 0
	s_add_i32 s56, s88, s3
	global_load_lds_dwordx4 v[230:231], off
	s_mov_b32 m0, s56
	s_nop 0
	global_load_lds_dwordx4 v138, s[52:53]
	s_add_i32 m0, s56, 0x2000
	s_nop 0
	global_load_lds_dwordx4 v142, s[52:53]
	v_lshl_add_u64 v[230:231], v[234:235], 0, s[12:13]
	s_mov_b32 m0, s38
	s_nop 0
	global_load_lds_dwordx4 v[230:231], off
	v_lshl_add_u64 v[230:231], v[236:237], 0, s[12:13]
	s_mov_b32 m0, s39
	s_nop 0
	global_load_lds_dwordx4 v[230:231], off
	s_waitcnt vmcnt(8)
	s_waitcnt lgkmcnt(0)
	s_setprio 1
	s_barrier
	v_mfma_f32_16x16x32_bf16 v[60:63], v[166:169], v[198:201], v[60:63]
	v_mfma_f32_16x16x32_bf16 v[56:59], v[174:177], v[198:201], v[56:59]
	v_mfma_f32_16x16x32_bf16 v[52:55], v[166:169], v[206:209], v[52:55]
	v_mfma_f32_16x16x32_bf16 v[44:47], v[174:177], v[206:209], v[44:47]
	v_mfma_f32_16x16x32_bf16 v[36:39], v[166:169], v[214:217], v[36:39]
	v_mfma_f32_16x16x32_bf16 v[28:31], v[174:177], v[214:217], v[28:31]
	v_mfma_f32_16x16x32_bf16 v[20:23], v[166:169], v[222:225], v[20:23]
	v_mfma_f32_16x16x32_bf16 v[12:15], v[174:177], v[222:225], v[12:15]
	v_mfma_f32_16x16x32_bf16 v[60:63], v[170:173], v[202:205], v[60:63]
	v_mfma_f32_16x16x32_bf16 v[56:59], v[178:181], v[202:205], v[56:59]
	v_mfma_f32_16x16x32_bf16 v[52:55], v[170:173], v[210:213], v[52:55]
	v_mfma_f32_16x16x32_bf16 v[44:47], v[178:181], v[210:213], v[44:47]
	v_mfma_f32_16x16x32_bf16 v[36:39], v[170:173], v[218:221], v[36:39]
	v_mfma_f32_16x16x32_bf16 v[28:31], v[178:181], v[218:221], v[28:31]
	v_mfma_f32_16x16x32_bf16 v[20:23], v[170:173], v[226:229], v[20:23]
	v_mfma_f32_16x16x32_bf16 v[12:15], v[178:181], v[226:229], v[12:15]
	s_setprio 0
	s_setprio 1
	v_mfma_f32_16x16x32_bf16 v[48:51], v[182:185], v[198:201], v[48:51]
	v_mfma_f32_16x16x32_bf16 v[40:43], v[190:193], v[198:201], v[40:43]
	v_mfma_f32_16x16x32_bf16 v[32:35], v[182:185], v[206:209], v[32:35]
	v_mfma_f32_16x16x32_bf16 v[24:27], v[190:193], v[206:209], v[24:27]
	v_mfma_f32_16x16x32_bf16 v[16:19], v[182:185], v[214:217], v[16:19]
	v_mfma_f32_16x16x32_bf16 v[8:11], v[190:193], v[214:217], v[8:11]
	v_mfma_f32_16x16x32_bf16 v[4:7], v[182:185], v[222:225], v[4:7]
	v_mfma_f32_16x16x32_bf16 v[0:3], v[190:193], v[222:225], v[0:3]
	v_mfma_f32_16x16x32_bf16 v[48:51], v[186:189], v[202:205], v[48:51]
	v_mfma_f32_16x16x32_bf16 v[40:43], v[194:197], v[202:205], v[40:43]
	v_mfma_f32_16x16x32_bf16 v[32:35], v[186:189], v[210:213], v[32:35]
	v_mfma_f32_16x16x32_bf16 v[24:27], v[194:197], v[210:213], v[24:27]
	v_mfma_f32_16x16x32_bf16 v[16:19], v[186:189], v[218:221], v[16:19]
	v_mfma_f32_16x16x32_bf16 v[8:11], v[194:197], v[218:221], v[8:11]
	s_setprio 2
	s_barrier
	v_mfma_f32_16x16x32_bf16 v[4:7], v[186:189], v[226:229], v[4:7]
	v_mfma_f32_16x16x32_bf16 v[0:3], v[194:197], v[226:229], v[0:3]
	s_setprio 0
	s_add_i32 s51, s51, 2
	s_add_u32 s74, s74, 0x100
	s_addc_u32 s75, s75, 0
	s_add_u32 s37, s37, 0x100
	s_addc_u32 s49, s49, 0
	s_cmp_gt_u32 s51, 5
	s_cbranch_scc0 .LBB0_410
	s_and_b64 vcc, exec, s[14:15]
	s_cbranch_vccz .LBB0_413
	s_barrier

; #define PG8_STAGE(bufoff, gbase, voff) do { _Pragma("unroll") for (int _i = 0; _i < 2; ++_i) \
;         __builtin_amdgcn_global_load_lds((const unsigned*)((const char*)(gbase) + (voff)[_i]), (PG8_LAS unsigned*)(lds + (bufoff) + ldsw + _i * 8192), 16, 0, 0); } while (0)
; #define PG8_LDA(dst, b, h) do { _Pragma("unroll") for (int m = 0; m < 4; ++m) _Pragma("unroll") for (int k = 0; k < 2; ++k) dst[m][k] = *(const PG8_LAS bf16x8*)(lds + PG8_SA(b, h) + aoff + m * 2048 + k * 1024); } while (0)
; #define PG8_LDB(dst, b, h) do { _Pragma("unroll") for (int n = 0; n < 2; ++n) _Pragma("unroll") for (int k = 0; k < 2; ++k) dst[n][k] = *(const PG8_LAS bf16x8*)(lds + PG8_SB(b, h) + boff + n * 2048 + k * 1024); } while (0)
; #define PG8_MMA(ai, bj, At, Bt) do { __builtin_amdgcn_s_setprio(1); _Pragma("unroll") for (int m = 0; m < 4; ++m) _Pragma("unroll") for (int n = 0; n < 2; ++n) _Pragma("unroll") for (int k = 0; k < 2; ++k) \
;         acc[ai][bj][m][n] = __builtin_amdgcn_mfma_f32_16x16x32_bf16(Bt[n][k], At[m][k], acc[ai][bj][m][n], 0, 0, 0); __builtin_amdgcn_s_setprio(0); } while (0)
; #define PG8_WAIT_V(n) asm volatile("s_waitcnt vmcnt(" #n ")" ::: "memory")
; #define PG8_WAIT_L(n) asm volatile("s_waitcnt lgkmcnt(" #n ")" ::: "memory")
; #define PG8_BAR __builtin_amdgcn_s_barrier()
; template <class Epi, class Sched, bool ALIGN_EPI = false, bool SP2 = false>
; __device__ __forceinline__ void gemm_phase(PG8_LAS unsigned char* lds, const Gemm g, const Sched& S, const Epi& E) {
;     ...
;             const bool last = (t == nt - 2);
;             const char* a1 = cA + (size_t)(t + 1) * kstep;
;             const char* a2 = last ? nA : cA + (size_t)(t + 2) * kstep; const char* b2 = last ? nB : cB + (size_t)(t + 2) * kstep;
;             const char* a3 = a2 + kstep; const char* b3 = b2 + kstep;
;             if constexpr (SP2) {
;             PG8_LDB(B0, 0, 0); PG8_LDB(B1, 0, 1); PG8_SCHED; PG8_LDA(At, 0, 0); PG8_STAGE(PG8_SA(1, 1), a1 + hstep, voffA);
;             PG8_WAIT_V(8); PG8_WAIT_L(0); PG8_BAR; PG8_MMA(0, 0, At, B0); PG8_MMA(0, 1, At, B1); PG8_BAR; PG8_SCHED;
;             PG8_LDA(At, 0, 1); PG8_STAGE(PG8_SB(0, 0), b2, voffB); PG8_STAGE(PG8_SB(0, 1), b2 + hstep, voffB); PG8_STAGE(PG8_SA(0, 0), a2, voffA);
;             PG8_WAIT_V(8); PG8_WAIT_L(0); PG8_BAR; PG8_MMA(1, 0, At, B0); PG8_MMA(1, 1, At, B1); PG8_BAR; PG8_SCHED;
.LBB0_545:
	ds_read_b128 v[112:115], v174
	ds_read_b128 v[116:119], v174 offset:1024
	ds_read_b128 v[120:123], v174 offset:2048
	ds_read_b128 v[124:127], v174 offset:3072
	ds_read_b128 v[164:167], v175
	ds_read_b128 v[168:171], v175 offset:1024
	ds_read_b128 v[178:181], v175 offset:2048
	ds_read_b128 v[182:185], v175 offset:3072
	s_add_u32 s52, s68, 0xfff80080
	s_addc_u32 s53, s69, -1
	s_cmp_eq_u32 s88, 28
	s_cselect_b32 s73, s41, s53
	s_cselect_b32 s72, s84, s52
	s_cselect_b32 s71, s37, s87
	s_cselect_b32 s70, s85, s86
	s_add_i32 m0, s39, 0xc000
	ds_read_b128 v[186:189], v176
	ds_read_b128 v[190:193], v176 offset:1024
	ds_read_b128 v[194:197], v176 offset:2048
	ds_read_b128 v[198:201], v176 offset:3072
	ds_read_b128 v[202:205], v176 offset:4096
	ds_read_b128 v[206:209], v176 offset:5120
	ds_read_b128 v[210:213], v176 offset:6144
	ds_read_b128 v[214:217], v176 offset:7168
	global_load_lds_dwordx4 v156, s[68:69]
	s_add_i32 m0, s39, 0xe000
	s_nop 0
	global_load_lds_dwordx4 v158, s[68:69]
	s_waitcnt vmcnt(8)
	s_waitcnt lgkmcnt(0)
	s_setprio 1
	s_barrier
	v_mfma_f32_16x16x32_bf16 v[140:143], v[112:115], v[186:189], v[140:143]
	v_mfma_f32_16x16x32_bf16 v[136:139], v[120:123], v[186:189], v[136:139]
	v_mfma_f32_16x16x32_bf16 v[108:111], v[112:115], v[194:197], v[108:111]
	v_mfma_f32_16x16x32_bf16 v[104:107], v[120:123], v[194:197], v[104:107]
	v_mfma_f32_16x16x32_bf16 v[92:95], v[112:115], v[202:205], v[92:95]
	v_mfma_f32_16x16x32_bf16 v[88:91], v[120:123], v[202:205], v[88:91]
	v_mfma_f32_16x16x32_bf16 v[76:79], v[112:115], v[210:213], v[76:79]
	v_mfma_f32_16x16x32_bf16 v[72:75], v[120:123], v[210:213], v[72:75]
	v_mfma_f32_16x16x32_bf16 v[140:143], v[116:119], v[190:193], v[140:143]
	v_mfma_f32_16x16x32_bf16 v[136:139], v[124:127], v[190:193], v[136:139]
	v_mfma_f32_16x16x32_bf16 v[108:111], v[116:119], v[198:201], v[108:111]
	v_mfma_f32_16x16x32_bf16 v[104:107], v[124:127], v[198:201], v[104:107]
	v_mfma_f32_16x16x32_bf16 v[92:95], v[116:119], v[206:209], v[92:95]
	v_mfma_f32_16x16x32_bf16 v[88:91], v[124:127], v[206:209], v[88:91]
	v_mfma_f32_16x16x32_bf16 v[76:79], v[116:119], v[214:217], v[76:79]
	v_mfma_f32_16x16x32_bf16 v[72:75], v[124:127], v[214:217], v[72:75]
	s_setprio 0
	s_setprio 1
	v_mfma_f32_16x16x32_bf16 v[132:135], v[164:167], v[186:189], v[132:135]
	v_mfma_f32_16x16x32_bf16 v[128:131], v[178:181], v[186:189], v[128:131]
	v_mfma_f32_16x16x32_bf16 v[100:103], v[164:167], v[194:197], v[100:103]
	v_mfma_f32_16x16x32_bf16 v[96:99], v[178:181], v[194:197], v[96:99]
	v_mfma_f32_16x16x32_bf16 v[84:87], v[164:167], v[202:205], v[84:87]
	v_mfma_f32_16x16x32_bf16 v[80:83], v[178:181], v[202:205], v[80:83]
	v_mfma_f32_16x16x32_bf16 v[68:71], v[164:167], v[210:213], v[68:71]
	v_mfma_f32_16x16x32_bf16 v[64:67], v[178:181], v[210:213], v[64:67]
	v_mfma_f32_16x16x32_bf16 v[132:135], v[168:171], v[190:193], v[132:135]
	v_mfma_f32_16x16x32_bf16 v[128:131], v[182:185], v[190:193], v[128:131]
	v_mfma_f32_16x16x32_bf16 v[100:103], v[168:171], v[198:201], v[100:103]
	v_mfma_f32_16x16x32_bf16 v[96:99], v[182:185], v[198:201], v[96:99]
	v_mfma_f32_16x16x32_bf16 v[84:87], v[168:171], v[206:209], v[84:87]
	v_mfma_f32_16x16x32_bf16 v[80:83], v[182:185], v[206:209], v[80:83]
	s_setprio 2
	s_barrier
	v_mfma_f32_16x16x32_bf16 v[68:71], v[168:171], v[214:217], v[68:71]
	v_mfma_f32_16x16x32_bf16 v[64:67], v[182:185], v[214:217], v[64:67]
	s_setprio 0
	s_add_i32 s52, s81, s29
	v_lshl_add_u64 v[218:219], s[70:71], 0, v[152:153]
	s_mov_b32 m0, s52
	ds_read_b128 v[186:189], v176 offset:16384
	ds_read_b128 v[190:193], v176 offset:17408
	ds_read_b128 v[194:197], v176 offset:18432
	ds_read_b128 v[198:201], v176 offset:19456
	ds_read_b128 v[202:205], v176 offset:20480
	ds_read_b128 v[206:209], v176 offset:21504
	ds_read_b128 v[210:213], v176 offset:22528
	ds_read_b128 v[214:217], v176 offset:23552
	global_load_lds_dwordx4 v[218:219], off
	s_add_i32 m0, s52, 0x2000
	s_add_u32 s52, s70, 0x80000
	v_lshl_add_u64 v[220:221], s[70:71], 0, v[148:149]
	s_addc_u32 s53, s71, 0
	s_add_i32 s56, s82, s29
	global_load_lds_dwordx4 v[220:221], off
	s_mov_b32 m0, s56
	v_lshl_add_u64 v[224:225], s[72:73], 0, v[150:151]
	global_load_lds_dwordx4 v152, s[52:53]
	s_add_i32 m0, s56, 0x2000
	s_nop 0
	global_load_lds_dwordx4 v148, s[52:53]
	v_lshl_add_u64 v[222:223], s[72:73], 0, v[154:155]
	s_mov_b32 m0, s39
	s_nop 0
	global_load_lds_dwordx4 v[222:223], off
	s_mov_b32 m0, s55
	s_nop 0
	global_load_lds_dwordx4 v[224:225], off
	s_waitcnt vmcnt(8)
	s_waitcnt lgkmcnt(0)
	s_setprio 1
	s_barrier
	v_mfma_f32_16x16x32_bf16 v[60:63], v[112:115], v[186:189], v[60:63]
	v_mfma_f32_16x16x32_bf16 v[56:59], v[120:123], v[186:189], v[56:59]
	v_mfma_f32_16x16x32_bf16 v[44:47], v[112:115], v[194:197], v[44:47]
	v_mfma_f32_16x16x32_bf16 v[40:43], v[120:123], v[194:197], v[40:43]
	v_mfma_f32_16x16x32_bf16 v[28:31], v[112:115], v[202:205], v[28:31]
	v_mfma_f32_16x16x32_bf16 v[24:27], v[120:123], v[202:205], v[24:27]
	v_mfma_f32_16x16x32_bf16 v[12:15], v[112:115], v[210:213], v[12:15]
	v_mfma_f32_16x16x32_bf16 v[8:11], v[120:123], v[210:213], v[8:11]
	v_mfma_f32_16x16x32_bf16 v[60:63], v[116:119], v[190:193], v[60:63]
	v_mfma_f32_16x16x32_bf16 v[56:59], v[124:127], v[190:193], v[56:59]
	v_mfma_f32_16x16x32_bf16 v[44:47], v[116:119], v[198:201], v[44:47]
	v_mfma_f32_16x16x32_bf16 v[40:43], v[124:127], v[198:201], v[40:43]
	v_mfma_f32_16x16x32_bf16 v[28:31], v[116:119], v[206:209], v[28:31]
	v_mfma_f32_16x16x32_bf16 v[24:27], v[124:127], v[206:209], v[24:27]
	v_mfma_f32_16x16x32_bf16 v[12:15], v[116:119], v[214:217], v[12:15]
	v_mfma_f32_16x16x32_bf16 v[8:11], v[124:127], v[214:217], v[8:11]
	s_setprio 0
	s_setprio 1
	v_mfma_f32_16x16x32_bf16 v[52:55], v[164:167], v[186:189], v[52:55]
	v_mfma_f32_16x16x32_bf16 v[48:51], v[178:181], v[186:189], v[48:51]
	v_mfma_f32_16x16x32_bf16 v[36:39], v[164:167], v[194:197], v[36:39]
	v_mfma_f32_16x16x32_bf16 v[32:35], v[178:181], v[194:197], v[32:35]
	v_mfma_f32_16x16x32_bf16 v[20:23], v[164:167], v[202:205], v[20:23]
	v_mfma_f32_16x16x32_bf16 v[16:19], v[178:181], v[202:205], v[16:19]
	v_mfma_f32_16x16x32_bf16 v[4:7], v[164:167], v[210:213], v[4:7]
	v_mfma_f32_16x16x32_bf16 v[0:3], v[178:181], v[210:213], v[0:3]
	v_mfma_f32_16x16x32_bf16 v[52:55], v[168:171], v[190:193], v[52:55]
	v_mfma_f32_16x16x32_bf16 v[48:51], v[182:185], v[190:193], v[48:51]
	v_mfma_f32_16x16x32_bf16 v[36:39], v[168:171], v[198:201], v[36:39]
	v_mfma_f32_16x16x32_bf16 v[32:35], v[182:185], v[198:201], v[32:35]
	v_mfma_f32_16x16x32_bf16 v[20:23], v[168:171], v[206:209], v[20:23]
	v_mfma_f32_16x16x32_bf16 v[16:19], v[182:185], v[206:209], v[16:19]
	s_setprio 2
	s_barrier
; #define PG8_STAGE(bufoff, gbase, voff) do { _Pragma("unroll") for (int _i = 0; _i < 2; ++_i) \
;         __builtin_amdgcn_global_load_lds((const unsigned*)((const char*)(gbase) + (voff)[_i]), (PG8_LAS unsigned*)(lds + (bufoff) + ldsw + _i * 8192), 16, 0, 0); } while (0)
; #define PG8_LDA(dst, b, h) do { _Pragma("unroll") for (int m = 0; m < 4; ++m) _Pragma("unroll") for (int k = 0; k < 2; ++k) dst[m][k] = *(const PG8_LAS bf16x8*)(lds + PG8_SA(b, h) + aoff + m * 2048 + k * 1024); } while (0)
; #define PG8_LDB(dst, b, h) do { _Pragma("unroll") for (int n = 0; n < 2; ++n) _Pragma("unroll") for (int k = 0; k < 2; ++k) dst[n][k] = *(const PG8_LAS bf16x8*)(lds + PG8_SB(b, h) + boff + n * 2048 + k * 1024); } while (0)
; #define PG8_MMA(ai, bj, At, Bt) do { __builtin_amdgcn_s_setprio(1); _Pragma("unroll") for (int m = 0; m < 4; ++m) _Pragma("unroll") for (int n = 0; n < 2; ++n) _Pragma("unroll") for (int k = 0; k < 2; ++k) \
;         acc[ai][bj][m][n] = __builtin_amdgcn_mfma_f32_16x16x32_bf16(Bt[n][k], At[m][k], acc[ai][bj][m][n], 0, 0, 0); __builtin_amdgcn_s_setprio(0); } while (0)
; #define PG8_WAIT_V(n) asm volatile("s_waitcnt vmcnt(" #n ")" ::: "memory")
; #define PG8_WAIT_L(n) asm volatile("s_waitcnt lgkmcnt(" #n ")" ::: "memory")
; #define PG8_BAR __builtin_amdgcn_s_barrier()
; #define PG8_SCHED __builtin_amdgcn_sched_barrier(0)
; template <class Epi, class Sched, bool ALIGN_EPI = false, bool SP2 = false>
; __device__ __forceinline__ void gemm_phase(PG8_LAS unsigned char* lds, const Gemm g, const Sched& S, const Epi& E) {
;     ...
;             PG8_LDB(B0, 1, 0); PG8_LDB(B1, 1, 1); PG8_SCHED; PG8_LDA(At, 1, 0); PG8_STAGE(PG8_SA(0, 1), a2 + hstep, voffA);
;             PG8_WAIT_V(8); PG8_WAIT_L(0); PG8_BAR; PG8_MMA(0, 0, At, B0); PG8_MMA(0, 1, At, B1); PG8_BAR; PG8_SCHED;
	v_mfma_f32_16x16x32_bf16 v[4:7], v[168:171], v[214:217], v[4:7]
	v_mfma_f32_16x16x32_bf16 v[0:3], v[182:185], v[214:217], v[0:3]
	s_setprio 0
	s_add_i32 s56, 0, 0x18000
	s_add_i32 s57, 0, 0x1c000
	v_add_u32_e32 v124, s56, v172
	v_add_u32_e32 v177, s57, v172
	ds_read_b128 v[112:115], v124
	ds_read_b128 v[116:119], v124 offset:1024
	ds_read_b128 v[120:123], v124 offset:2048
	ds_read_b128 v[124:127], v124 offset:3072
	ds_read_b128 v[164:167], v177
	ds_read_b128 v[168:171], v177 offset:1024
	ds_read_b128 v[178:181], v177 offset:2048
	ds_read_b128 v[182:185], v177 offset:3072
	s_add_u32 s52, s72, 0x80000
	s_addc_u32 s53, s73, 0
	s_mov_b32 m0, s74
	ds_read_b128 v[186:189], v176 offset:32768
	ds_read_b128 v[190:193], v176 offset:33792
	ds_read_b128 v[194:197], v176 offset:34816
	ds_read_b128 v[198:201], v176 offset:35840
	ds_read_b128 v[202:205], v176 offset:36864
	ds_read_b128 v[206:209], v176 offset:37888
	ds_read_b128 v[210:213], v176 offset:38912
	ds_read_b128 v[214:217], v176 offset:39936
	global_load_lds_dwordx4 v154, s[52:53]
	s_mov_b32 m0, s75
	s_nop 0
	global_load_lds_dwordx4 v150, s[52:53]
	s_waitcnt vmcnt(8)
	s_waitcnt lgkmcnt(0)
	s_setprio 1
	s_barrier
	v_mfma_f32_16x16x32_bf16 v[140:143], v[112:115], v[186:189], v[140:143]
	v_mfma_f32_16x16x32_bf16 v[136:139], v[120:123], v[186:189], v[136:139]
	v_mfma_f32_16x16x32_bf16 v[108:111], v[112:115], v[194:197], v[108:111]
	v_mfma_f32_16x16x32_bf16 v[104:107], v[120:123], v[194:197], v[104:107]
	v_mfma_f32_16x16x32_bf16 v[92:95], v[112:115], v[202:205], v[92:95]
	v_mfma_f32_16x16x32_bf16 v[88:91], v[120:123], v[202:205], v[88:91]
	v_mfma_f32_16x16x32_bf16 v[76:79], v[112:115], v[210:213], v[76:79]
	v_mfma_f32_16x16x32_bf16 v[72:75], v[120:123], v[210:213], v[72:75]
	v_mfma_f32_16x16x32_bf16 v[140:143], v[116:119], v[190:193], v[140:143]
	v_mfma_f32_16x16x32_bf16 v[136:139], v[124:127], v[190:193], v[136:139]
	v_mfma_f32_16x16x32_bf16 v[108:111], v[116:119], v[198:201], v[108:111]
	v_mfma_f32_16x16x32_bf16 v[104:107], v[124:127], v[198:201], v[104:107]
	v_mfma_f32_16x16x32_bf16 v[92:95], v[116:119], v[206:209], v[92:95]
	v_mfma_f32_16x16x32_bf16 v[88:91], v[124:127], v[206:209], v[88:91]
	v_mfma_f32_16x16x32_bf16 v[76:79], v[116:119], v[214:217], v[76:79]
	v_mfma_f32_16x16x32_bf16 v[72:75], v[124:127], v[214:217], v[72:75]
	s_setprio 0
	s_setprio 1
	v_mfma_f32_16x16x32_bf16 v[132:135], v[164:167], v[186:189], v[132:135]
	v_mfma_f32_16x16x32_bf16 v[128:131], v[178:181], v[186:189], v[128:131]
	v_mfma_f32_16x16x32_bf16 v[100:103], v[164:167], v[194:197], v[100:103]
	v_mfma_f32_16x16x32_bf16 v[96:99], v[178:181], v[194:197], v[96:99]
	v_mfma_f32_16x16x32_bf16 v[84:87], v[164:167], v[202:205], v[84:87]
	v_mfma_f32_16x16x32_bf16 v[80:83], v[178:181], v[202:205], v[80:83]
	v_mfma_f32_16x16x32_bf16 v[68:71], v[164:167], v[210:213], v[68:71]
	v_mfma_f32_16x16x32_bf16 v[64:67], v[178:181], v[210:213], v[64:67]
	v_mfma_f32_16x16x32_bf16 v[132:135], v[168:171], v[190:193], v[132:135]
	v_mfma_f32_16x16x32_bf16 v[128:131], v[182:185], v[190:193], v[128:131]
	v_mfma_f32_16x16x32_bf16 v[100:103], v[168:171], v[198:201], v[100:103]
	v_mfma_f32_16x16x32_bf16 v[96:99], v[182:185], v[198:201], v[96:99]
	v_mfma_f32_16x16x32_bf16 v[84:87], v[168:171], v[206:209], v[84:87]
	v_mfma_f32_16x16x32_bf16 v[80:83], v[182:185], v[206:209], v[80:83]
	s_setprio 2
	s_barrier
; #define PG8_STAGE(bufoff, gbase, voff) do { _Pragma("unroll") for (int _i = 0; _i < 2; ++_i) \
;         __builtin_amdgcn_global_load_lds((const unsigned*)((const char*)(gbase) + (voff)[_i]), (PG8_LAS unsigned*)(lds + (bufoff) + ldsw + _i * 8192), 16, 0, 0); } while (0)
; #define PG8_LDA(dst, b, h) do { _Pragma("unroll") for (int m = 0; m < 4; ++m) _Pragma("unroll") for (int k = 0; k < 2; ++k) dst[m][k] = *(const PG8_LAS bf16x8*)(lds + PG8_SA(b, h) + aoff + m * 2048 + k * 1024); } while (0)
; #define PG8_MMA(ai, bj, At, Bt) do { __builtin_amdgcn_s_setprio(1); _Pragma("unroll") for (int m = 0; m < 4; ++m) _Pragma("unroll") for (int n = 0; n < 2; ++n) _Pragma("unroll") for (int k = 0; k < 2; ++k) \
;         acc[ai][bj][m][n] = __builtin_amdgcn_mfma_f32_16x16x32_bf16(Bt[n][k], At[m][k], acc[ai][bj][m][n], 0, 0, 0); __builtin_amdgcn_s_setprio(0); } while (0)
; #define PG8_WAIT_V(n) asm volatile("s_waitcnt vmcnt(" #n ")" ::: "memory")
; #define PG8_WAIT_L(n) asm volatile("s_waitcnt lgkmcnt(" #n ")" ::: "memory")
; #define PG8_BAR __builtin_amdgcn_s_barrier()
; #define PG8_SCHED __builtin_amdgcn_sched_barrier(0)
; template <class Epi, class Sched, bool ALIGN_EPI = false, bool SP2 = false>
; __device__ __forceinline__ void gemm_phase(PG8_LAS unsigned char* lds, const Gemm g, const Sched& S, const Epi& E) {
;     ...
;             PG8_LDA(At, 1, 1); PG8_STAGE(PG8_SB(1, 0), b3, voffB); PG8_STAGE(PG8_SB(1, 1), b3 + hstep, voffB); PG8_STAGE(PG8_SA(1, 0), a3, voffA);
;             PG8_WAIT_V(8); PG8_WAIT_L(0); PG8_BAR; PG8_MMA(1, 0, At, B0); PG8_MMA(1, 1, At, B1); PG8_BAR; PG8_SCHED;
;     ...
;         if constexpr (ALIGN_EPI) { if (wr == 0) PG8_BAR; }
	v_mfma_f32_16x16x32_bf16 v[68:71], v[168:171], v[214:217], v[68:71]
	v_mfma_f32_16x16x32_bf16 v[64:67], v[182:185], v[214:217], v[64:67]
	s_setprio 0
	s_add_i32 s52, s56, s29
	v_lshl_add_u64 v[218:219], v[218:219], 0, s[12:13]
	s_mov_b32 m0, s52
	ds_read_b128 v[186:189], v176 offset:49152
	ds_read_b128 v[190:193], v176 offset:50176
	ds_read_b128 v[194:197], v176 offset:51200
	ds_read_b128 v[198:201], v176 offset:52224
	ds_read_b128 v[202:205], v176 offset:53248
	ds_read_b128 v[206:209], v176 offset:54272
	ds_read_b128 v[210:213], v176 offset:55296
	ds_read_b128 v[214:217], v176 offset:56320
	global_load_lds_dwordx4 v[218:219], off
	s_add_i32 m0, s52, 0x2000
	s_add_u32 s52, s70, 0x80080
	v_lshl_add_u64 v[218:219], v[220:221], 0, s[12:13]
	s_addc_u32 s53, s71, 0
	s_add_i32 s56, s57, s29
	global_load_lds_dwordx4 v[218:219], off
	s_mov_b32 m0, s56
	s_nop 0
	global_load_lds_dwordx4 v152, s[52:53]
	s_add_i32 m0, s56, 0x2000
	s_nop 0
	global_load_lds_dwordx4 v148, s[52:53]
	v_lshl_add_u64 v[218:219], v[222:223], 0, s[12:13]
	s_mov_b32 m0, s77
	s_nop 0
	global_load_lds_dwordx4 v[218:219], off
	v_lshl_add_u64 v[218:219], v[224:225], 0, s[12:13]
	s_mov_b32 m0, s78
	s_nop 0
	global_load_lds_dwordx4 v[218:219], off
	s_waitcnt vmcnt(8)
	s_waitcnt lgkmcnt(0)
	s_setprio 1
	s_barrier
	v_mfma_f32_16x16x32_bf16 v[60:63], v[112:115], v[186:189], v[60:63]
	v_mfma_f32_16x16x32_bf16 v[56:59], v[120:123], v[186:189], v[56:59]
	v_mfma_f32_16x16x32_bf16 v[44:47], v[112:115], v[194:197], v[44:47]
	v_mfma_f32_16x16x32_bf16 v[40:43], v[120:123], v[194:197], v[40:43]
	v_mfma_f32_16x16x32_bf16 v[28:31], v[112:115], v[202:205], v[28:31]
	v_mfma_f32_16x16x32_bf16 v[24:27], v[120:123], v[202:205], v[24:27]
	v_mfma_f32_16x16x32_bf16 v[12:15], v[112:115], v[210:213], v[12:15]
	v_mfma_f32_16x16x32_bf16 v[8:11], v[120:123], v[210:213], v[8:11]
	v_mfma_f32_16x16x32_bf16 v[60:63], v[116:119], v[190:193], v[60:63]
	v_mfma_f32_16x16x32_bf16 v[56:59], v[124:127], v[190:193], v[56:59]
	v_mfma_f32_16x16x32_bf16 v[44:47], v[116:119], v[198:201], v[44:47]
	v_mfma_f32_16x16x32_bf16 v[40:43], v[124:127], v[198:201], v[40:43]
	v_mfma_f32_16x16x32_bf16 v[28:31], v[116:119], v[206:209], v[28:31]
	v_mfma_f32_16x16x32_bf16 v[24:27], v[124:127], v[206:209], v[24:27]
	v_mfma_f32_16x16x32_bf16 v[12:15], v[116:119], v[214:217], v[12:15]
	v_mfma_f32_16x16x32_bf16 v[8:11], v[124:127], v[214:217], v[8:11]
	s_setprio 0
	s_setprio 1
	v_mfma_f32_16x16x32_bf16 v[52:55], v[164:167], v[186:189], v[52:55]
	v_mfma_f32_16x16x32_bf16 v[48:51], v[178:181], v[186:189], v[48:51]
	v_mfma_f32_16x16x32_bf16 v[36:39], v[164:167], v[194:197], v[36:39]
	v_mfma_f32_16x16x32_bf16 v[32:35], v[178:181], v[194:197], v[32:35]
	v_mfma_f32_16x16x32_bf16 v[20:23], v[164:167], v[202:205], v[20:23]
	v_mfma_f32_16x16x32_bf16 v[16:19], v[178:181], v[202:205], v[16:19]
	v_mfma_f32_16x16x32_bf16 v[4:7], v[164:167], v[210:213], v[4:7]
	v_mfma_f32_16x16x32_bf16 v[0:3], v[178:181], v[210:213], v[0:3]
	v_mfma_f32_16x16x32_bf16 v[52:55], v[168:171], v[190:193], v[52:55]
	v_mfma_f32_16x16x32_bf16 v[48:51], v[182:185], v[190:193], v[48:51]
	v_mfma_f32_16x16x32_bf16 v[36:39], v[168:171], v[198:201], v[36:39]
	v_mfma_f32_16x16x32_bf16 v[32:35], v[182:185], v[198:201], v[32:35]
	v_mfma_f32_16x16x32_bf16 v[20:23], v[168:171], v[206:209], v[20:23]
	v_mfma_f32_16x16x32_bf16 v[16:19], v[182:185], v[206:209], v[16:19]
	s_setprio 2
	s_barrier
	v_mfma_f32_16x16x32_bf16 v[4:7], v[168:171], v[214:217], v[4:7]
	v_mfma_f32_16x16x32_bf16 v[0:3], v[182:185], v[214:217], v[0:3]
	s_setprio 0
	s_add_i32 s88, s88, 2
	s_add_u32 s68, s68, 0x100
	s_addc_u32 s69, s69, 0
	s_add_u32 s86, s86, 0x100
	s_addc_u32 s87, s87, 0
	s_cmp_gt_u32 s88, 29
	s_cbranch_scc0 .LBB0_545
	s_and_b64 vcc, exec, s[14:15]
	s_cbranch_vccz .LBB0_548
	s_barrier

; #define PG8_STAGE(bufoff, gbase, voff) do { _Pragma("unroll") for (int _i = 0; _i < 2; ++_i) \
;         __builtin_amdgcn_global_load_lds((const unsigned*)((const char*)(gbase) + (voff)[_i]), (PG8_LAS unsigned*)(lds + (bufoff) + ldsw + _i * 8192), 16, 0, 0); } while (0)
; #define PG8_LDA(dst, b, h) do { _Pragma("unroll") for (int m = 0; m < 4; ++m) _Pragma("unroll") for (int k = 0; k < 2; ++k) dst[m][k] = *(const PG8_LAS bf16x8*)(lds + PG8_SA(b, h) + aoff + m * 2048 + k * 1024); } while (0)
; #define PG8_LDB(dst, b, h) do { _Pragma("unroll") for (int n = 0; n < 2; ++n) _Pragma("unroll") for (int k = 0; k < 2; ++k) dst[n][k] = *(const PG8_LAS bf16x8*)(lds + PG8_SB(b, h) + boff + n * 2048 + k * 1024); } while (0)
; #define PG8_MMA(ai, bj, At, Bt) do { __builtin_amdgcn_s_setprio(1); _Pragma("unroll") for (int m = 0; m < 4; ++m) _Pragma("unroll") for (int n = 0; n < 2; ++n) _Pragma("unroll") for (int k = 0; k < 2; ++k) \
;         acc[ai][bj][m][n] = __builtin_amdgcn_mfma_f32_16x16x32_bf16(Bt[n][k], At[m][k], acc[ai][bj][m][n], 0, 0, 0); __builtin_amdgcn_s_setprio(0); } while (0)
; #define PG8_WAIT_V(n) asm volatile("s_waitcnt vmcnt(" #n ")" ::: "memory")
; #define PG8_WAIT_L(n) asm volatile("s_waitcnt lgkmcnt(" #n ")" ::: "memory")
; #define PG8_BAR __builtin_amdgcn_s_barrier()
; template <class Epi, class Sched, bool ALIGN_EPI = false, bool SP2 = false>
; __device__ __forceinline__ void gemm_phase(PG8_LAS unsigned char* lds, const Gemm g, const Sched& S, const Epi& E) {
;     ...
;             const bool last = (t == nt - 2);
;             const char* a1 = cA + (size_t)(t + 1) * kstep;
;             const char* a2 = last ? nA : cA + (size_t)(t + 2) * kstep; const char* b2 = last ? nB : cB + (size_t)(t + 2) * kstep;
;             const char* a3 = a2 + kstep; const char* b3 = b2 + kstep;
;             if constexpr (SP2) {
;             PG8_LDB(B0, 0, 0); PG8_LDB(B1, 0, 1); PG8_SCHED; PG8_LDA(At, 0, 0); PG8_STAGE(PG8_SA(1, 1), a1 + hstep, voffA);
;             PG8_WAIT_V(8); PG8_WAIT_L(0); PG8_BAR; PG8_MMA(0, 0, At, B0); PG8_MMA(0, 1, At, B1); PG8_BAR; PG8_SCHED;
;             PG8_LDA(At, 0, 1); PG8_STAGE(PG8_SB(0, 0), b2, voffB); PG8_STAGE(PG8_SB(0, 1), b2 + hstep, voffB); PG8_STAGE(PG8_SA(0, 0), a2, voffA);
;             PG8_WAIT_V(8); PG8_WAIT_L(0); PG8_BAR; PG8_MMA(1, 0, At, B0); PG8_MMA(1, 1, At, B1); PG8_BAR; PG8_SCHED;
.LBB0_624:
	ds_read_b128 v[128:131], v214
	ds_read_b128 v[132:135], v214 offset:1024
	ds_read_b128 v[158:161], v214 offset:2048
	ds_read_b128 v[162:165], v214 offset:3072
	ds_read_b128 v[166:169], v215
	ds_read_b128 v[170:173], v215 offset:1024
	ds_read_b128 v[174:177], v215 offset:2048
	ds_read_b128 v[178:181], v215 offset:3072
	s_add_u32 s52, s74, 0xffe00080
	s_addc_u32 s53, s75, -1
	s_cmpk_eq_i32 vcc_hi, 0x7c
	s_cselect_b32 s79, s51, s53
	s_cselect_b32 s78, s71, s52
	s_cselect_b32 s77, s49, vcc_lo
	s_cselect_b32 s76, s73, s93
	s_add_i32 m0, s83, 0xc000
	ds_read_b128 v[182:185], v216
	ds_read_b128 v[186:189], v216 offset:1024
	ds_read_b128 v[190:193], v216 offset:2048
	ds_read_b128 v[194:197], v216 offset:3072
	ds_read_b128 v[198:201], v216 offset:4096
	ds_read_b128 v[202:205], v216 offset:5120
	ds_read_b128 v[218:221], v216 offset:6144
	ds_read_b128 v[222:225], v216 offset:7168
	global_load_lds_dwordx4 v150, s[74:75]
	s_add_i32 m0, s83, 0xe000
	s_nop 0
	global_load_lds_dwordx4 v152, s[74:75]
	s_waitcnt vmcnt(8)
	s_waitcnt lgkmcnt(0)
	s_setprio 1
	s_barrier
	v_mfma_f32_16x16x32_bf16 v[124:127], v[128:131], v[182:185], v[124:127]
	v_mfma_f32_16x16x32_bf16 v[120:123], v[158:161], v[182:185], v[120:123]
	v_mfma_f32_16x16x32_bf16 v[116:119], v[128:131], v[190:193], v[116:119]
	v_mfma_f32_16x16x32_bf16 v[112:115], v[158:161], v[190:193], v[112:115]
	v_mfma_f32_16x16x32_bf16 v[108:111], v[128:131], v[198:201], v[108:111]
	v_mfma_f32_16x16x32_bf16 v[104:107], v[158:161], v[198:201], v[104:107]
	v_mfma_f32_16x16x32_bf16 v[100:103], v[128:131], v[218:221], v[100:103]
	v_mfma_f32_16x16x32_bf16 v[96:99], v[158:161], v[218:221], v[96:99]
	v_mfma_f32_16x16x32_bf16 v[124:127], v[132:135], v[186:189], v[124:127]
	v_mfma_f32_16x16x32_bf16 v[120:123], v[162:165], v[186:189], v[120:123]
	v_mfma_f32_16x16x32_bf16 v[116:119], v[132:135], v[194:197], v[116:119]
	v_mfma_f32_16x16x32_bf16 v[112:115], v[162:165], v[194:197], v[112:115]
	v_mfma_f32_16x16x32_bf16 v[108:111], v[132:135], v[202:205], v[108:111]
	v_mfma_f32_16x16x32_bf16 v[104:107], v[162:165], v[202:205], v[104:107]
	v_mfma_f32_16x16x32_bf16 v[100:103], v[132:135], v[222:225], v[100:103]
	v_mfma_f32_16x16x32_bf16 v[96:99], v[162:165], v[222:225], v[96:99]
	s_setprio 0
	s_setprio 1
	v_mfma_f32_16x16x32_bf16 v[60:63], v[166:169], v[182:185], v[60:63]
	v_mfma_f32_16x16x32_bf16 v[56:59], v[174:177], v[182:185], v[56:59]
	v_mfma_f32_16x16x32_bf16 v[52:55], v[166:169], v[190:193], v[52:55]
	v_mfma_f32_16x16x32_bf16 v[48:51], v[174:177], v[190:193], v[48:51]
	v_mfma_f32_16x16x32_bf16 v[44:47], v[166:169], v[198:201], v[44:47]
	v_mfma_f32_16x16x32_bf16 v[40:43], v[174:177], v[198:201], v[40:43]
	v_mfma_f32_16x16x32_bf16 v[36:39], v[166:169], v[218:221], v[36:39]
	v_mfma_f32_16x16x32_bf16 v[32:35], v[174:177], v[218:221], v[32:35]
	v_mfma_f32_16x16x32_bf16 v[60:63], v[170:173], v[186:189], v[60:63]
	v_mfma_f32_16x16x32_bf16 v[56:59], v[178:181], v[186:189], v[56:59]
	v_mfma_f32_16x16x32_bf16 v[52:55], v[170:173], v[194:197], v[52:55]
	v_mfma_f32_16x16x32_bf16 v[48:51], v[178:181], v[194:197], v[48:51]
	v_mfma_f32_16x16x32_bf16 v[44:47], v[170:173], v[202:205], v[44:47]
	v_mfma_f32_16x16x32_bf16 v[40:43], v[178:181], v[202:205], v[40:43]
	s_setprio 2
	s_barrier
	v_mfma_f32_16x16x32_bf16 v[36:39], v[170:173], v[222:225], v[36:39]
	v_mfma_f32_16x16x32_bf16 v[32:35], v[178:181], v[222:225], v[32:35]
	s_setprio 0
	s_add_i32 s52, s33, s82
	v_lshl_add_u64 v[226:227], s[76:77], 0, v[138:139]
	s_mov_b32 m0, s52
	ds_read_b128 v[182:185], v216 offset:16384
	ds_read_b128 v[186:189], v216 offset:17408
	ds_read_b128 v[190:193], v216 offset:18432
	ds_read_b128 v[194:197], v216 offset:19456
	ds_read_b128 v[198:201], v216 offset:20480
	ds_read_b128 v[202:205], v216 offset:21504
	ds_read_b128 v[218:221], v216 offset:22528
	ds_read_b128 v[222:225], v216 offset:23552
	global_load_lds_dwordx4 v[226:227], off
	s_add_i32 m0, s52, 0x2000
	s_add_u32 s52, s76, 0x200000
	v_lshl_add_u64 v[228:229], s[76:77], 0, v[142:143]
	s_addc_u32 s53, s77, 0
	s_add_i32 s56, s92, s82
	global_load_lds_dwordx4 v[228:229], off
	s_mov_b32 m0, s56
	v_lshl_add_u64 v[232:233], s[78:79], 0, v[140:141]
	global_load_lds_dwordx4 v138, s[52:53]
	s_add_i32 m0, s56, 0x2000
	s_nop 0
	global_load_lds_dwordx4 v142, s[52:53]
	v_lshl_add_u64 v[230:231], s[78:79], 0, v[136:137]
	s_mov_b32 m0, s83
	s_nop 0
	global_load_lds_dwordx4 v[230:231], off
	s_mov_b32 m0, s84
	s_nop 0
	global_load_lds_dwordx4 v[232:233], off
	s_waitcnt vmcnt(8)
	s_waitcnt lgkmcnt(0)
	s_setprio 1
	s_barrier
	v_mfma_f32_16x16x32_bf16 v[92:95], v[128:131], v[182:185], v[92:95]
	v_mfma_f32_16x16x32_bf16 v[88:91], v[158:161], v[182:185], v[88:91]
	v_mfma_f32_16x16x32_bf16 v[84:87], v[128:131], v[190:193], v[84:87]
	v_mfma_f32_16x16x32_bf16 v[80:83], v[158:161], v[190:193], v[80:83]
	v_mfma_f32_16x16x32_bf16 v[76:79], v[128:131], v[198:201], v[76:79]
	v_mfma_f32_16x16x32_bf16 v[72:75], v[158:161], v[198:201], v[72:75]
	v_mfma_f32_16x16x32_bf16 v[68:71], v[128:131], v[218:221], v[68:71]
	v_mfma_f32_16x16x32_bf16 v[64:67], v[158:161], v[218:221], v[64:67]
	v_mfma_f32_16x16x32_bf16 v[92:95], v[132:135], v[186:189], v[92:95]
	v_mfma_f32_16x16x32_bf16 v[88:91], v[162:165], v[186:189], v[88:91]
	v_mfma_f32_16x16x32_bf16 v[84:87], v[132:135], v[194:197], v[84:87]
	v_mfma_f32_16x16x32_bf16 v[80:83], v[162:165], v[194:197], v[80:83]
	v_mfma_f32_16x16x32_bf16 v[76:79], v[132:135], v[202:205], v[76:79]
	v_mfma_f32_16x16x32_bf16 v[72:75], v[162:165], v[202:205], v[72:75]
	v_mfma_f32_16x16x32_bf16 v[68:71], v[132:135], v[222:225], v[68:71]
	v_mfma_f32_16x16x32_bf16 v[64:67], v[162:165], v[222:225], v[64:67]
	s_setprio 0
	s_setprio 1
	v_mfma_f32_16x16x32_bf16 v[28:31], v[166:169], v[182:185], v[28:31]
	v_mfma_f32_16x16x32_bf16 v[24:27], v[174:177], v[182:185], v[24:27]
	v_mfma_f32_16x16x32_bf16 v[20:23], v[166:169], v[190:193], v[20:23]
	v_mfma_f32_16x16x32_bf16 v[16:19], v[174:177], v[190:193], v[16:19]
	v_mfma_f32_16x16x32_bf16 v[12:15], v[166:169], v[198:201], v[12:15]
	v_mfma_f32_16x16x32_bf16 v[8:11], v[174:177], v[198:201], v[8:11]
	v_mfma_f32_16x16x32_bf16 v[4:7], v[166:169], v[218:221], v[4:7]
	v_mfma_f32_16x16x32_bf16 v[0:3], v[174:177], v[218:221], v[0:3]
	v_mfma_f32_16x16x32_bf16 v[28:31], v[170:173], v[186:189], v[28:31]
	v_mfma_f32_16x16x32_bf16 v[24:27], v[178:181], v[186:189], v[24:27]
	v_mfma_f32_16x16x32_bf16 v[20:23], v[170:173], v[194:197], v[20:23]
	v_mfma_f32_16x16x32_bf16 v[16:19], v[178:181], v[194:197], v[16:19]
	v_mfma_f32_16x16x32_bf16 v[12:15], v[170:173], v[202:205], v[12:15]
	v_mfma_f32_16x16x32_bf16 v[8:11], v[178:181], v[202:205], v[8:11]
	s_setprio 2
	s_barrier
; #define PG8_STAGE(bufoff, gbase, voff) do { _Pragma("unroll") for (int _i = 0; _i < 2; ++_i) \
;         __builtin_amdgcn_global_load_lds((const unsigned*)((const char*)(gbase) + (voff)[_i]), (PG8_LAS unsigned*)(lds + (bufoff) + ldsw + _i * 8192), 16, 0, 0); } while (0)
; #define PG8_LDA(dst, b, h) do { _Pragma("unroll") for (int m = 0; m < 4; ++m) _Pragma("unroll") for (int k = 0; k < 2; ++k) dst[m][k] = *(const PG8_LAS bf16x8*)(lds + PG8_SA(b, h) + aoff + m * 2048 + k * 1024); } while (0)
; #define PG8_LDB(dst, b, h) do { _Pragma("unroll") for (int n = 0; n < 2; ++n) _Pragma("unroll") for (int k = 0; k < 2; ++k) dst[n][k] = *(const PG8_LAS bf16x8*)(lds + PG8_SB(b, h) + boff + n * 2048 + k * 1024); } while (0)
; #define PG8_MMA(ai, bj, At, Bt) do { __builtin_amdgcn_s_setprio(1); _Pragma("unroll") for (int m = 0; m < 4; ++m) _Pragma("unroll") for (int n = 0; n < 2; ++n) _Pragma("unroll") for (int k = 0; k < 2; ++k) \
;         acc[ai][bj][m][n] = __builtin_amdgcn_mfma_f32_16x16x32_bf16(Bt[n][k], At[m][k], acc[ai][bj][m][n], 0, 0, 0); __builtin_amdgcn_s_setprio(0); } while (0)
; #define PG8_WAIT_V(n) asm volatile("s_waitcnt vmcnt(" #n ")" ::: "memory")
; #define PG8_WAIT_L(n) asm volatile("s_waitcnt lgkmcnt(" #n ")" ::: "memory")
; #define PG8_BAR __builtin_amdgcn_s_barrier()
; #define PG8_SCHED __builtin_amdgcn_sched_barrier(0)
; template <class Epi, class Sched, bool ALIGN_EPI = false, bool SP2 = false>
; __device__ __forceinline__ void gemm_phase(PG8_LAS unsigned char* lds, const Gemm g, const Sched& S, const Epi& E) {
;     ...
;             PG8_LDB(B0, 1, 0); PG8_LDB(B1, 1, 1); PG8_SCHED; PG8_LDA(At, 1, 0); PG8_STAGE(PG8_SA(0, 1), a2 + hstep, voffA);
;             PG8_WAIT_V(8); PG8_WAIT_L(0); PG8_BAR; PG8_MMA(0, 0, At, B0); PG8_MMA(0, 1, At, B1); PG8_BAR; PG8_SCHED;
	v_mfma_f32_16x16x32_bf16 v[4:7], v[170:173], v[222:225], v[4:7]
	v_mfma_f32_16x16x32_bf16 v[0:3], v[178:181], v[222:225], v[0:3]
	s_setprio 0
	s_add_i32 s56, 0, 0x18000
	s_add_i32 s57, 0, 0x1c000
	v_add_u32_e32 v162, s56, v212
	v_add_u32_e32 v178, s57, v212
	ds_read_b128 v[128:131], v162
	ds_read_b128 v[132:135], v162 offset:1024
	ds_read_b128 v[158:161], v162 offset:2048
	ds_read_b128 v[162:165], v162 offset:3072
	ds_read_b128 v[166:169], v178
	ds_read_b128 v[170:173], v178 offset:1024
	ds_read_b128 v[174:177], v178 offset:2048
	ds_read_b128 v[178:181], v178 offset:3072
	s_add_u32 s52, s78, 0x200000
	s_addc_u32 s53, s79, 0
	s_mov_b32 m0, s85
	ds_read_b128 v[182:185], v216 offset:32768
	ds_read_b128 v[186:189], v216 offset:33792
	ds_read_b128 v[190:193], v216 offset:34816
	ds_read_b128 v[194:197], v216 offset:35840
	ds_read_b128 v[198:201], v216 offset:36864
	ds_read_b128 v[202:205], v216 offset:37888
	ds_read_b128 v[218:221], v216 offset:38912
	ds_read_b128 v[222:225], v216 offset:39936
	global_load_lds_dwordx4 v136, s[52:53]
	s_mov_b32 m0, s86
	s_nop 0
	global_load_lds_dwordx4 v140, s[52:53]
	s_waitcnt vmcnt(8)
	s_waitcnt lgkmcnt(0)
	s_setprio 1
	s_barrier
	v_mfma_f32_16x16x32_bf16 v[124:127], v[128:131], v[182:185], v[124:127]
	v_mfma_f32_16x16x32_bf16 v[120:123], v[158:161], v[182:185], v[120:123]
	v_mfma_f32_16x16x32_bf16 v[116:119], v[128:131], v[190:193], v[116:119]
	v_mfma_f32_16x16x32_bf16 v[112:115], v[158:161], v[190:193], v[112:115]
	v_mfma_f32_16x16x32_bf16 v[108:111], v[128:131], v[198:201], v[108:111]
	v_mfma_f32_16x16x32_bf16 v[104:107], v[158:161], v[198:201], v[104:107]
	v_mfma_f32_16x16x32_bf16 v[100:103], v[128:131], v[218:221], v[100:103]
	v_mfma_f32_16x16x32_bf16 v[96:99], v[158:161], v[218:221], v[96:99]
	v_mfma_f32_16x16x32_bf16 v[124:127], v[132:135], v[186:189], v[124:127]
	v_mfma_f32_16x16x32_bf16 v[120:123], v[162:165], v[186:189], v[120:123]
	v_mfma_f32_16x16x32_bf16 v[116:119], v[132:135], v[194:197], v[116:119]
	v_mfma_f32_16x16x32_bf16 v[112:115], v[162:165], v[194:197], v[112:115]
	v_mfma_f32_16x16x32_bf16 v[108:111], v[132:135], v[202:205], v[108:111]
	v_mfma_f32_16x16x32_bf16 v[104:107], v[162:165], v[202:205], v[104:107]
	v_mfma_f32_16x16x32_bf16 v[100:103], v[132:135], v[222:225], v[100:103]
	v_mfma_f32_16x16x32_bf16 v[96:99], v[162:165], v[222:225], v[96:99]
	s_setprio 0
	s_setprio 1
	v_mfma_f32_16x16x32_bf16 v[60:63], v[166:169], v[182:185], v[60:63]
	v_mfma_f32_16x16x32_bf16 v[56:59], v[174:177], v[182:185], v[56:59]
	v_mfma_f32_16x16x32_bf16 v[52:55], v[166:169], v[190:193], v[52:55]
	v_mfma_f32_16x16x32_bf16 v[48:51], v[174:177], v[190:193], v[48:51]
	v_mfma_f32_16x16x32_bf16 v[44:47], v[166:169], v[198:201], v[44:47]
	v_mfma_f32_16x16x32_bf16 v[40:43], v[174:177], v[198:201], v[40:43]
	v_mfma_f32_16x16x32_bf16 v[36:39], v[166:169], v[218:221], v[36:39]
	v_mfma_f32_16x16x32_bf16 v[32:35], v[174:177], v[218:221], v[32:35]
	v_mfma_f32_16x16x32_bf16 v[60:63], v[170:173], v[186:189], v[60:63]
	v_mfma_f32_16x16x32_bf16 v[56:59], v[178:181], v[186:189], v[56:59]
	v_mfma_f32_16x16x32_bf16 v[52:55], v[170:173], v[194:197], v[52:55]
	v_mfma_f32_16x16x32_bf16 v[48:51], v[178:181], v[194:197], v[48:51]
	v_mfma_f32_16x16x32_bf16 v[44:47], v[170:173], v[202:205], v[44:47]
	v_mfma_f32_16x16x32_bf16 v[40:43], v[178:181], v[202:205], v[40:43]
	s_setprio 2
	s_barrier
; #define PG8_STAGE(bufoff, gbase, voff) do { _Pragma("unroll") for (int _i = 0; _i < 2; ++_i) \
;         __builtin_amdgcn_global_load_lds((const unsigned*)((const char*)(gbase) + (voff)[_i]), (PG8_LAS unsigned*)(lds + (bufoff) + ldsw + _i * 8192), 16, 0, 0); } while (0)
; #define PG8_LDA(dst, b, h) do { _Pragma("unroll") for (int m = 0; m < 4; ++m) _Pragma("unroll") for (int k = 0; k < 2; ++k) dst[m][k] = *(const PG8_LAS bf16x8*)(lds + PG8_SA(b, h) + aoff + m * 2048 + k * 1024); } while (0)
; #define PG8_MMA(ai, bj, At, Bt) do { __builtin_amdgcn_s_setprio(1); _Pragma("unroll") for (int m = 0; m < 4; ++m) _Pragma("unroll") for (int n = 0; n < 2; ++n) _Pragma("unroll") for (int k = 0; k < 2; ++k) \
;         acc[ai][bj][m][n] = __builtin_amdgcn_mfma_f32_16x16x32_bf16(Bt[n][k], At[m][k], acc[ai][bj][m][n], 0, 0, 0); __builtin_amdgcn_s_setprio(0); } while (0)
; #define PG8_WAIT_V(n) asm volatile("s_waitcnt vmcnt(" #n ")" ::: "memory")
; #define PG8_WAIT_L(n) asm volatile("s_waitcnt lgkmcnt(" #n ")" ::: "memory")
; #define PG8_BAR __builtin_amdgcn_s_barrier()
; #define PG8_SCHED __builtin_amdgcn_sched_barrier(0)
; template <class Epi, class Sched, bool ALIGN_EPI = false, bool SP2 = false>
; __device__ __forceinline__ void gemm_phase(PG8_LAS unsigned char* lds, const Gemm g, const Sched& S, const Epi& E) {
;     ...
;             PG8_LDA(At, 1, 1); PG8_STAGE(PG8_SB(1, 0), b3, voffB); PG8_STAGE(PG8_SB(1, 1), b3 + hstep, voffB); PG8_STAGE(PG8_SA(1, 0), a3, voffA);
;             PG8_WAIT_V(8); PG8_WAIT_L(0); PG8_BAR; PG8_MMA(1, 0, At, B0); PG8_MMA(1, 1, At, B1); PG8_BAR; PG8_SCHED;
;     ...
;         if constexpr (ALIGN_EPI) { if (wr == 0) PG8_BAR; }
	v_mfma_f32_16x16x32_bf16 v[36:39], v[170:173], v[222:225], v[36:39]
	v_mfma_f32_16x16x32_bf16 v[32:35], v[178:181], v[222:225], v[32:35]
	s_setprio 0
	s_add_i32 s52, s56, s82
	v_lshl_add_u64 v[226:227], v[226:227], 0, s[36:37]
	s_mov_b32 m0, s52
	ds_read_b128 v[182:185], v216 offset:49152
	ds_read_b128 v[186:189], v216 offset:50176
	ds_read_b128 v[190:193], v216 offset:51200
	ds_read_b128 v[194:197], v216 offset:52224
	ds_read_b128 v[198:201], v216 offset:53248
	ds_read_b128 v[202:205], v216 offset:54272
	ds_read_b128 v[218:221], v216 offset:55296
	ds_read_b128 v[222:225], v216 offset:56320
	global_load_lds_dwordx4 v[226:227], off
	s_add_i32 m0, s52, 0x2000
	s_add_u32 s52, s76, 0x200080
	v_lshl_add_u64 v[226:227], v[228:229], 0, s[36:37]
	s_addc_u32 s53, s77, 0
	s_add_i32 s56, s57, s82
	global_load_lds_dwordx4 v[226:227], off
	s_mov_b32 m0, s56
	s_nop 0
	global_load_lds_dwordx4 v138, s[52:53]
	s_add_i32 m0, s56, 0x2000
	s_nop 0
	global_load_lds_dwordx4 v142, s[52:53]
	v_lshl_add_u64 v[226:227], v[230:231], 0, s[36:37]
	s_mov_b32 m0, s94
	s_nop 0
	global_load_lds_dwordx4 v[226:227], off
	v_lshl_add_u64 v[226:227], v[232:233], 0, s[36:37]
	s_mov_b32 m0, s95
	s_nop 0
	global_load_lds_dwordx4 v[226:227], off
	s_waitcnt vmcnt(8)
	s_waitcnt lgkmcnt(0)
	s_setprio 1
	s_barrier
	v_mfma_f32_16x16x32_bf16 v[92:95], v[128:131], v[182:185], v[92:95]
	v_mfma_f32_16x16x32_bf16 v[88:91], v[158:161], v[182:185], v[88:91]
	v_mfma_f32_16x16x32_bf16 v[84:87], v[128:131], v[190:193], v[84:87]
	v_mfma_f32_16x16x32_bf16 v[80:83], v[158:161], v[190:193], v[80:83]
	v_mfma_f32_16x16x32_bf16 v[76:79], v[128:131], v[198:201], v[76:79]
	v_mfma_f32_16x16x32_bf16 v[72:75], v[158:161], v[198:201], v[72:75]
	v_mfma_f32_16x16x32_bf16 v[68:71], v[128:131], v[218:221], v[68:71]
	v_mfma_f32_16x16x32_bf16 v[64:67], v[158:161], v[218:221], v[64:67]
	v_mfma_f32_16x16x32_bf16 v[92:95], v[132:135], v[186:189], v[92:95]
	v_mfma_f32_16x16x32_bf16 v[88:91], v[162:165], v[186:189], v[88:91]
	v_mfma_f32_16x16x32_bf16 v[84:87], v[132:135], v[194:197], v[84:87]
	v_mfma_f32_16x16x32_bf16 v[80:83], v[162:165], v[194:197], v[80:83]
	v_mfma_f32_16x16x32_bf16 v[76:79], v[132:135], v[202:205], v[76:79]
	v_mfma_f32_16x16x32_bf16 v[72:75], v[162:165], v[202:205], v[72:75]
	v_mfma_f32_16x16x32_bf16 v[68:71], v[132:135], v[222:225], v[68:71]
	v_mfma_f32_16x16x32_bf16 v[64:67], v[162:165], v[222:225], v[64:67]
	s_setprio 0
	s_setprio 1
	v_mfma_f32_16x16x32_bf16 v[28:31], v[166:169], v[182:185], v[28:31]
	v_mfma_f32_16x16x32_bf16 v[24:27], v[174:177], v[182:185], v[24:27]
	v_mfma_f32_16x16x32_bf16 v[20:23], v[166:169], v[190:193], v[20:23]
	v_mfma_f32_16x16x32_bf16 v[16:19], v[174:177], v[190:193], v[16:19]
	v_mfma_f32_16x16x32_bf16 v[12:15], v[166:169], v[198:201], v[12:15]
	v_mfma_f32_16x16x32_bf16 v[8:11], v[174:177], v[198:201], v[8:11]
	v_mfma_f32_16x16x32_bf16 v[4:7], v[166:169], v[218:221], v[4:7]
	v_mfma_f32_16x16x32_bf16 v[0:3], v[174:177], v[218:221], v[0:3]
	v_mfma_f32_16x16x32_bf16 v[28:31], v[170:173], v[186:189], v[28:31]
	v_mfma_f32_16x16x32_bf16 v[24:27], v[178:181], v[186:189], v[24:27]
	v_mfma_f32_16x16x32_bf16 v[20:23], v[170:173], v[194:197], v[20:23]
	v_mfma_f32_16x16x32_bf16 v[16:19], v[178:181], v[194:197], v[16:19]
	v_mfma_f32_16x16x32_bf16 v[12:15], v[170:173], v[202:205], v[12:15]
	v_mfma_f32_16x16x32_bf16 v[8:11], v[178:181], v[202:205], v[8:11]
	s_setprio 2
	s_barrier
	v_mfma_f32_16x16x32_bf16 v[4:7], v[170:173], v[222:225], v[4:7]
	v_mfma_f32_16x16x32_bf16 v[0:3], v[178:181], v[222:225], v[0:3]
	s_setprio 0
	s_add_i32 vcc_hi, vcc_hi, 2
	s_add_u32 s74, s74, 0x100
	s_addc_u32 s75, s75, 0
	s_add_u32 s93, s93, 0x100
	s_addc_u32 vcc_lo, vcc_lo, 0
	s_cmpk_gt_u32 vcc_hi, 0x7d
	s_cbranch_scc0 .LBB0_624
	s_and_b64 vcc, exec, s[40:41]
	s_cbranch_vccz .LBB0_627
	s_barrier

; #define PG8_STAGE(bufoff, gbase, voff) do { _Pragma("unroll") for (int _i = 0; _i < 2; ++_i) \
;         __builtin_amdgcn_global_load_lds((const unsigned*)((const char*)(gbase) + (voff)[_i]), (PG8_LAS unsigned*)(lds + (bufoff) + ldsw + _i * 8192), 16, 0, 0); } while (0)
; #define PG8_LDA(dst, b, h) do { _Pragma("unroll") for (int m = 0; m < 4; ++m) _Pragma("unroll") for (int k = 0; k < 2; ++k) dst[m][k] = *(const PG8_LAS bf16x8*)(lds + PG8_SA(b, h) + aoff + m * 2048 + k * 1024); } while (0)
; #define PG8_LDB(dst, b, h) do { _Pragma("unroll") for (int n = 0; n < 2; ++n) _Pragma("unroll") for (int k = 0; k < 2; ++k) dst[n][k] = *(const PG8_LAS bf16x8*)(lds + PG8_SB(b, h) + boff + n * 2048 + k * 1024); } while (0)
; #define PG8_MMA(ai, bj, At, Bt) do { __builtin_amdgcn_s_setprio(1); _Pragma("unroll") for (int m = 0; m < 4; ++m) _Pragma("unroll") for (int n = 0; n < 2; ++n) _Pragma("unroll") for (int k = 0; k < 2; ++k) \
;         acc[ai][bj][m][n] = __builtin_amdgcn_mfma_f32_16x16x32_bf16(Bt[n][k], At[m][k], acc[ai][bj][m][n], 0, 0, 0); __builtin_amdgcn_s_setprio(0); } while (0)
; #define PG8_WAIT_V(n) asm volatile("s_waitcnt vmcnt(" #n ")" ::: "memory")
; #define PG8_WAIT_L(n) asm volatile("s_waitcnt lgkmcnt(" #n ")" ::: "memory")
; #define PG8_BAR __builtin_amdgcn_s_barrier()
; template <class Epi, class Sched, bool ALIGN_EPI = false, bool SP2 = false>
; __device__ __forceinline__ void gemm_phase(PG8_LAS unsigned char* lds, const Gemm g, const Sched& S, const Epi& E) {
;     ...
;             const bool last = (t == nt - 2);
;             const char* a1 = cA + (size_t)(t + 1) * kstep;
;             const char* a2 = last ? nA : cA + (size_t)(t + 2) * kstep; const char* b2 = last ? nB : cB + (size_t)(t + 2) * kstep;
;             const char* a3 = a2 + kstep; const char* b3 = b2 + kstep;
;             if constexpr (SP2) {
;             PG8_LDB(B0, 0, 0); PG8_LDB(B1, 0, 1); PG8_SCHED; PG8_LDA(At, 0, 0); PG8_STAGE(PG8_SA(1, 1), a1 + hstep, voffA);
;             PG8_WAIT_V(8); PG8_WAIT_L(0); PG8_BAR; PG8_MMA(0, 0, At, B0); PG8_MMA(0, 1, At, B1); PG8_BAR; PG8_SCHED;
;             PG8_LDA(At, 0, 1); PG8_STAGE(PG8_SB(0, 0), b2, voffB); PG8_STAGE(PG8_SB(0, 1), b2 + hstep, voffB); PG8_STAGE(PG8_SA(0, 0), a2, voffA);
;             PG8_WAIT_V(8); PG8_WAIT_L(0); PG8_BAR; PG8_MMA(1, 0, At, B0); PG8_MMA(1, 1, At, B1); PG8_BAR; PG8_SCHED;
.LBB0_660:
	ds_read_b128 v[166:169], v145
	ds_read_b128 v[170:173], v145 offset:1024
	ds_read_b128 v[174:177], v145 offset:2048
	ds_read_b128 v[178:181], v145 offset:3072
	ds_read_b128 v[182:185], v149
	ds_read_b128 v[186:189], v149 offset:1024
	ds_read_b128 v[190:193], v149 offset:2048
	ds_read_b128 v[194:197], v149 offset:3072
	s_add_u32 s52, s72, 0xffe00080
	s_addc_u32 s53, s73, -1
	s_cmp_eq_u32 s49, 28
	s_cselect_b32 s77, s51, s53
	s_cselect_b32 s76, s50, s52
	s_cselect_b32 s75, s55, s41
	s_cselect_b32 s74, s54, s37
	s_mov_b32 m0, s82
	ds_read_b128 v[198:201], v164
	ds_read_b128 v[202:205], v164 offset:1024
	ds_read_b128 v[206:209], v164 offset:2048
	ds_read_b128 v[210:213], v164 offset:3072
	ds_read_b128 v[214:217], v164 offset:4096
	ds_read_b128 v[218:221], v164 offset:5120
	ds_read_b128 v[222:225], v164 offset:6144
	ds_read_b128 v[226:229], v164 offset:7168
	global_load_lds_dwordx4 v160, s[72:73]
	s_mov_b32 m0, s83
	s_nop 0
	global_load_lds_dwordx4 v162, s[72:73]
	s_waitcnt vmcnt(8)
	s_waitcnt lgkmcnt(0)
	s_setprio 1
	s_barrier
	v_mfma_f32_16x16x32_bf16 v[124:127], v[166:169], v[198:201], v[124:127]
	v_mfma_f32_16x16x32_bf16 v[120:123], v[174:177], v[198:201], v[120:123]
	v_mfma_f32_16x16x32_bf16 v[116:119], v[166:169], v[206:209], v[116:119]
	v_mfma_f32_16x16x32_bf16 v[108:111], v[174:177], v[206:209], v[108:111]
	v_mfma_f32_16x16x32_bf16 v[100:103], v[166:169], v[214:217], v[100:103]
	v_mfma_f32_16x16x32_bf16 v[92:95], v[174:177], v[214:217], v[92:95]
	v_mfma_f32_16x16x32_bf16 v[84:87], v[166:169], v[222:225], v[84:87]
	v_mfma_f32_16x16x32_bf16 v[76:79], v[174:177], v[222:225], v[76:79]
	v_mfma_f32_16x16x32_bf16 v[124:127], v[170:173], v[202:205], v[124:127]
	v_mfma_f32_16x16x32_bf16 v[120:123], v[178:181], v[202:205], v[120:123]
	v_mfma_f32_16x16x32_bf16 v[116:119], v[170:173], v[210:213], v[116:119]
	v_mfma_f32_16x16x32_bf16 v[108:111], v[178:181], v[210:213], v[108:111]
	v_mfma_f32_16x16x32_bf16 v[100:103], v[170:173], v[218:221], v[100:103]
	v_mfma_f32_16x16x32_bf16 v[92:95], v[178:181], v[218:221], v[92:95]
	v_mfma_f32_16x16x32_bf16 v[84:87], v[170:173], v[226:229], v[84:87]
	v_mfma_f32_16x16x32_bf16 v[76:79], v[178:181], v[226:229], v[76:79]
	s_setprio 0
	s_setprio 1
	v_mfma_f32_16x16x32_bf16 v[112:115], v[182:185], v[198:201], v[112:115]
	v_mfma_f32_16x16x32_bf16 v[104:107], v[190:193], v[198:201], v[104:107]
	v_mfma_f32_16x16x32_bf16 v[96:99], v[182:185], v[206:209], v[96:99]
	v_mfma_f32_16x16x32_bf16 v[88:91], v[190:193], v[206:209], v[88:91]
	v_mfma_f32_16x16x32_bf16 v[80:83], v[182:185], v[214:217], v[80:83]
	v_mfma_f32_16x16x32_bf16 v[72:75], v[190:193], v[214:217], v[72:75]
	v_mfma_f32_16x16x32_bf16 v[68:71], v[182:185], v[222:225], v[68:71]
	v_mfma_f32_16x16x32_bf16 v[64:67], v[190:193], v[222:225], v[64:67]
	v_mfma_f32_16x16x32_bf16 v[112:115], v[186:189], v[202:205], v[112:115]
	v_mfma_f32_16x16x32_bf16 v[104:107], v[194:197], v[202:205], v[104:107]
	v_mfma_f32_16x16x32_bf16 v[96:99], v[186:189], v[210:213], v[96:99]
	v_mfma_f32_16x16x32_bf16 v[88:91], v[194:197], v[210:213], v[88:91]
	v_mfma_f32_16x16x32_bf16 v[80:83], v[186:189], v[218:221], v[80:83]
	v_mfma_f32_16x16x32_bf16 v[72:75], v[194:197], v[218:221], v[72:75]
	s_setprio 2
	s_barrier
	v_mfma_f32_16x16x32_bf16 v[68:71], v[186:189], v[226:229], v[68:71]
	v_mfma_f32_16x16x32_bf16 v[64:67], v[194:197], v[226:229], v[64:67]
	s_setprio 0
	s_mov_b32 m0, s84
	v_lshl_add_u64 v[230:231], s[74:75], 0, v[138:139]
	s_add_u32 s52, s74, 0x200000
	ds_read_b128 v[198:201], v164 offset:16384
	ds_read_b128 v[202:205], v164 offset:17408
	ds_read_b128 v[206:209], v164 offset:18432
	ds_read_b128 v[210:213], v164 offset:19456
	ds_read_b128 v[214:217], v164 offset:20480
	ds_read_b128 v[218:221], v164 offset:21504
	ds_read_b128 v[222:225], v164 offset:22528
	ds_read_b128 v[226:229], v164 offset:23552
	global_load_lds_dwordx4 v[230:231], off
	v_lshl_add_u64 v[232:233], s[74:75], 0, v[142:143]
	s_mov_b32 m0, s85
	s_addc_u32 s53, s75, 0
	global_load_lds_dwordx4 v[232:233], off
	s_mov_b32 m0, s86
	v_lshl_add_u64 v[236:237], s[76:77], 0, v[140:141]
	global_load_lds_dwordx4 v138, s[52:53]
	s_mov_b32 m0, s87
	s_nop 0
	global_load_lds_dwordx4 v142, s[52:53]
	v_lshl_add_u64 v[234:235], s[76:77], 0, v[136:137]
	s_mov_b32 m0, s28
	s_nop 0
	global_load_lds_dwordx4 v[234:235], off
	s_mov_b32 m0, s29
	s_nop 0
	global_load_lds_dwordx4 v[236:237], off
	s_waitcnt vmcnt(8)
	s_waitcnt lgkmcnt(0)
	s_setprio 1
	s_barrier
	v_mfma_f32_16x16x32_bf16 v[60:63], v[166:169], v[198:201], v[60:63]
	v_mfma_f32_16x16x32_bf16 v[56:59], v[174:177], v[198:201], v[56:59]
	v_mfma_f32_16x16x32_bf16 v[52:55], v[166:169], v[206:209], v[52:55]
	v_mfma_f32_16x16x32_bf16 v[44:47], v[174:177], v[206:209], v[44:47]
	v_mfma_f32_16x16x32_bf16 v[36:39], v[166:169], v[214:217], v[36:39]
	v_mfma_f32_16x16x32_bf16 v[28:31], v[174:177], v[214:217], v[28:31]
	v_mfma_f32_16x16x32_bf16 v[20:23], v[166:169], v[222:225], v[20:23]
	v_mfma_f32_16x16x32_bf16 v[12:15], v[174:177], v[222:225], v[12:15]
	v_mfma_f32_16x16x32_bf16 v[60:63], v[170:173], v[202:205], v[60:63]
	v_mfma_f32_16x16x32_bf16 v[56:59], v[178:181], v[202:205], v[56:59]
	v_mfma_f32_16x16x32_bf16 v[52:55], v[170:173], v[210:213], v[52:55]
	v_mfma_f32_16x16x32_bf16 v[44:47], v[178:181], v[210:213], v[44:47]
	v_mfma_f32_16x16x32_bf16 v[36:39], v[170:173], v[218:221], v[36:39]
	v_mfma_f32_16x16x32_bf16 v[28:31], v[178:181], v[218:221], v[28:31]
	v_mfma_f32_16x16x32_bf16 v[20:23], v[170:173], v[226:229], v[20:23]
	v_mfma_f32_16x16x32_bf16 v[12:15], v[178:181], v[226:229], v[12:15]
	s_setprio 0
	s_setprio 1
	v_mfma_f32_16x16x32_bf16 v[48:51], v[182:185], v[198:201], v[48:51]
	v_mfma_f32_16x16x32_bf16 v[40:43], v[190:193], v[198:201], v[40:43]
	v_mfma_f32_16x16x32_bf16 v[32:35], v[182:185], v[206:209], v[32:35]
	v_mfma_f32_16x16x32_bf16 v[24:27], v[190:193], v[206:209], v[24:27]
	v_mfma_f32_16x16x32_bf16 v[16:19], v[182:185], v[214:217], v[16:19]
	v_mfma_f32_16x16x32_bf16 v[8:11], v[190:193], v[214:217], v[8:11]
	v_mfma_f32_16x16x32_bf16 v[4:7], v[182:185], v[222:225], v[4:7]
	v_mfma_f32_16x16x32_bf16 v[0:3], v[190:193], v[222:225], v[0:3]
	v_mfma_f32_16x16x32_bf16 v[48:51], v[186:189], v[202:205], v[48:51]
	v_mfma_f32_16x16x32_bf16 v[40:43], v[194:197], v[202:205], v[40:43]
	v_mfma_f32_16x16x32_bf16 v[32:35], v[186:189], v[210:213], v[32:35]
	v_mfma_f32_16x16x32_bf16 v[24:27], v[194:197], v[210:213], v[24:27]
	v_mfma_f32_16x16x32_bf16 v[16:19], v[186:189], v[218:221], v[16:19]
	v_mfma_f32_16x16x32_bf16 v[8:11], v[194:197], v[218:221], v[8:11]
	s_setprio 2
	s_barrier
; #define PG8_STAGE(bufoff, gbase, voff) do { _Pragma("unroll") for (int _i = 0; _i < 2; ++_i) \
;         __builtin_amdgcn_global_load_lds((const unsigned*)((const char*)(gbase) + (voff)[_i]), (PG8_LAS unsigned*)(lds + (bufoff) + ldsw + _i * 8192), 16, 0, 0); } while (0)
; #define PG8_LDA(dst, b, h) do { _Pragma("unroll") for (int m = 0; m < 4; ++m) _Pragma("unroll") for (int k = 0; k < 2; ++k) dst[m][k] = *(const PG8_LAS bf16x8*)(lds + PG8_SA(b, h) + aoff + m * 2048 + k * 1024); } while (0)
; #define PG8_LDB(dst, b, h) do { _Pragma("unroll") for (int n = 0; n < 2; ++n) _Pragma("unroll") for (int k = 0; k < 2; ++k) dst[n][k] = *(const PG8_LAS bf16x8*)(lds + PG8_SB(b, h) + boff + n * 2048 + k * 1024); } while (0)
; #define PG8_MMA(ai, bj, At, Bt) do { __builtin_amdgcn_s_setprio(1); _Pragma("unroll") for (int m = 0; m < 4; ++m) _Pragma("unroll") for (int n = 0; n < 2; ++n) _Pragma("unroll") for (int k = 0; k < 2; ++k) \
;         acc[ai][bj][m][n] = __builtin_amdgcn_mfma_f32_16x16x32_bf16(Bt[n][k], At[m][k], acc[ai][bj][m][n], 0, 0, 0); __builtin_amdgcn_s_setprio(0); } while (0)
; #define PG8_WAIT_V(n) asm volatile("s_waitcnt vmcnt(" #n ")" ::: "memory")
; #define PG8_WAIT_L(n) asm volatile("s_waitcnt lgkmcnt(" #n ")" ::: "memory")
; #define PG8_BAR __builtin_amdgcn_s_barrier()
; #define PG8_SCHED __builtin_amdgcn_sched_barrier(0)
; template <class Epi, class Sched, bool ALIGN_EPI = false, bool SP2 = false>
; __device__ __forceinline__ void gemm_phase(PG8_LAS unsigned char* lds, const Gemm g, const Sched& S, const Epi& E) {
;     ...
;             PG8_LDB(B0, 1, 0); PG8_LDB(B1, 1, 1); PG8_SCHED; PG8_LDA(At, 1, 0); PG8_STAGE(PG8_SA(0, 1), a2 + hstep, voffA);
;             PG8_WAIT_V(8); PG8_WAIT_L(0); PG8_BAR; PG8_MMA(0, 0, At, B0); PG8_MMA(0, 1, At, B1); PG8_BAR; PG8_SCHED;
;             PG8_LDA(At, 1, 1); PG8_STAGE(PG8_SB(1, 0), b3, voffB); PG8_STAGE(PG8_SB(1, 1), b3 + hstep, voffB); PG8_STAGE(PG8_SA(1, 0), a3, voffA);
;             PG8_WAIT_V(8); PG8_WAIT_L(0); PG8_BAR; PG8_MMA(1, 0, At, B0); PG8_MMA(1, 1, At, B1); PG8_BAR; PG8_SCHED;
	v_mfma_f32_16x16x32_bf16 v[4:7], v[186:189], v[226:229], v[4:7]
	v_mfma_f32_16x16x32_bf16 v[0:3], v[194:197], v[226:229], v[0:3]
	s_setprio 0
	ds_read_b128 v[166:169], v148
	ds_read_b128 v[170:173], v148 offset:1024
	ds_read_b128 v[174:177], v148 offset:2048
	ds_read_b128 v[178:181], v148 offset:3072
	ds_read_b128 v[182:185], v165
	ds_read_b128 v[186:189], v165 offset:1024
	ds_read_b128 v[190:193], v165 offset:2048
	ds_read_b128 v[194:197], v165 offset:3072
	s_add_u32 s52, s76, 0x200000
	s_addc_u32 s53, s77, 0
	s_mov_b32 m0, s33
	ds_read_b128 v[198:201], v164 offset:32768
	ds_read_b128 v[202:205], v164 offset:33792
	ds_read_b128 v[206:209], v164 offset:34816
	ds_read_b128 v[210:213], v164 offset:35840
	ds_read_b128 v[214:217], v164 offset:36864
	ds_read_b128 v[218:221], v164 offset:37888
	ds_read_b128 v[222:225], v164 offset:38912
	ds_read_b128 v[226:229], v164 offset:39936
	global_load_lds_dwordx4 v136, s[52:53]
	s_mov_b32 m0, s38
	s_nop 0
	global_load_lds_dwordx4 v140, s[52:53]
	s_waitcnt vmcnt(8)
	s_waitcnt lgkmcnt(0)
	s_setprio 1
	s_barrier
	v_mfma_f32_16x16x32_bf16 v[124:127], v[166:169], v[198:201], v[124:127]
	v_mfma_f32_16x16x32_bf16 v[120:123], v[174:177], v[198:201], v[120:123]
	v_mfma_f32_16x16x32_bf16 v[116:119], v[166:169], v[206:209], v[116:119]
	v_mfma_f32_16x16x32_bf16 v[108:111], v[174:177], v[206:209], v[108:111]
	v_mfma_f32_16x16x32_bf16 v[100:103], v[166:169], v[214:217], v[100:103]
	v_mfma_f32_16x16x32_bf16 v[92:95], v[174:177], v[214:217], v[92:95]
	v_mfma_f32_16x16x32_bf16 v[84:87], v[166:169], v[222:225], v[84:87]
	v_mfma_f32_16x16x32_bf16 v[76:79], v[174:177], v[222:225], v[76:79]
	v_mfma_f32_16x16x32_bf16 v[124:127], v[170:173], v[202:205], v[124:127]
	v_mfma_f32_16x16x32_bf16 v[120:123], v[178:181], v[202:205], v[120:123]
	v_mfma_f32_16x16x32_bf16 v[116:119], v[170:173], v[210:213], v[116:119]
	v_mfma_f32_16x16x32_bf16 v[108:111], v[178:181], v[210:213], v[108:111]
	v_mfma_f32_16x16x32_bf16 v[100:103], v[170:173], v[218:221], v[100:103]
	v_mfma_f32_16x16x32_bf16 v[92:95], v[178:181], v[218:221], v[92:95]
	v_mfma_f32_16x16x32_bf16 v[84:87], v[170:173], v[226:229], v[84:87]
	v_mfma_f32_16x16x32_bf16 v[76:79], v[178:181], v[226:229], v[76:79]
	s_setprio 0
	s_setprio 1
	v_mfma_f32_16x16x32_bf16 v[112:115], v[182:185], v[198:201], v[112:115]
	v_mfma_f32_16x16x32_bf16 v[104:107], v[190:193], v[198:201], v[104:107]
	v_mfma_f32_16x16x32_bf16 v[96:99], v[182:185], v[206:209], v[96:99]
	v_mfma_f32_16x16x32_bf16 v[88:91], v[190:193], v[206:209], v[88:91]
	v_mfma_f32_16x16x32_bf16 v[80:83], v[182:185], v[214:217], v[80:83]
	v_mfma_f32_16x16x32_bf16 v[72:75], v[190:193], v[214:217], v[72:75]
	v_mfma_f32_16x16x32_bf16 v[68:71], v[182:185], v[222:225], v[68:71]
	v_mfma_f32_16x16x32_bf16 v[64:67], v[190:193], v[222:225], v[64:67]
	v_mfma_f32_16x16x32_bf16 v[112:115], v[186:189], v[202:205], v[112:115]
	v_mfma_f32_16x16x32_bf16 v[104:107], v[194:197], v[202:205], v[104:107]
	v_mfma_f32_16x16x32_bf16 v[96:99], v[186:189], v[210:213], v[96:99]
	v_mfma_f32_16x16x32_bf16 v[88:91], v[194:197], v[210:213], v[88:91]
	v_mfma_f32_16x16x32_bf16 v[80:83], v[186:189], v[218:221], v[80:83]
	v_mfma_f32_16x16x32_bf16 v[72:75], v[194:197], v[218:221], v[72:75]
	s_setprio 2
	s_barrier
	v_mfma_f32_16x16x32_bf16 v[68:71], v[186:189], v[226:229], v[68:71]
	v_mfma_f32_16x16x32_bf16 v[64:67], v[194:197], v[226:229], v[64:67]
	s_setprio 0
	s_mov_b32 m0, s89
	v_lshl_add_u64 v[230:231], v[230:231], 0, s[12:13]
	ds_read_b128 v[198:201], v164 offset:49152
	ds_read_b128 v[202:205], v164 offset:50176
	ds_read_b128 v[206:209], v164 offset:51200
	ds_read_b128 v[210:213], v164 offset:52224
	ds_read_b128 v[214:217], v164 offset:53248
	ds_read_b128 v[218:221], v164 offset:54272
	ds_read_b128 v[222:225], v164 offset:55296
	ds_read_b128 v[226:229], v164 offset:56320
	global_load_lds_dwordx4 v[230:231], off
	s_add_i32 m0, s89, 0x2000
	s_add_u32 s52, s74, 0x200080
	v_lshl_add_u64 v[230:231], v[232:233], 0, s[12:13]
	s_addc_u32 s53, s75, 0
	s_add_i32 s56, s88, s3
	global_load_lds_dwordx4 v[230:231], off
	s_mov_b32 m0, s56
	s_nop 0
	global_load_lds_dwordx4 v138, s[52:53]
	s_add_i32 m0, s56, 0x2000
	s_nop 0
	global_load_lds_dwordx4 v142, s[52:53]
	v_lshl_add_u64 v[230:231], v[234:235], 0, s[12:13]
	s_mov_b32 m0, s71
	s_nop 0
	global_load_lds_dwordx4 v[230:231], off
	v_lshl_add_u64 v[230:231], v[236:237], 0, s[12:13]
	s_mov_b32 m0, s78
	s_nop 0
	global_load_lds_dwordx4 v[230:231], off
	s_waitcnt vmcnt(8)
	s_waitcnt lgkmcnt(0)
	s_setprio 1
	s_barrier
	v_mfma_f32_16x16x32_bf16 v[60:63], v[166:169], v[198:201], v[60:63]
	v_mfma_f32_16x16x32_bf16 v[56:59], v[174:177], v[198:201], v[56:59]
	v_mfma_f32_16x16x32_bf16 v[52:55], v[166:169], v[206:209], v[52:55]
	v_mfma_f32_16x16x32_bf16 v[44:47], v[174:177], v[206:209], v[44:47]
	v_mfma_f32_16x16x32_bf16 v[36:39], v[166:169], v[214:217], v[36:39]
	v_mfma_f32_16x16x32_bf16 v[28:31], v[174:177], v[214:217], v[28:31]
	v_mfma_f32_16x16x32_bf16 v[20:23], v[166:169], v[222:225], v[20:23]
	v_mfma_f32_16x16x32_bf16 v[12:15], v[174:177], v[222:225], v[12:15]
	v_mfma_f32_16x16x32_bf16 v[60:63], v[170:173], v[202:205], v[60:63]
	v_mfma_f32_16x16x32_bf16 v[56:59], v[178:181], v[202:205], v[56:59]
	v_mfma_f32_16x16x32_bf16 v[52:55], v[170:173], v[210:213], v[52:55]
	v_mfma_f32_16x16x32_bf16 v[44:47], v[178:181], v[210:213], v[44:47]
	v_mfma_f32_16x16x32_bf16 v[36:39], v[170:173], v[218:221], v[36:39]
	v_mfma_f32_16x16x32_bf16 v[28:31], v[178:181], v[218:221], v[28:31]
	v_mfma_f32_16x16x32_bf16 v[20:23], v[170:173], v[226:229], v[20:23]
	v_mfma_f32_16x16x32_bf16 v[12:15], v[178:181], v[226:229], v[12:15]
	s_setprio 0
	s_setprio 1
	v_mfma_f32_16x16x32_bf16 v[48:51], v[182:185], v[198:201], v[48:51]
	v_mfma_f32_16x16x32_bf16 v[40:43], v[190:193], v[198:201], v[40:43]
	v_mfma_f32_16x16x32_bf16 v[32:35], v[182:185], v[206:209], v[32:35]
	v_mfma_f32_16x16x32_bf16 v[24:27], v[190:193], v[206:209], v[24:27]
	v_mfma_f32_16x16x32_bf16 v[16:19], v[182:185], v[214:217], v[16:19]
	v_mfma_f32_16x16x32_bf16 v[8:11], v[190:193], v[214:217], v[8:11]
	v_mfma_f32_16x16x32_bf16 v[4:7], v[182:185], v[222:225], v[4:7]
	v_mfma_f32_16x16x32_bf16 v[0:3], v[190:193], v[222:225], v[0:3]
	v_mfma_f32_16x16x32_bf16 v[48:51], v[186:189], v[202:205], v[48:51]
	v_mfma_f32_16x16x32_bf16 v[40:43], v[194:197], v[202:205], v[40:43]
	v_mfma_f32_16x16x32_bf16 v[32:35], v[186:189], v[210:213], v[32:35]
	v_mfma_f32_16x16x32_bf16 v[24:27], v[194:197], v[210:213], v[24:27]
	v_mfma_f32_16x16x32_bf16 v[16:19], v[186:189], v[218:221], v[16:19]
	v_mfma_f32_16x16x32_bf16 v[8:11], v[194:197], v[218:221], v[8:11]
	s_setprio 2
	s_barrier
	v_mfma_f32_16x16x32_bf16 v[4:7], v[186:189], v[226:229], v[4:7]
	v_mfma_f32_16x16x32_bf16 v[0:3], v[194:197], v[226:229], v[0:3]
	s_setprio 0
	s_add_i32 s49, s49, 2
	s_add_u32 s72, s72, 0x100
	s_addc_u32 s73, s73, 0
	s_add_u32 s37, s37, 0x100
	s_addc_u32 s41, s41, 0
	s_cmp_gt_u32 s49, 29
	s_cbranch_scc0 .LBB0_660
	s_and_b64 vcc, exec, s[14:15]
	s_cbranch_vccz .LBB0_663
	s_barrier

; #define PG8_STAGE(bufoff, gbase, voff) do { _Pragma("unroll") for (int _i = 0; _i < 2; ++_i) \
;         __builtin_amdgcn_global_load_lds((const unsigned*)((const char*)(gbase) + (voff)[_i]), (PG8_LAS unsigned*)(lds + (bufoff) + ldsw + _i * 8192), 16, 0, 0); } while (0)
; #define PG8_LDA(dst, b, h) do { _Pragma("unroll") for (int m = 0; m < 4; ++m) _Pragma("unroll") for (int k = 0; k < 2; ++k) dst[m][k] = *(const PG8_LAS bf16x8*)(lds + PG8_SA(b, h) + aoff + m * 2048 + k * 1024); } while (0)
; #define PG8_LDB(dst, b, h) do { _Pragma("unroll") for (int n = 0; n < 2; ++n) _Pragma("unroll") for (int k = 0; k < 2; ++k) dst[n][k] = *(const PG8_LAS bf16x8*)(lds + PG8_SB(b, h) + boff + n * 2048 + k * 1024); } while (0)
; #define PG8_MMA(ai, bj, At, Bt) do { __builtin_amdgcn_s_setprio(1); _Pragma("unroll") for (int m = 0; m < 4; ++m) _Pragma("unroll") for (int n = 0; n < 2; ++n) _Pragma("unroll") for (int k = 0; k < 2; ++k) \
;         acc[ai][bj][m][n] = __builtin_amdgcn_mfma_f32_16x16x32_bf16(Bt[n][k], At[m][k], acc[ai][bj][m][n], 0, 0, 0); __builtin_amdgcn_s_setprio(0); } while (0)
; #define PG8_WAIT_V(n) asm volatile("s_waitcnt vmcnt(" #n ")" ::: "memory")
; #define PG8_WAIT_L(n) asm volatile("s_waitcnt lgkmcnt(" #n ")" ::: "memory")
; #define PG8_BAR __builtin_amdgcn_s_barrier()
; template <class Epi, class Sched, bool ALIGN_EPI = false, bool SP2 = false>
; __device__ __forceinline__ void gemm_phase(PG8_LAS unsigned char* lds, const Gemm g, const Sched& S, const Epi& E) {
;     ...
;             const bool last = (t == nt - 2);
;             const char* a1 = cA + (size_t)(t + 1) * kstep;
;             const char* a2 = last ? nA : cA + (size_t)(t + 2) * kstep; const char* b2 = last ? nB : cB + (size_t)(t + 2) * kstep;
;             const char* a3 = a2 + kstep; const char* b3 = b2 + kstep;
;             if constexpr (SP2) {
;             PG8_LDB(B0, 0, 0); PG8_LDB(B1, 0, 1); PG8_SCHED; PG8_LDA(At, 0, 0); PG8_STAGE(PG8_SA(1, 1), a1 + hstep, voffA);
;             PG8_WAIT_V(8); PG8_WAIT_L(0); PG8_BAR; PG8_MMA(0, 0, At, B0); PG8_MMA(0, 1, At, B1); PG8_BAR; PG8_SCHED;
;             PG8_LDA(At, 0, 1); PG8_STAGE(PG8_SB(0, 0), b2, voffB); PG8_STAGE(PG8_SB(0, 1), b2 + hstep, voffB); PG8_STAGE(PG8_SA(0, 0), a2, voffA);
;             PG8_WAIT_V(8); PG8_WAIT_L(0); PG8_BAR; PG8_MMA(1, 0, At, B0); PG8_MMA(1, 1, At, B1); PG8_BAR; PG8_SCHED;
.LBB0_809:
	ds_read_b128 v[128:131], v180
	ds_read_b128 v[132:135], v180 offset:1024
	ds_read_b128 v[136:139], v180 offset:2048
	ds_read_b128 v[140:143], v180 offset:3072
	ds_read_b128 v[160:163], v181
	ds_read_b128 v[164:167], v181 offset:1024
	ds_read_b128 v[184:187], v181 offset:2048
	ds_read_b128 v[188:191], v181 offset:3072
	s_add_u32 s52, s72, 0xfff80080
	s_addc_u32 s53, s73, -1
	s_cmp_eq_u32 s92, 28
	s_cselect_b32 s77, s5, s53
	s_cselect_b32 s76, s49, s52
	s_cselect_b32 s75, s45, s91
	s_cselect_b32 s74, s89, s90
	s_add_i32 m0, s71, 0xc000
	ds_read_b128 v[192:195], v182
	ds_read_b128 v[196:199], v182 offset:1024
	ds_read_b128 v[200:203], v182 offset:2048
	ds_read_b128 v[204:207], v182 offset:3072
	ds_read_b128 v[208:211], v182 offset:4096
	ds_read_b128 v[212:215], v182 offset:5120
	ds_read_b128 v[216:219], v182 offset:6144
	ds_read_b128 v[220:223], v182 offset:7168
	global_load_lds_dwordx4 v154, s[72:73]
	s_add_i32 m0, s71, 0xe000
	s_nop 0
	global_load_lds_dwordx4 v156, s[72:73]
	s_waitcnt vmcnt(8)
	s_waitcnt lgkmcnt(0)
	s_setprio 1
	s_barrier
	v_mfma_f32_16x16x32_bf16 v[124:127], v[128:131], v[192:195], v[124:127]
	v_mfma_f32_16x16x32_bf16 v[120:123], v[136:139], v[192:195], v[120:123]
	v_mfma_f32_16x16x32_bf16 v[108:111], v[128:131], v[200:203], v[108:111]
	v_mfma_f32_16x16x32_bf16 v[104:107], v[136:139], v[200:203], v[104:107]
	v_mfma_f32_16x16x32_bf16 v[92:95], v[128:131], v[208:211], v[92:95]
	v_mfma_f32_16x16x32_bf16 v[88:91], v[136:139], v[208:211], v[88:91]
	v_mfma_f32_16x16x32_bf16 v[76:79], v[128:131], v[216:219], v[76:79]
	v_mfma_f32_16x16x32_bf16 v[72:75], v[136:139], v[216:219], v[72:75]
	v_mfma_f32_16x16x32_bf16 v[124:127], v[132:135], v[196:199], v[124:127]
	v_mfma_f32_16x16x32_bf16 v[120:123], v[140:143], v[196:199], v[120:123]
	v_mfma_f32_16x16x32_bf16 v[108:111], v[132:135], v[204:207], v[108:111]
	v_mfma_f32_16x16x32_bf16 v[104:107], v[140:143], v[204:207], v[104:107]
	v_mfma_f32_16x16x32_bf16 v[92:95], v[132:135], v[212:215], v[92:95]
	v_mfma_f32_16x16x32_bf16 v[88:91], v[140:143], v[212:215], v[88:91]
	v_mfma_f32_16x16x32_bf16 v[76:79], v[132:135], v[220:223], v[76:79]
	v_mfma_f32_16x16x32_bf16 v[72:75], v[140:143], v[220:223], v[72:75]
	s_setprio 0
	s_setprio 1
	v_mfma_f32_16x16x32_bf16 v[116:119], v[160:163], v[192:195], v[116:119]
	v_mfma_f32_16x16x32_bf16 v[112:115], v[184:187], v[192:195], v[112:115]
	v_mfma_f32_16x16x32_bf16 v[100:103], v[160:163], v[200:203], v[100:103]
	v_mfma_f32_16x16x32_bf16 v[96:99], v[184:187], v[200:203], v[96:99]
	v_mfma_f32_16x16x32_bf16 v[84:87], v[160:163], v[208:211], v[84:87]
	v_mfma_f32_16x16x32_bf16 v[80:83], v[184:187], v[208:211], v[80:83]
	v_mfma_f32_16x16x32_bf16 v[68:71], v[160:163], v[216:219], v[68:71]
	v_mfma_f32_16x16x32_bf16 v[64:67], v[184:187], v[216:219], v[64:67]
	v_mfma_f32_16x16x32_bf16 v[116:119], v[164:167], v[196:199], v[116:119]
	v_mfma_f32_16x16x32_bf16 v[112:115], v[188:191], v[196:199], v[112:115]
	v_mfma_f32_16x16x32_bf16 v[100:103], v[164:167], v[204:207], v[100:103]
	v_mfma_f32_16x16x32_bf16 v[96:99], v[188:191], v[204:207], v[96:99]
	v_mfma_f32_16x16x32_bf16 v[84:87], v[164:167], v[212:215], v[84:87]
	v_mfma_f32_16x16x32_bf16 v[80:83], v[188:191], v[212:215], v[80:83]
	s_setprio 2
	s_barrier
	v_mfma_f32_16x16x32_bf16 v[68:71], v[164:167], v[220:223], v[68:71]
	v_mfma_f32_16x16x32_bf16 v[64:67], v[188:191], v[220:223], v[64:67]
	s_setprio 0
	s_add_i32 s52, s83, s78
	v_lshl_add_u64 v[168:169], s[74:75], 0, v[148:149]
	s_mov_b32 m0, s52
	ds_read_b128 v[192:195], v182 offset:16384
	ds_read_b128 v[196:199], v182 offset:17408
	ds_read_b128 v[200:203], v182 offset:18432
	ds_read_b128 v[204:207], v182 offset:19456
	ds_read_b128 v[208:211], v182 offset:20480
	ds_read_b128 v[212:215], v182 offset:21504
	ds_read_b128 v[216:219], v182 offset:22528
	ds_read_b128 v[220:223], v182 offset:23552
	global_load_lds_dwordx4 v[168:169], off
	s_add_i32 m0, s52, 0x2000
	s_add_u32 s52, s74, 0x80000
	v_lshl_add_u64 v[224:225], s[74:75], 0, v[152:153]
	s_addc_u32 s53, s75, 0
	s_add_i32 s56, s84, s78
	global_load_lds_dwordx4 v[224:225], off
	s_mov_b32 m0, s56
	v_lshl_add_u64 v[228:229], s[76:77], 0, v[150:151]
	global_load_lds_dwordx4 v148, s[52:53]
	s_add_i32 m0, s56, 0x2000
	s_nop 0
	global_load_lds_dwordx4 v152, s[52:53]
	v_lshl_add_u64 v[226:227], s[76:77], 0, v[144:145]
	s_mov_b32 m0, s71
	s_nop 0
	global_load_lds_dwordx4 v[226:227], off
	s_mov_b32 m0, s79
	s_nop 0
	global_load_lds_dwordx4 v[228:229], off
	s_waitcnt vmcnt(8)
	s_waitcnt lgkmcnt(0)
	s_setprio 1
	s_barrier
	v_mfma_f32_16x16x32_bf16 v[60:63], v[128:131], v[192:195], v[60:63]
	v_mfma_f32_16x16x32_bf16 v[56:59], v[136:139], v[192:195], v[56:59]
	v_mfma_f32_16x16x32_bf16 v[44:47], v[128:131], v[200:203], v[44:47]
	v_mfma_f32_16x16x32_bf16 v[40:43], v[136:139], v[200:203], v[40:43]
	v_mfma_f32_16x16x32_bf16 v[28:31], v[128:131], v[208:211], v[28:31]
	v_mfma_f32_16x16x32_bf16 v[24:27], v[136:139], v[208:211], v[24:27]
	v_mfma_f32_16x16x32_bf16 v[12:15], v[128:131], v[216:219], v[12:15]
	v_mfma_f32_16x16x32_bf16 v[8:11], v[136:139], v[216:219], v[8:11]
	v_mfma_f32_16x16x32_bf16 v[60:63], v[132:135], v[196:199], v[60:63]
	v_mfma_f32_16x16x32_bf16 v[56:59], v[140:143], v[196:199], v[56:59]
	v_mfma_f32_16x16x32_bf16 v[44:47], v[132:135], v[204:207], v[44:47]
	v_mfma_f32_16x16x32_bf16 v[40:43], v[140:143], v[204:207], v[40:43]
	v_mfma_f32_16x16x32_bf16 v[28:31], v[132:135], v[212:215], v[28:31]
	v_mfma_f32_16x16x32_bf16 v[24:27], v[140:143], v[212:215], v[24:27]
	v_mfma_f32_16x16x32_bf16 v[12:15], v[132:135], v[220:223], v[12:15]
	v_mfma_f32_16x16x32_bf16 v[8:11], v[140:143], v[220:223], v[8:11]
	s_setprio 0
	s_setprio 1
	v_mfma_f32_16x16x32_bf16 v[52:55], v[160:163], v[192:195], v[52:55]
	v_mfma_f32_16x16x32_bf16 v[48:51], v[184:187], v[192:195], v[48:51]
	v_mfma_f32_16x16x32_bf16 v[36:39], v[160:163], v[200:203], v[36:39]
	v_mfma_f32_16x16x32_bf16 v[32:35], v[184:187], v[200:203], v[32:35]
	v_mfma_f32_16x16x32_bf16 v[20:23], v[160:163], v[208:211], v[20:23]
	v_mfma_f32_16x16x32_bf16 v[16:19], v[184:187], v[208:211], v[16:19]
	v_mfma_f32_16x16x32_bf16 v[4:7], v[160:163], v[216:219], v[4:7]
	v_mfma_f32_16x16x32_bf16 v[0:3], v[184:187], v[216:219], v[0:3]
	v_mfma_f32_16x16x32_bf16 v[52:55], v[164:167], v[196:199], v[52:55]
	v_mfma_f32_16x16x32_bf16 v[48:51], v[188:191], v[196:199], v[48:51]
	v_mfma_f32_16x16x32_bf16 v[36:39], v[164:167], v[204:207], v[36:39]
	v_mfma_f32_16x16x32_bf16 v[32:35], v[188:191], v[204:207], v[32:35]
	v_mfma_f32_16x16x32_bf16 v[20:23], v[164:167], v[212:215], v[20:23]
	v_mfma_f32_16x16x32_bf16 v[16:19], v[188:191], v[212:215], v[16:19]
	s_setprio 2
	s_barrier
; #define PG8_STAGE(bufoff, gbase, voff) do { _Pragma("unroll") for (int _i = 0; _i < 2; ++_i) \
;         __builtin_amdgcn_global_load_lds((const unsigned*)((const char*)(gbase) + (voff)[_i]), (PG8_LAS unsigned*)(lds + (bufoff) + ldsw + _i * 8192), 16, 0, 0); } while (0)
; #define PG8_LDA(dst, b, h) do { _Pragma("unroll") for (int m = 0; m < 4; ++m) _Pragma("unroll") for (int k = 0; k < 2; ++k) dst[m][k] = *(const PG8_LAS bf16x8*)(lds + PG8_SA(b, h) + aoff + m * 2048 + k * 1024); } while (0)
; #define PG8_LDB(dst, b, h) do { _Pragma("unroll") for (int n = 0; n < 2; ++n) _Pragma("unroll") for (int k = 0; k < 2; ++k) dst[n][k] = *(const PG8_LAS bf16x8*)(lds + PG8_SB(b, h) + boff + n * 2048 + k * 1024); } while (0)
; #define PG8_MMA(ai, bj, At, Bt) do { __builtin_amdgcn_s_setprio(1); _Pragma("unroll") for (int m = 0; m < 4; ++m) _Pragma("unroll") for (int n = 0; n < 2; ++n) _Pragma("unroll") for (int k = 0; k < 2; ++k) \
;         acc[ai][bj][m][n] = __builtin_amdgcn_mfma_f32_16x16x32_bf16(Bt[n][k], At[m][k], acc[ai][bj][m][n], 0, 0, 0); __builtin_amdgcn_s_setprio(0); } while (0)
; #define PG8_WAIT_V(n) asm volatile("s_waitcnt vmcnt(" #n ")" ::: "memory")
; #define PG8_WAIT_L(n) asm volatile("s_waitcnt lgkmcnt(" #n ")" ::: "memory")
; #define PG8_BAR __builtin_amdgcn_s_barrier()
; #define PG8_SCHED __builtin_amdgcn_sched_barrier(0)
; template <class Epi, class Sched, bool ALIGN_EPI = false, bool SP2 = false>
; __device__ __forceinline__ void gemm_phase(PG8_LAS unsigned char* lds, const Gemm g, const Sched& S, const Epi& E) {
;     ...
;             PG8_LDB(B0, 1, 0); PG8_LDB(B1, 1, 1); PG8_SCHED; PG8_LDA(At, 1, 0); PG8_STAGE(PG8_SA(0, 1), a2 + hstep, voffA);
;             PG8_WAIT_V(8); PG8_WAIT_L(0); PG8_BAR; PG8_MMA(0, 0, At, B0); PG8_MMA(0, 1, At, B1); PG8_BAR; PG8_SCHED;
	v_mfma_f32_16x16x32_bf16 v[4:7], v[164:167], v[220:223], v[4:7]
	v_mfma_f32_16x16x32_bf16 v[0:3], v[188:191], v[220:223], v[0:3]
	s_setprio 0
	s_add_i32 s56, 0, 0x18000
	s_add_i32 s57, 0, 0x1c000
	v_add_u32_e32 v140, s56, v171
	v_add_u32_e32 v188, s57, v171
	ds_read_b128 v[128:131], v140
	ds_read_b128 v[132:135], v140 offset:1024
	ds_read_b128 v[136:139], v140 offset:2048
	ds_read_b128 v[140:143], v140 offset:3072
	ds_read_b128 v[160:163], v188
	ds_read_b128 v[164:167], v188 offset:1024
	ds_read_b128 v[184:187], v188 offset:2048
	ds_read_b128 v[188:191], v188 offset:3072
	s_add_u32 s52, s76, 0x80000
	s_addc_u32 s53, s77, 0
	s_mov_b32 m0, s80
	ds_read_b128 v[192:195], v182 offset:32768
	ds_read_b128 v[196:199], v182 offset:33792
	ds_read_b128 v[200:203], v182 offset:34816
	ds_read_b128 v[204:207], v182 offset:35840
	ds_read_b128 v[208:211], v182 offset:36864
	ds_read_b128 v[212:215], v182 offset:37888
	ds_read_b128 v[216:219], v182 offset:38912
	ds_read_b128 v[220:223], v182 offset:39936
	global_load_lds_dwordx4 v144, s[52:53]
	s_mov_b32 m0, s81
	s_nop 0
	global_load_lds_dwordx4 v150, s[52:53]
	s_waitcnt vmcnt(8)
	s_waitcnt lgkmcnt(0)
	s_setprio 1
	s_barrier
	v_mfma_f32_16x16x32_bf16 v[124:127], v[128:131], v[192:195], v[124:127]
	v_mfma_f32_16x16x32_bf16 v[120:123], v[136:139], v[192:195], v[120:123]
	v_mfma_f32_16x16x32_bf16 v[108:111], v[128:131], v[200:203], v[108:111]
	v_mfma_f32_16x16x32_bf16 v[104:107], v[136:139], v[200:203], v[104:107]
	v_mfma_f32_16x16x32_bf16 v[92:95], v[128:131], v[208:211], v[92:95]
	v_mfma_f32_16x16x32_bf16 v[88:91], v[136:139], v[208:211], v[88:91]
	v_mfma_f32_16x16x32_bf16 v[76:79], v[128:131], v[216:219], v[76:79]
	v_mfma_f32_16x16x32_bf16 v[72:75], v[136:139], v[216:219], v[72:75]
	v_mfma_f32_16x16x32_bf16 v[124:127], v[132:135], v[196:199], v[124:127]
	v_mfma_f32_16x16x32_bf16 v[120:123], v[140:143], v[196:199], v[120:123]
	v_mfma_f32_16x16x32_bf16 v[108:111], v[132:135], v[204:207], v[108:111]
	v_mfma_f32_16x16x32_bf16 v[104:107], v[140:143], v[204:207], v[104:107]
	v_mfma_f32_16x16x32_bf16 v[92:95], v[132:135], v[212:215], v[92:95]
	v_mfma_f32_16x16x32_bf16 v[88:91], v[140:143], v[212:215], v[88:91]
	v_mfma_f32_16x16x32_bf16 v[76:79], v[132:135], v[220:223], v[76:79]
	v_mfma_f32_16x16x32_bf16 v[72:75], v[140:143], v[220:223], v[72:75]
	s_setprio 0
	s_setprio 1
	v_mfma_f32_16x16x32_bf16 v[116:119], v[160:163], v[192:195], v[116:119]
	v_mfma_f32_16x16x32_bf16 v[112:115], v[184:187], v[192:195], v[112:115]
	v_mfma_f32_16x16x32_bf16 v[100:103], v[160:163], v[200:203], v[100:103]
	v_mfma_f32_16x16x32_bf16 v[96:99], v[184:187], v[200:203], v[96:99]
	v_mfma_f32_16x16x32_bf16 v[84:87], v[160:163], v[208:211], v[84:87]
	v_mfma_f32_16x16x32_bf16 v[80:83], v[184:187], v[208:211], v[80:83]
	v_mfma_f32_16x16x32_bf16 v[68:71], v[160:163], v[216:219], v[68:71]
	v_mfma_f32_16x16x32_bf16 v[64:67], v[184:187], v[216:219], v[64:67]
	v_mfma_f32_16x16x32_bf16 v[116:119], v[164:167], v[196:199], v[116:119]
	v_mfma_f32_16x16x32_bf16 v[112:115], v[188:191], v[196:199], v[112:115]
	v_mfma_f32_16x16x32_bf16 v[100:103], v[164:167], v[204:207], v[100:103]
	v_mfma_f32_16x16x32_bf16 v[96:99], v[188:191], v[204:207], v[96:99]
	v_mfma_f32_16x16x32_bf16 v[84:87], v[164:167], v[212:215], v[84:87]
	v_mfma_f32_16x16x32_bf16 v[80:83], v[188:191], v[212:215], v[80:83]
	s_setprio 2
	s_barrier
; #define PG8_STAGE(bufoff, gbase, voff) do { _Pragma("unroll") for (int _i = 0; _i < 2; ++_i) \
;         __builtin_amdgcn_global_load_lds((const unsigned*)((const char*)(gbase) + (voff)[_i]), (PG8_LAS unsigned*)(lds + (bufoff) + ldsw + _i * 8192), 16, 0, 0); } while (0)
; #define PG8_LDA(dst, b, h) do { _Pragma("unroll") for (int m = 0; m < 4; ++m) _Pragma("unroll") for (int k = 0; k < 2; ++k) dst[m][k] = *(const PG8_LAS bf16x8*)(lds + PG8_SA(b, h) + aoff + m * 2048 + k * 1024); } while (0)
; #define PG8_MMA(ai, bj, At, Bt) do { __builtin_amdgcn_s_setprio(1); _Pragma("unroll") for (int m = 0; m < 4; ++m) _Pragma("unroll") for (int n = 0; n < 2; ++n) _Pragma("unroll") for (int k = 0; k < 2; ++k) \
;         acc[ai][bj][m][n] = __builtin_amdgcn_mfma_f32_16x16x32_bf16(Bt[n][k], At[m][k], acc[ai][bj][m][n], 0, 0, 0); __builtin_amdgcn_s_setprio(0); } while (0)
; #define PG8_WAIT_V(n) asm volatile("s_waitcnt vmcnt(" #n ")" ::: "memory")
; #define PG8_WAIT_L(n) asm volatile("s_waitcnt lgkmcnt(" #n ")" ::: "memory")
; #define PG8_BAR __builtin_amdgcn_s_barrier()
; #define PG8_SCHED __builtin_amdgcn_sched_barrier(0)
; template <class Epi, class Sched, bool ALIGN_EPI = false, bool SP2 = false>
; __device__ __forceinline__ void gemm_phase(PG8_LAS unsigned char* lds, const Gemm g, const Sched& S, const Epi& E) {
;     ...
;             PG8_LDA(At, 1, 1); PG8_STAGE(PG8_SB(1, 0), b3, voffB); PG8_STAGE(PG8_SB(1, 1), b3 + hstep, voffB); PG8_STAGE(PG8_SA(1, 0), a3, voffA);
;             PG8_WAIT_V(8); PG8_WAIT_L(0); PG8_BAR; PG8_MMA(1, 0, At, B0); PG8_MMA(1, 1, At, B1); PG8_BAR; PG8_SCHED;
;     ...
;         if constexpr (ALIGN_EPI) { if (wr == 0) PG8_BAR; }
	v_mfma_f32_16x16x32_bf16 v[68:71], v[164:167], v[220:223], v[68:71]
	v_mfma_f32_16x16x32_bf16 v[64:67], v[188:191], v[220:223], v[64:67]
	s_setprio 0
	s_add_i32 s52, s56, s78
	v_lshl_add_u64 v[168:169], v[168:169], 0, s[40:41]
	s_mov_b32 m0, s52
	ds_read_b128 v[192:195], v182 offset:49152
	ds_read_b128 v[196:199], v182 offset:50176
	ds_read_b128 v[200:203], v182 offset:51200
	ds_read_b128 v[204:207], v182 offset:52224
	ds_read_b128 v[208:211], v182 offset:53248
	ds_read_b128 v[212:215], v182 offset:54272
	ds_read_b128 v[216:219], v182 offset:55296
	ds_read_b128 v[220:223], v182 offset:56320
	global_load_lds_dwordx4 v[168:169], off
	s_add_i32 m0, s52, 0x2000
	s_add_u32 s52, s74, 0x80080
	v_lshl_add_u64 v[168:169], v[224:225], 0, s[40:41]
	s_addc_u32 s53, s75, 0
	s_add_i32 s56, s57, s78
	global_load_lds_dwordx4 v[168:169], off
	s_mov_b32 m0, s56
	s_nop 0
	global_load_lds_dwordx4 v148, s[52:53]
	s_add_i32 m0, s56, 0x2000
	s_nop 0
	global_load_lds_dwordx4 v152, s[52:53]
	v_lshl_add_u64 v[168:169], v[226:227], 0, s[40:41]
	s_mov_b32 m0, s3
	s_nop 0
	global_load_lds_dwordx4 v[168:169], off
	v_lshl_add_u64 v[168:169], v[228:229], 0, s[40:41]
	s_mov_b32 m0, s28
	s_nop 0
	global_load_lds_dwordx4 v[168:169], off
	s_waitcnt vmcnt(8)
	s_waitcnt lgkmcnt(0)
	s_setprio 1
	s_barrier
	v_mfma_f32_16x16x32_bf16 v[60:63], v[128:131], v[192:195], v[60:63]
	v_mfma_f32_16x16x32_bf16 v[56:59], v[136:139], v[192:195], v[56:59]
	v_mfma_f32_16x16x32_bf16 v[44:47], v[128:131], v[200:203], v[44:47]
	v_mfma_f32_16x16x32_bf16 v[40:43], v[136:139], v[200:203], v[40:43]
	v_mfma_f32_16x16x32_bf16 v[28:31], v[128:131], v[208:211], v[28:31]
	v_mfma_f32_16x16x32_bf16 v[24:27], v[136:139], v[208:211], v[24:27]
	v_mfma_f32_16x16x32_bf16 v[12:15], v[128:131], v[216:219], v[12:15]
	v_mfma_f32_16x16x32_bf16 v[8:11], v[136:139], v[216:219], v[8:11]
	v_mfma_f32_16x16x32_bf16 v[60:63], v[132:135], v[196:199], v[60:63]
	v_mfma_f32_16x16x32_bf16 v[56:59], v[140:143], v[196:199], v[56:59]
	v_mfma_f32_16x16x32_bf16 v[44:47], v[132:135], v[204:207], v[44:47]
	v_mfma_f32_16x16x32_bf16 v[40:43], v[140:143], v[204:207], v[40:43]
	v_mfma_f32_16x16x32_bf16 v[28:31], v[132:135], v[212:215], v[28:31]
	v_mfma_f32_16x16x32_bf16 v[24:27], v[140:143], v[212:215], v[24:27]
	v_mfma_f32_16x16x32_bf16 v[12:15], v[132:135], v[220:223], v[12:15]
	v_mfma_f32_16x16x32_bf16 v[8:11], v[140:143], v[220:223], v[8:11]
	s_setprio 0
	s_setprio 1
	v_mfma_f32_16x16x32_bf16 v[52:55], v[160:163], v[192:195], v[52:55]
	v_mfma_f32_16x16x32_bf16 v[48:51], v[184:187], v[192:195], v[48:51]
	v_mfma_f32_16x16x32_bf16 v[36:39], v[160:163], v[200:203], v[36:39]
	v_mfma_f32_16x16x32_bf16 v[32:35], v[184:187], v[200:203], v[32:35]
	v_mfma_f32_16x16x32_bf16 v[20:23], v[160:163], v[208:211], v[20:23]
	v_mfma_f32_16x16x32_bf16 v[16:19], v[184:187], v[208:211], v[16:19]
	v_mfma_f32_16x16x32_bf16 v[4:7], v[160:163], v[216:219], v[4:7]
	v_mfma_f32_16x16x32_bf16 v[0:3], v[184:187], v[216:219], v[0:3]
	v_mfma_f32_16x16x32_bf16 v[52:55], v[164:167], v[196:199], v[52:55]
	v_mfma_f32_16x16x32_bf16 v[48:51], v[188:191], v[196:199], v[48:51]
	v_mfma_f32_16x16x32_bf16 v[36:39], v[164:167], v[204:207], v[36:39]
	v_mfma_f32_16x16x32_bf16 v[32:35], v[188:191], v[204:207], v[32:35]
	v_mfma_f32_16x16x32_bf16 v[20:23], v[164:167], v[212:215], v[20:23]
	v_mfma_f32_16x16x32_bf16 v[16:19], v[188:191], v[212:215], v[16:19]
	s_setprio 2
	s_barrier
	v_mfma_f32_16x16x32_bf16 v[4:7], v[164:167], v[220:223], v[4:7]
	v_mfma_f32_16x16x32_bf16 v[0:3], v[188:191], v[220:223], v[0:3]
	s_setprio 0
	s_add_i32 s92, s92, 2
	s_add_u32 s72, s72, 0x100
	s_addc_u32 s73, s73, 0
	s_add_u32 s90, s90, 0x100
	s_addc_u32 s91, s91, 0
	s_cmp_gt_u32 s92, 29
	s_cbranch_scc0 .LBB0_809
	s_and_b64 vcc, exec, s[42:43]
	s_cbranch_vccz .LBB0_812
	s_barrier

; #define PG8_STAGE(bufoff, gbase, voff) do { _Pragma("unroll") for (int _i = 0; _i < 2; ++_i) \
;         __builtin_amdgcn_global_load_lds((const unsigned*)((const char*)(gbase) + (voff)[_i]), (PG8_LAS unsigned*)(lds + (bufoff) + ldsw + _i * 8192), 16, 0, 0); } while (0)
; #define PG8_LDA(dst, b, h) do { _Pragma("unroll") for (int m = 0; m < 4; ++m) _Pragma("unroll") for (int k = 0; k < 2; ++k) dst[m][k] = *(const PG8_LAS bf16x8*)(lds + PG8_SA(b, h) + aoff + m * 2048 + k * 1024); } while (0)
; #define PG8_LDB(dst, b, h) do { _Pragma("unroll") for (int n = 0; n < 2; ++n) _Pragma("unroll") for (int k = 0; k < 2; ++k) dst[n][k] = *(const PG8_LAS bf16x8*)(lds + PG8_SB(b, h) + boff + n * 2048 + k * 1024); } while (0)
; #define PG8_MMA(ai, bj, At, Bt) do { __builtin_amdgcn_s_setprio(1); _Pragma("unroll") for (int m = 0; m < 4; ++m) _Pragma("unroll") for (int n = 0; n < 2; ++n) _Pragma("unroll") for (int k = 0; k < 2; ++k) \
;         acc[ai][bj][m][n] = __builtin_amdgcn_mfma_f32_16x16x32_bf16(Bt[n][k], At[m][k], acc[ai][bj][m][n], 0, 0, 0); __builtin_amdgcn_s_setprio(0); } while (0)
; #define PG8_WAIT_V(n) asm volatile("s_waitcnt vmcnt(" #n ")" ::: "memory")
; #define PG8_WAIT_L(n) asm volatile("s_waitcnt lgkmcnt(" #n ")" ::: "memory")
; #define PG8_BAR __builtin_amdgcn_s_barrier()
; template <class Epi, class Sched, bool ALIGN_EPI = false, bool SP2 = false>
; __device__ __forceinline__ void gemm_phase(PG8_LAS unsigned char* lds, const Gemm g, const Sched& S, const Epi& E) {
;     ...
;             const bool last = (t == nt - 2);
;             const char* a1 = cA + (size_t)(t + 1) * kstep;
;             const char* a2 = last ? nA : cA + (size_t)(t + 2) * kstep; const char* b2 = last ? nB : cB + (size_t)(t + 2) * kstep;
;             const char* a3 = a2 + kstep; const char* b3 = b2 + kstep;
;             if constexpr (SP2) {
;             PG8_LDB(B0, 0, 0); PG8_LDB(B1, 0, 1); PG8_SCHED; PG8_LDA(At, 0, 0); PG8_STAGE(PG8_SA(1, 1), a1 + hstep, voffA);
;             PG8_WAIT_V(8); PG8_WAIT_L(0); PG8_BAR; PG8_MMA(0, 0, At, B0); PG8_MMA(0, 1, At, B1); PG8_BAR; PG8_SCHED;
;             PG8_LDA(At, 0, 1); PG8_STAGE(PG8_SB(0, 0), b2, voffB); PG8_STAGE(PG8_SB(0, 1), b2 + hstep, voffB); PG8_STAGE(PG8_SA(0, 0), a2, voffA);
;             PG8_WAIT_V(8); PG8_WAIT_L(0); PG8_BAR; PG8_MMA(1, 0, At, B0); PG8_MMA(1, 1, At, B1); PG8_BAR; PG8_SCHED;
.LBB0_1051:
	ds_read_b128 v[128:131], v205
	ds_read_b128 v[132:135], v205 offset:1024
	ds_read_b128 v[154:157], v205 offset:2048
	ds_read_b128 v[158:161], v205 offset:3072
	ds_read_b128 v[162:165], v206
	ds_read_b128 v[166:169], v206 offset:1024
	ds_read_b128 v[170:173], v206 offset:2048
	ds_read_b128 v[174:177], v206 offset:3072
	s_add_u32 s54, s52, 0xfff80080
	s_addc_u32 s55, s53, -1
	s_cmp_eq_u32 s77, 28
	s_cselect_b32 s57, s43, s55
	s_cselect_b32 s56, s49, s54
	s_cselect_b32 s55, s37, s76
	s_cselect_b32 s54, s51, s75
	s_add_i32 m0, s61, 0xc000
	ds_read_b128 v[178:181], v207
	ds_read_b128 v[182:185], v207 offset:1024
	ds_read_b128 v[186:189], v207 offset:2048
	ds_read_b128 v[190:193], v207 offset:3072
	ds_read_b128 v[194:197], v207 offset:4096
	ds_read_b128 v[198:201], v207 offset:5120
	ds_read_b128 v[210:213], v207 offset:6144
	ds_read_b128 v[214:217], v207 offset:7168
	global_load_lds_dwordx4 v144, s[52:53]
	s_add_i32 m0, s61, 0xe000
	s_nop 0
	global_load_lds_dwordx4 v148, s[52:53]
	s_waitcnt vmcnt(8)
	s_waitcnt lgkmcnt(0)
	s_setprio 1
	s_barrier
	v_mfma_f32_16x16x32_bf16 v[124:127], v[128:131], v[178:181], v[124:127]
	v_mfma_f32_16x16x32_bf16 v[120:123], v[154:157], v[178:181], v[120:123]
	v_mfma_f32_16x16x32_bf16 v[116:119], v[128:131], v[186:189], v[116:119]
	v_mfma_f32_16x16x32_bf16 v[112:115], v[154:157], v[186:189], v[112:115]
	v_mfma_f32_16x16x32_bf16 v[108:111], v[128:131], v[194:197], v[108:111]
	v_mfma_f32_16x16x32_bf16 v[104:107], v[154:157], v[194:197], v[104:107]
	v_mfma_f32_16x16x32_bf16 v[100:103], v[128:131], v[210:213], v[100:103]
	v_mfma_f32_16x16x32_bf16 v[96:99], v[154:157], v[210:213], v[96:99]
	v_mfma_f32_16x16x32_bf16 v[124:127], v[132:135], v[182:185], v[124:127]
	v_mfma_f32_16x16x32_bf16 v[120:123], v[158:161], v[182:185], v[120:123]
	v_mfma_f32_16x16x32_bf16 v[116:119], v[132:135], v[190:193], v[116:119]
	v_mfma_f32_16x16x32_bf16 v[112:115], v[158:161], v[190:193], v[112:115]
	v_mfma_f32_16x16x32_bf16 v[108:111], v[132:135], v[198:201], v[108:111]
	v_mfma_f32_16x16x32_bf16 v[104:107], v[158:161], v[198:201], v[104:107]
	v_mfma_f32_16x16x32_bf16 v[100:103], v[132:135], v[214:217], v[100:103]
	v_mfma_f32_16x16x32_bf16 v[96:99], v[158:161], v[214:217], v[96:99]
	s_setprio 0
	s_setprio 1
	v_mfma_f32_16x16x32_bf16 v[60:63], v[162:165], v[178:181], v[60:63]
	v_mfma_f32_16x16x32_bf16 v[56:59], v[170:173], v[178:181], v[56:59]
	v_mfma_f32_16x16x32_bf16 v[52:55], v[162:165], v[186:189], v[52:55]
	v_mfma_f32_16x16x32_bf16 v[48:51], v[170:173], v[186:189], v[48:51]
	v_mfma_f32_16x16x32_bf16 v[44:47], v[162:165], v[194:197], v[44:47]
	v_mfma_f32_16x16x32_bf16 v[40:43], v[170:173], v[194:197], v[40:43]
	v_mfma_f32_16x16x32_bf16 v[36:39], v[162:165], v[210:213], v[36:39]
	v_mfma_f32_16x16x32_bf16 v[32:35], v[170:173], v[210:213], v[32:35]
	v_mfma_f32_16x16x32_bf16 v[60:63], v[166:169], v[182:185], v[60:63]
	v_mfma_f32_16x16x32_bf16 v[56:59], v[174:177], v[182:185], v[56:59]
	v_mfma_f32_16x16x32_bf16 v[52:55], v[166:169], v[190:193], v[52:55]
	v_mfma_f32_16x16x32_bf16 v[48:51], v[174:177], v[190:193], v[48:51]
	v_mfma_f32_16x16x32_bf16 v[44:47], v[166:169], v[198:201], v[44:47]
	v_mfma_f32_16x16x32_bf16 v[40:43], v[174:177], v[198:201], v[40:43]
	s_setprio 2
	s_barrier
	v_mfma_f32_16x16x32_bf16 v[36:39], v[166:169], v[214:217], v[36:39]
	v_mfma_f32_16x16x32_bf16 v[32:35], v[174:177], v[214:217], v[32:35]
	s_setprio 0
	s_add_i32 s78, s33, s60
	v_lshl_add_u64 v[218:219], s[54:55], 0, v[138:139]
	s_mov_b32 m0, s78
	ds_read_b128 v[178:181], v207 offset:16384
	ds_read_b128 v[182:185], v207 offset:17408
	ds_read_b128 v[186:189], v207 offset:18432
	ds_read_b128 v[190:193], v207 offset:19456
	ds_read_b128 v[194:197], v207 offset:20480
	ds_read_b128 v[198:201], v207 offset:21504
	ds_read_b128 v[210:213], v207 offset:22528
	ds_read_b128 v[214:217], v207 offset:23552
	global_load_lds_dwordx4 v[218:219], off
	s_add_i32 m0, s78, 0x2000
	s_add_u32 s78, s54, 0x80000
	v_lshl_add_u64 v[220:221], s[54:55], 0, v[142:143]
	s_addc_u32 s79, s55, 0
	s_add_i32 s80, s74, s60
	global_load_lds_dwordx4 v[220:221], off
	s_mov_b32 m0, s80
	v_lshl_add_u64 v[224:225], s[56:57], 0, v[140:141]
	global_load_lds_dwordx4 v138, s[78:79]
	s_add_i32 m0, s80, 0x2000
	s_nop 0
	global_load_lds_dwordx4 v142, s[78:79]
	v_lshl_add_u64 v[222:223], s[56:57], 0, v[136:137]
	s_mov_b32 m0, s61
	s_nop 0
	global_load_lds_dwordx4 v[222:223], off
	s_mov_b32 m0, s62
	s_nop 0
	global_load_lds_dwordx4 v[224:225], off
	s_waitcnt vmcnt(8)
	s_waitcnt lgkmcnt(0)
	s_setprio 1
	s_barrier
	v_mfma_f32_16x16x32_bf16 v[92:95], v[128:131], v[178:181], v[92:95]
	v_mfma_f32_16x16x32_bf16 v[88:91], v[154:157], v[178:181], v[88:91]
	v_mfma_f32_16x16x32_bf16 v[84:87], v[128:131], v[186:189], v[84:87]
	v_mfma_f32_16x16x32_bf16 v[80:83], v[154:157], v[186:189], v[80:83]
	v_mfma_f32_16x16x32_bf16 v[76:79], v[128:131], v[194:197], v[76:79]
	v_mfma_f32_16x16x32_bf16 v[72:75], v[154:157], v[194:197], v[72:75]
	v_mfma_f32_16x16x32_bf16 v[68:71], v[128:131], v[210:213], v[68:71]
	v_mfma_f32_16x16x32_bf16 v[64:67], v[154:157], v[210:213], v[64:67]
	v_mfma_f32_16x16x32_bf16 v[92:95], v[132:135], v[182:185], v[92:95]
	v_mfma_f32_16x16x32_bf16 v[88:91], v[158:161], v[182:185], v[88:91]
	v_mfma_f32_16x16x32_bf16 v[84:87], v[132:135], v[190:193], v[84:87]
	v_mfma_f32_16x16x32_bf16 v[80:83], v[158:161], v[190:193], v[80:83]
	v_mfma_f32_16x16x32_bf16 v[76:79], v[132:135], v[198:201], v[76:79]
	v_mfma_f32_16x16x32_bf16 v[72:75], v[158:161], v[198:201], v[72:75]
	v_mfma_f32_16x16x32_bf16 v[68:71], v[132:135], v[214:217], v[68:71]
	v_mfma_f32_16x16x32_bf16 v[64:67], v[158:161], v[214:217], v[64:67]
	s_setprio 0
	s_setprio 1
	v_mfma_f32_16x16x32_bf16 v[28:31], v[162:165], v[178:181], v[28:31]
	v_mfma_f32_16x16x32_bf16 v[24:27], v[170:173], v[178:181], v[24:27]
	v_mfma_f32_16x16x32_bf16 v[20:23], v[162:165], v[186:189], v[20:23]
	v_mfma_f32_16x16x32_bf16 v[16:19], v[170:173], v[186:189], v[16:19]
	v_mfma_f32_16x16x32_bf16 v[12:15], v[162:165], v[194:197], v[12:15]
	v_mfma_f32_16x16x32_bf16 v[8:11], v[170:173], v[194:197], v[8:11]
	v_mfma_f32_16x16x32_bf16 v[4:7], v[162:165], v[210:213], v[4:7]
	v_mfma_f32_16x16x32_bf16 v[0:3], v[170:173], v[210:213], v[0:3]
	v_mfma_f32_16x16x32_bf16 v[28:31], v[166:169], v[182:185], v[28:31]
	v_mfma_f32_16x16x32_bf16 v[24:27], v[174:177], v[182:185], v[24:27]
	v_mfma_f32_16x16x32_bf16 v[20:23], v[166:169], v[190:193], v[20:23]
	v_mfma_f32_16x16x32_bf16 v[16:19], v[174:177], v[190:193], v[16:19]
	v_mfma_f32_16x16x32_bf16 v[12:15], v[166:169], v[198:201], v[12:15]
	v_mfma_f32_16x16x32_bf16 v[8:11], v[174:177], v[198:201], v[8:11]
	s_setprio 2
	s_barrier
; #define PG8_STAGE(bufoff, gbase, voff) do { _Pragma("unroll") for (int _i = 0; _i < 2; ++_i) \
;         __builtin_amdgcn_global_load_lds((const unsigned*)((const char*)(gbase) + (voff)[_i]), (PG8_LAS unsigned*)(lds + (bufoff) + ldsw + _i * 8192), 16, 0, 0); } while (0)
; #define PG8_LDA(dst, b, h) do { _Pragma("unroll") for (int m = 0; m < 4; ++m) _Pragma("unroll") for (int k = 0; k < 2; ++k) dst[m][k] = *(const PG8_LAS bf16x8*)(lds + PG8_SA(b, h) + aoff + m * 2048 + k * 1024); } while (0)
; #define PG8_LDB(dst, b, h) do { _Pragma("unroll") for (int n = 0; n < 2; ++n) _Pragma("unroll") for (int k = 0; k < 2; ++k) dst[n][k] = *(const PG8_LAS bf16x8*)(lds + PG8_SB(b, h) + boff + n * 2048 + k * 1024); } while (0)
; #define PG8_MMA(ai, bj, At, Bt) do { __builtin_amdgcn_s_setprio(1); _Pragma("unroll") for (int m = 0; m < 4; ++m) _Pragma("unroll") for (int n = 0; n < 2; ++n) _Pragma("unroll") for (int k = 0; k < 2; ++k) \
;         acc[ai][bj][m][n] = __builtin_amdgcn_mfma_f32_16x16x32_bf16(Bt[n][k], At[m][k], acc[ai][bj][m][n], 0, 0, 0); __builtin_amdgcn_s_setprio(0); } while (0)
; #define PG8_WAIT_V(n) asm volatile("s_waitcnt vmcnt(" #n ")" ::: "memory")
; #define PG8_WAIT_L(n) asm volatile("s_waitcnt lgkmcnt(" #n ")" ::: "memory")
; #define PG8_BAR __builtin_amdgcn_s_barrier()
; #define PG8_SCHED __builtin_amdgcn_sched_barrier(0)
; template <class Epi, class Sched, bool ALIGN_EPI = false, bool SP2 = false>
; __device__ __forceinline__ void gemm_phase(PG8_LAS unsigned char* lds, const Gemm g, const Sched& S, const Epi& E) {
;     ...
;             PG8_LDB(B0, 1, 0); PG8_LDB(B1, 1, 1); PG8_SCHED; PG8_LDA(At, 1, 0); PG8_STAGE(PG8_SA(0, 1), a2 + hstep, voffA);
;             PG8_WAIT_V(8); PG8_WAIT_L(0); PG8_BAR; PG8_MMA(0, 0, At, B0); PG8_MMA(0, 1, At, B1); PG8_BAR; PG8_SCHED;
	v_mfma_f32_16x16x32_bf16 v[4:7], v[166:169], v[214:217], v[4:7]
	v_mfma_f32_16x16x32_bf16 v[0:3], v[174:177], v[214:217], v[0:3]
	s_setprio 0
	s_add_i32 s78, 0, 0x18000
	s_add_i32 s79, 0, 0x1c000
	v_add_u32_e32 v158, s78, v203
	v_add_u32_e32 v174, s79, v203
	ds_read_b128 v[128:131], v158
	ds_read_b128 v[132:135], v158 offset:1024
	ds_read_b128 v[154:157], v158 offset:2048
	ds_read_b128 v[158:161], v158 offset:3072
	ds_read_b128 v[162:165], v174
	ds_read_b128 v[166:169], v174 offset:1024
	ds_read_b128 v[170:173], v174 offset:2048
	ds_read_b128 v[174:177], v174 offset:3072
	s_add_u32 s56, s56, 0x80000
	s_addc_u32 s57, s57, 0
	s_mov_b32 m0, s63
	ds_read_b128 v[178:181], v207 offset:32768
	ds_read_b128 v[182:185], v207 offset:33792
	ds_read_b128 v[186:189], v207 offset:34816
	ds_read_b128 v[190:193], v207 offset:35840
	ds_read_b128 v[194:197], v207 offset:36864
	ds_read_b128 v[198:201], v207 offset:37888
	ds_read_b128 v[210:213], v207 offset:38912
	ds_read_b128 v[214:217], v207 offset:39936
	global_load_lds_dwordx4 v136, s[56:57]
	s_mov_b32 m0, s64
	s_nop 0
	global_load_lds_dwordx4 v140, s[56:57]
	s_waitcnt vmcnt(8)
	s_waitcnt lgkmcnt(0)
	s_setprio 1
	s_barrier
	v_mfma_f32_16x16x32_bf16 v[124:127], v[128:131], v[178:181], v[124:127]
	v_mfma_f32_16x16x32_bf16 v[120:123], v[154:157], v[178:181], v[120:123]
	v_mfma_f32_16x16x32_bf16 v[116:119], v[128:131], v[186:189], v[116:119]
	v_mfma_f32_16x16x32_bf16 v[112:115], v[154:157], v[186:189], v[112:115]
	v_mfma_f32_16x16x32_bf16 v[108:111], v[128:131], v[194:197], v[108:111]
	v_mfma_f32_16x16x32_bf16 v[104:107], v[154:157], v[194:197], v[104:107]
	v_mfma_f32_16x16x32_bf16 v[100:103], v[128:131], v[210:213], v[100:103]
	v_mfma_f32_16x16x32_bf16 v[96:99], v[154:157], v[210:213], v[96:99]
	v_mfma_f32_16x16x32_bf16 v[124:127], v[132:135], v[182:185], v[124:127]
	v_mfma_f32_16x16x32_bf16 v[120:123], v[158:161], v[182:185], v[120:123]
	v_mfma_f32_16x16x32_bf16 v[116:119], v[132:135], v[190:193], v[116:119]
	v_mfma_f32_16x16x32_bf16 v[112:115], v[158:161], v[190:193], v[112:115]
	v_mfma_f32_16x16x32_bf16 v[108:111], v[132:135], v[198:201], v[108:111]
	v_mfma_f32_16x16x32_bf16 v[104:107], v[158:161], v[198:201], v[104:107]
	v_mfma_f32_16x16x32_bf16 v[100:103], v[132:135], v[214:217], v[100:103]
	v_mfma_f32_16x16x32_bf16 v[96:99], v[158:161], v[214:217], v[96:99]
	s_setprio 0
	s_setprio 1
	v_mfma_f32_16x16x32_bf16 v[60:63], v[162:165], v[178:181], v[60:63]
	v_mfma_f32_16x16x32_bf16 v[56:59], v[170:173], v[178:181], v[56:59]
	v_mfma_f32_16x16x32_bf16 v[52:55], v[162:165], v[186:189], v[52:55]
	v_mfma_f32_16x16x32_bf16 v[48:51], v[170:173], v[186:189], v[48:51]
	v_mfma_f32_16x16x32_bf16 v[44:47], v[162:165], v[194:197], v[44:47]
	v_mfma_f32_16x16x32_bf16 v[40:43], v[170:173], v[194:197], v[40:43]
	v_mfma_f32_16x16x32_bf16 v[36:39], v[162:165], v[210:213], v[36:39]
	v_mfma_f32_16x16x32_bf16 v[32:35], v[170:173], v[210:213], v[32:35]
	v_mfma_f32_16x16x32_bf16 v[60:63], v[166:169], v[182:185], v[60:63]
	v_mfma_f32_16x16x32_bf16 v[56:59], v[174:177], v[182:185], v[56:59]
	v_mfma_f32_16x16x32_bf16 v[52:55], v[166:169], v[190:193], v[52:55]
	v_mfma_f32_16x16x32_bf16 v[48:51], v[174:177], v[190:193], v[48:51]
	v_mfma_f32_16x16x32_bf16 v[44:47], v[166:169], v[198:201], v[44:47]
	v_mfma_f32_16x16x32_bf16 v[40:43], v[174:177], v[198:201], v[40:43]
	s_setprio 2
	s_barrier
; #define PG8_STAGE(bufoff, gbase, voff) do { _Pragma("unroll") for (int _i = 0; _i < 2; ++_i) \
;         __builtin_amdgcn_global_load_lds((const unsigned*)((const char*)(gbase) + (voff)[_i]), (PG8_LAS unsigned*)(lds + (bufoff) + ldsw + _i * 8192), 16, 0, 0); } while (0)
; #define PG8_LDA(dst, b, h) do { _Pragma("unroll") for (int m = 0; m < 4; ++m) _Pragma("unroll") for (int k = 0; k < 2; ++k) dst[m][k] = *(const PG8_LAS bf16x8*)(lds + PG8_SA(b, h) + aoff + m * 2048 + k * 1024); } while (0)
; #define PG8_MMA(ai, bj, At, Bt) do { __builtin_amdgcn_s_setprio(1); _Pragma("unroll") for (int m = 0; m < 4; ++m) _Pragma("unroll") for (int n = 0; n < 2; ++n) _Pragma("unroll") for (int k = 0; k < 2; ++k) \
;         acc[ai][bj][m][n] = __builtin_amdgcn_mfma_f32_16x16x32_bf16(Bt[n][k], At[m][k], acc[ai][bj][m][n], 0, 0, 0); __builtin_amdgcn_s_setprio(0); } while (0)
; #define PG8_WAIT_V(n) asm volatile("s_waitcnt vmcnt(" #n ")" ::: "memory")
; #define PG8_WAIT_L(n) asm volatile("s_waitcnt lgkmcnt(" #n ")" ::: "memory")
; #define PG8_BAR __builtin_amdgcn_s_barrier()
; #define PG8_SCHED __builtin_amdgcn_sched_barrier(0)
; template <class Epi, class Sched, bool ALIGN_EPI = false, bool SP2 = false>
; __device__ __forceinline__ void gemm_phase(PG8_LAS unsigned char* lds, const Gemm g, const Sched& S, const Epi& E) {
;     ...
;             PG8_LDA(At, 1, 1); PG8_STAGE(PG8_SB(1, 0), b3, voffB); PG8_STAGE(PG8_SB(1, 1), b3 + hstep, voffB); PG8_STAGE(PG8_SA(1, 0), a3, voffA);
;             PG8_WAIT_V(8); PG8_WAIT_L(0); PG8_BAR; PG8_MMA(1, 0, At, B0); PG8_MMA(1, 1, At, B1); PG8_BAR; PG8_SCHED;
;     ...
;         if constexpr (ALIGN_EPI) { if (wr == 0) PG8_BAR; }
	v_mfma_f32_16x16x32_bf16 v[36:39], v[166:169], v[214:217], v[36:39]
	v_mfma_f32_16x16x32_bf16 v[32:35], v[174:177], v[214:217], v[32:35]
	s_setprio 0
	s_add_i32 s56, s78, s60
	v_lshl_add_u64 v[218:219], v[218:219], 0, s[12:13]
	s_mov_b32 m0, s56
	ds_read_b128 v[178:181], v207 offset:49152
	ds_read_b128 v[182:185], v207 offset:50176
	ds_read_b128 v[186:189], v207 offset:51200
	ds_read_b128 v[190:193], v207 offset:52224
	ds_read_b128 v[194:197], v207 offset:53248
	ds_read_b128 v[198:201], v207 offset:54272
	ds_read_b128 v[210:213], v207 offset:55296
	ds_read_b128 v[214:217], v207 offset:56320
	global_load_lds_dwordx4 v[218:219], off
	s_add_i32 m0, s56, 0x2000
	s_add_u32 s54, s54, 0x80080
	v_lshl_add_u64 v[218:219], v[220:221], 0, s[12:13]
	s_addc_u32 s55, s55, 0
	s_add_i32 s56, s79, s60
	global_load_lds_dwordx4 v[218:219], off
	s_mov_b32 m0, s56
	s_nop 0
	global_load_lds_dwordx4 v138, s[54:55]
	s_add_i32 m0, s56, 0x2000
	s_nop 0
	global_load_lds_dwordx4 v142, s[54:55]
	v_lshl_add_u64 v[218:219], v[222:223], 0, s[12:13]
	s_mov_b32 m0, s70
	s_nop 0
	global_load_lds_dwordx4 v[218:219], off
	v_lshl_add_u64 v[218:219], v[224:225], 0, s[12:13]
	s_mov_b32 m0, s71
	s_nop 0
	global_load_lds_dwordx4 v[218:219], off
	s_waitcnt vmcnt(8)
	s_waitcnt lgkmcnt(0)
	s_setprio 1
	s_barrier
	v_mfma_f32_16x16x32_bf16 v[92:95], v[128:131], v[178:181], v[92:95]
	v_mfma_f32_16x16x32_bf16 v[88:91], v[154:157], v[178:181], v[88:91]
	v_mfma_f32_16x16x32_bf16 v[84:87], v[128:131], v[186:189], v[84:87]
	v_mfma_f32_16x16x32_bf16 v[80:83], v[154:157], v[186:189], v[80:83]
	v_mfma_f32_16x16x32_bf16 v[76:79], v[128:131], v[194:197], v[76:79]
	v_mfma_f32_16x16x32_bf16 v[72:75], v[154:157], v[194:197], v[72:75]
	v_mfma_f32_16x16x32_bf16 v[68:71], v[128:131], v[210:213], v[68:71]
	v_mfma_f32_16x16x32_bf16 v[64:67], v[154:157], v[210:213], v[64:67]
	v_mfma_f32_16x16x32_bf16 v[92:95], v[132:135], v[182:185], v[92:95]
	v_mfma_f32_16x16x32_bf16 v[88:91], v[158:161], v[182:185], v[88:91]
	v_mfma_f32_16x16x32_bf16 v[84:87], v[132:135], v[190:193], v[84:87]
	v_mfma_f32_16x16x32_bf16 v[80:83], v[158:161], v[190:193], v[80:83]
	v_mfma_f32_16x16x32_bf16 v[76:79], v[132:135], v[198:201], v[76:79]
	v_mfma_f32_16x16x32_bf16 v[72:75], v[158:161], v[198:201], v[72:75]
	v_mfma_f32_16x16x32_bf16 v[68:71], v[132:135], v[214:217], v[68:71]
	v_mfma_f32_16x16x32_bf16 v[64:67], v[158:161], v[214:217], v[64:67]
	s_setprio 0
	s_setprio 1
	v_mfma_f32_16x16x32_bf16 v[28:31], v[162:165], v[178:181], v[28:31]
	v_mfma_f32_16x16x32_bf16 v[24:27], v[170:173], v[178:181], v[24:27]
	v_mfma_f32_16x16x32_bf16 v[20:23], v[162:165], v[186:189], v[20:23]
	v_mfma_f32_16x16x32_bf16 v[16:19], v[170:173], v[186:189], v[16:19]
	v_mfma_f32_16x16x32_bf16 v[12:15], v[162:165], v[194:197], v[12:15]
	v_mfma_f32_16x16x32_bf16 v[8:11], v[170:173], v[194:197], v[8:11]
	v_mfma_f32_16x16x32_bf16 v[4:7], v[162:165], v[210:213], v[4:7]
	v_mfma_f32_16x16x32_bf16 v[0:3], v[170:173], v[210:213], v[0:3]
	v_mfma_f32_16x16x32_bf16 v[28:31], v[166:169], v[182:185], v[28:31]
	v_mfma_f32_16x16x32_bf16 v[24:27], v[174:177], v[182:185], v[24:27]
	v_mfma_f32_16x16x32_bf16 v[20:23], v[166:169], v[190:193], v[20:23]
	v_mfma_f32_16x16x32_bf16 v[16:19], v[174:177], v[190:193], v[16:19]
	v_mfma_f32_16x16x32_bf16 v[12:15], v[166:169], v[198:201], v[12:15]
	v_mfma_f32_16x16x32_bf16 v[8:11], v[174:177], v[198:201], v[8:11]
	s_setprio 2
	s_barrier
	v_mfma_f32_16x16x32_bf16 v[4:7], v[166:169], v[214:217], v[4:7]
	v_mfma_f32_16x16x32_bf16 v[0:3], v[174:177], v[214:217], v[0:3]
	s_setprio 0
	s_add_i32 s77, s77, 2
	s_add_u32 s52, s52, 0x100
	s_addc_u32 s53, s53, 0
	s_add_u32 s75, s75, 0x100
	s_addc_u32 s76, s76, 0
	s_cmp_gt_u32 s77, 29
	s_cbranch_scc0 .LBB0_1051
	s_and_b64 vcc, exec, s[14:15]
	s_cbranch_vccz .LBB0_1054
	s_barrier

; #define PG8_STAGE(bufoff, gbase, voff) do { _Pragma("unroll") for (int _i = 0; _i < 2; ++_i) \
;         __builtin_amdgcn_global_load_lds((const unsigned*)((const char*)(gbase) + (voff)[_i]), (PG8_LAS unsigned*)(lds + (bufoff) + ldsw + _i * 8192), 16, 0, 0); } while (0)
; #define PG8_LDA(dst, b, h) do { _Pragma("unroll") for (int m = 0; m < 4; ++m) _Pragma("unroll") for (int k = 0; k < 2; ++k) dst[m][k] = *(const PG8_LAS bf16x8*)(lds + PG8_SA(b, h) + aoff + m * 2048 + k * 1024); } while (0)
; #define PG8_LDB(dst, b, h) do { _Pragma("unroll") for (int n = 0; n < 2; ++n) _Pragma("unroll") for (int k = 0; k < 2; ++k) dst[n][k] = *(const PG8_LAS bf16x8*)(lds + PG8_SB(b, h) + boff + n * 2048 + k * 1024); } while (0)
; #define PG8_MMA(ai, bj, At, Bt) do { __builtin_amdgcn_s_setprio(1); _Pragma("unroll") for (int m = 0; m < 4; ++m) _Pragma("unroll") for (int n = 0; n < 2; ++n) _Pragma("unroll") for (int k = 0; k < 2; ++k) \
;         acc[ai][bj][m][n] = __builtin_amdgcn_mfma_f32_16x16x32_bf16(Bt[n][k], At[m][k], acc[ai][bj][m][n], 0, 0, 0); __builtin_amdgcn_s_setprio(0); } while (0)
; #define PG8_WAIT_V(n) asm volatile("s_waitcnt vmcnt(" #n ")" ::: "memory")
; #define PG8_WAIT_L(n) asm volatile("s_waitcnt lgkmcnt(" #n ")" ::: "memory")
; #define PG8_BAR __builtin_amdgcn_s_barrier()
; template <class Epi, class Sched, bool ALIGN_EPI = false, bool SP2 = false>
; __device__ __forceinline__ void gemm_phase(PG8_LAS unsigned char* lds, const Gemm g, const Sched& S, const Epi& E) {
;     ...
;             const bool last = (t == nt - 2);
;             const char* a1 = cA + (size_t)(t + 1) * kstep;
;             const char* a2 = last ? nA : cA + (size_t)(t + 2) * kstep; const char* b2 = last ? nB : cB + (size_t)(t + 2) * kstep;
;             const char* a3 = a2 + kstep; const char* b3 = b2 + kstep;
;             if constexpr (SP2) {
;             PG8_LDB(B0, 0, 0); PG8_LDB(B1, 0, 1); PG8_SCHED; PG8_LDA(At, 0, 0); PG8_STAGE(PG8_SA(1, 1), a1 + hstep, voffA);
;             PG8_WAIT_V(8); PG8_WAIT_L(0); PG8_BAR; PG8_MMA(0, 0, At, B0); PG8_MMA(0, 1, At, B1); PG8_BAR; PG8_SCHED;
;             PG8_LDA(At, 0, 1); PG8_STAGE(PG8_SB(0, 0), b2, voffB); PG8_STAGE(PG8_SB(0, 1), b2 + hstep, voffB); PG8_STAGE(PG8_SA(0, 0), a2, voffA);
;             PG8_WAIT_V(8); PG8_WAIT_L(0); PG8_BAR; PG8_MMA(1, 0, At, B0); PG8_MMA(1, 1, At, B1); PG8_BAR; PG8_SCHED;
.LBB0_1142:
	ds_read_b128 v[80:83], v171
	ds_read_b128 v[84:87], v171 offset:1024
	ds_read_b128 v[88:91], v171 offset:2048
	ds_read_b128 v[92:95], v171 offset:3072
	ds_read_b128 v[164:167], v172
	ds_read_b128 v[176:179], v172 offset:1024
	ds_read_b128 v[180:183], v172 offset:2048
	ds_read_b128 v[184:187], v172 offset:3072
	s_add_u32 s44, s42, 0xfff80080
	s_addc_u32 s45, s43, -1
	s_cmp_eq_u32 s64, 28
	s_cselect_b32 s47, s15, s45
	s_cselect_b32 s46, s60, s44
	s_cselect_b32 s45, s13, s63
	s_cselect_b32 s44, s61, s62
	s_add_i32 m0, s41, 0xc000
	ds_read_b128 v[188:191], v173
	ds_read_b128 v[192:195], v173 offset:1024
	ds_read_b128 v[196:199], v173 offset:2048
	ds_read_b128 v[200:203], v173 offset:3072
	ds_read_b128 v[204:207], v173 offset:4096
	ds_read_b128 v[208:211], v173 offset:5120
	ds_read_b128 v[212:215], v173 offset:6144
	ds_read_b128 v[216:219], v173 offset:7168
	global_load_lds_dwordx4 v156, s[42:43]
	s_add_i32 m0, s41, 0xe000
	s_nop 0
	global_load_lds_dwordx4 v158, s[42:43]
	s_waitcnt vmcnt(8)
	s_waitcnt lgkmcnt(0)
	s_setprio 1
	s_barrier
	v_mfma_f32_16x16x32_bf16 v[140:143], v[80:83], v[188:191], v[140:143]
	v_mfma_f32_16x16x32_bf16 v[136:139], v[88:91], v[188:191], v[136:139]
	v_mfma_f32_16x16x32_bf16 v[124:127], v[80:83], v[196:199], v[124:127]
	v_mfma_f32_16x16x32_bf16 v[120:123], v[88:91], v[196:199], v[120:123]
	v_mfma_f32_16x16x32_bf16 v[108:111], v[80:83], v[204:207], v[108:111]
	v_mfma_f32_16x16x32_bf16 v[104:107], v[88:91], v[204:207], v[104:107]
	v_mfma_f32_16x16x32_bf16 v[76:79], v[80:83], v[212:215], v[76:79]
	v_mfma_f32_16x16x32_bf16 v[72:75], v[88:91], v[212:215], v[72:75]
	v_mfma_f32_16x16x32_bf16 v[140:143], v[84:87], v[192:195], v[140:143]
	v_mfma_f32_16x16x32_bf16 v[136:139], v[92:95], v[192:195], v[136:139]
	v_mfma_f32_16x16x32_bf16 v[124:127], v[84:87], v[200:203], v[124:127]
	v_mfma_f32_16x16x32_bf16 v[120:123], v[92:95], v[200:203], v[120:123]
	v_mfma_f32_16x16x32_bf16 v[108:111], v[84:87], v[208:211], v[108:111]
	v_mfma_f32_16x16x32_bf16 v[104:107], v[92:95], v[208:211], v[104:107]
	v_mfma_f32_16x16x32_bf16 v[76:79], v[84:87], v[216:219], v[76:79]
	v_mfma_f32_16x16x32_bf16 v[72:75], v[92:95], v[216:219], v[72:75]
	s_setprio 0
	s_setprio 1
	v_mfma_f32_16x16x32_bf16 v[132:135], v[164:167], v[188:191], v[132:135]
	v_mfma_f32_16x16x32_bf16 v[128:131], v[180:183], v[188:191], v[128:131]
	v_mfma_f32_16x16x32_bf16 v[116:119], v[164:167], v[196:199], v[116:119]
	v_mfma_f32_16x16x32_bf16 v[112:115], v[180:183], v[196:199], v[112:115]
	v_mfma_f32_16x16x32_bf16 v[100:103], v[164:167], v[204:207], v[100:103]
	v_mfma_f32_16x16x32_bf16 v[96:99], v[180:183], v[204:207], v[96:99]
	v_mfma_f32_16x16x32_bf16 v[68:71], v[164:167], v[212:215], v[68:71]
	v_mfma_f32_16x16x32_bf16 v[64:67], v[180:183], v[212:215], v[64:67]
	v_mfma_f32_16x16x32_bf16 v[132:135], v[176:179], v[192:195], v[132:135]
	v_mfma_f32_16x16x32_bf16 v[128:131], v[184:187], v[192:195], v[128:131]
	v_mfma_f32_16x16x32_bf16 v[116:119], v[176:179], v[200:203], v[116:119]
	v_mfma_f32_16x16x32_bf16 v[112:115], v[184:187], v[200:203], v[112:115]
	v_mfma_f32_16x16x32_bf16 v[100:103], v[176:179], v[208:211], v[100:103]
	v_mfma_f32_16x16x32_bf16 v[96:99], v[184:187], v[208:211], v[96:99]
	s_setprio 2
	s_barrier
	v_mfma_f32_16x16x32_bf16 v[68:71], v[176:179], v[216:219], v[68:71]
	v_mfma_f32_16x16x32_bf16 v[64:67], v[184:187], v[216:219], v[64:67]
	s_setprio 0
	s_add_i32 s65, s56, s33
	v_lshl_add_u64 v[220:221], s[44:45], 0, v[148:149]
	s_mov_b32 m0, s65
	ds_read_b128 v[188:191], v173 offset:16384
	ds_read_b128 v[192:195], v173 offset:17408
	ds_read_b128 v[196:199], v173 offset:18432
	ds_read_b128 v[200:203], v173 offset:19456
	ds_read_b128 v[204:207], v173 offset:20480
	ds_read_b128 v[208:211], v173 offset:21504
	ds_read_b128 v[212:215], v173 offset:22528
	ds_read_b128 v[216:219], v173 offset:23552
	global_load_lds_dwordx4 v[220:221], off
	s_add_i32 m0, s65, 0x2000
	s_add_u32 s66, s44, 0x80000
	v_lshl_add_u64 v[222:223], s[44:45], 0, v[152:153]
	s_addc_u32 s67, s45, 0
	s_add_i32 s65, s57, s33
	global_load_lds_dwordx4 v[222:223], off
	s_mov_b32 m0, s65
	v_lshl_add_u64 v[226:227], s[46:47], 0, v[150:151]
	global_load_lds_dwordx4 v148, s[66:67]
	s_add_i32 m0, s65, 0x2000
	s_nop 0
	global_load_lds_dwordx4 v152, s[66:67]
	v_lshl_add_u64 v[224:225], s[46:47], 0, v[144:145]
	s_mov_b32 m0, s41
	s_nop 0
	global_load_lds_dwordx4 v[224:225], off
	s_mov_b32 m0, s48
	s_nop 0
	global_load_lds_dwordx4 v[226:227], off
	s_waitcnt vmcnt(8)
	s_waitcnt lgkmcnt(0)
	s_setprio 1
	s_barrier
	v_mfma_f32_16x16x32_bf16 v[60:63], v[80:83], v[188:191], v[60:63]
	v_mfma_f32_16x16x32_bf16 v[56:59], v[88:91], v[188:191], v[56:59]
	v_mfma_f32_16x16x32_bf16 v[44:47], v[80:83], v[196:199], v[44:47]
	v_mfma_f32_16x16x32_bf16 v[40:43], v[88:91], v[196:199], v[40:43]
	v_mfma_f32_16x16x32_bf16 v[28:31], v[80:83], v[204:207], v[28:31]
	v_mfma_f32_16x16x32_bf16 v[24:27], v[88:91], v[204:207], v[24:27]
	v_mfma_f32_16x16x32_bf16 v[12:15], v[80:83], v[212:215], v[12:15]
	v_mfma_f32_16x16x32_bf16 v[8:11], v[88:91], v[212:215], v[8:11]
	v_mfma_f32_16x16x32_bf16 v[60:63], v[84:87], v[192:195], v[60:63]
	v_mfma_f32_16x16x32_bf16 v[56:59], v[92:95], v[192:195], v[56:59]
	v_mfma_f32_16x16x32_bf16 v[44:47], v[84:87], v[200:203], v[44:47]
	v_mfma_f32_16x16x32_bf16 v[40:43], v[92:95], v[200:203], v[40:43]
	v_mfma_f32_16x16x32_bf16 v[28:31], v[84:87], v[208:211], v[28:31]
	v_mfma_f32_16x16x32_bf16 v[24:27], v[92:95], v[208:211], v[24:27]
	v_mfma_f32_16x16x32_bf16 v[12:15], v[84:87], v[216:219], v[12:15]
	v_mfma_f32_16x16x32_bf16 v[8:11], v[92:95], v[216:219], v[8:11]
	s_setprio 0
	s_setprio 1
	v_mfma_f32_16x16x32_bf16 v[52:55], v[164:167], v[188:191], v[52:55]
	v_mfma_f32_16x16x32_bf16 v[48:51], v[180:183], v[188:191], v[48:51]
	v_mfma_f32_16x16x32_bf16 v[36:39], v[164:167], v[196:199], v[36:39]
	v_mfma_f32_16x16x32_bf16 v[32:35], v[180:183], v[196:199], v[32:35]
	v_mfma_f32_16x16x32_bf16 v[20:23], v[164:167], v[204:207], v[20:23]
	v_mfma_f32_16x16x32_bf16 v[16:19], v[180:183], v[204:207], v[16:19]
	v_mfma_f32_16x16x32_bf16 v[4:7], v[164:167], v[212:215], v[4:7]
	v_mfma_f32_16x16x32_bf16 v[0:3], v[180:183], v[212:215], v[0:3]
	v_mfma_f32_16x16x32_bf16 v[52:55], v[176:179], v[192:195], v[52:55]
	v_mfma_f32_16x16x32_bf16 v[48:51], v[184:187], v[192:195], v[48:51]
	v_mfma_f32_16x16x32_bf16 v[36:39], v[176:179], v[200:203], v[36:39]
	v_mfma_f32_16x16x32_bf16 v[32:35], v[184:187], v[200:203], v[32:35]
	v_mfma_f32_16x16x32_bf16 v[20:23], v[176:179], v[208:211], v[20:23]
	v_mfma_f32_16x16x32_bf16 v[16:19], v[184:187], v[208:211], v[16:19]
	s_setprio 2
	s_barrier
; #define PG8_STAGE(bufoff, gbase, voff) do { _Pragma("unroll") for (int _i = 0; _i < 2; ++_i) \
;         __builtin_amdgcn_global_load_lds((const unsigned*)((const char*)(gbase) + (voff)[_i]), (PG8_LAS unsigned*)(lds + (bufoff) + ldsw + _i * 8192), 16, 0, 0); } while (0)
; #define PG8_LDA(dst, b, h) do { _Pragma("unroll") for (int m = 0; m < 4; ++m) _Pragma("unroll") for (int k = 0; k < 2; ++k) dst[m][k] = *(const PG8_LAS bf16x8*)(lds + PG8_SA(b, h) + aoff + m * 2048 + k * 1024); } while (0)
; #define PG8_LDB(dst, b, h) do { _Pragma("unroll") for (int n = 0; n < 2; ++n) _Pragma("unroll") for (int k = 0; k < 2; ++k) dst[n][k] = *(const PG8_LAS bf16x8*)(lds + PG8_SB(b, h) + boff + n * 2048 + k * 1024); } while (0)
; #define PG8_MMA(ai, bj, At, Bt) do { __builtin_amdgcn_s_setprio(1); _Pragma("unroll") for (int m = 0; m < 4; ++m) _Pragma("unroll") for (int n = 0; n < 2; ++n) _Pragma("unroll") for (int k = 0; k < 2; ++k) \
;         acc[ai][bj][m][n] = __builtin_amdgcn_mfma_f32_16x16x32_bf16(Bt[n][k], At[m][k], acc[ai][bj][m][n], 0, 0, 0); __builtin_amdgcn_s_setprio(0); } while (0)
; #define PG8_WAIT_V(n) asm volatile("s_waitcnt vmcnt(" #n ")" ::: "memory")
; #define PG8_WAIT_L(n) asm volatile("s_waitcnt lgkmcnt(" #n ")" ::: "memory")
; #define PG8_BAR __builtin_amdgcn_s_barrier()
; #define PG8_SCHED __builtin_amdgcn_sched_barrier(0)
; template <class Epi, class Sched, bool ALIGN_EPI = false, bool SP2 = false>
; __device__ __forceinline__ void gemm_phase(PG8_LAS unsigned char* lds, const Gemm g, const Sched& S, const Epi& E) {
;     ...
;             PG8_LDB(B0, 1, 0); PG8_LDB(B1, 1, 1); PG8_SCHED; PG8_LDA(At, 1, 0); PG8_STAGE(PG8_SA(0, 1), a2 + hstep, voffA);
;             PG8_WAIT_V(8); PG8_WAIT_L(0); PG8_BAR; PG8_MMA(0, 0, At, B0); PG8_MMA(0, 1, At, B1); PG8_BAR; PG8_SCHED;
	v_mfma_f32_16x16x32_bf16 v[4:7], v[176:179], v[216:219], v[4:7]
	v_mfma_f32_16x16x32_bf16 v[0:3], v[184:187], v[216:219], v[0:3]
	s_setprio 0
	s_add_i32 s65, 0, 0x18000
	s_add_i32 s66, 0, 0x1c000
	v_add_u32_e32 v92, s65, v169
	v_add_u32_e32 v184, s66, v169
	ds_read_b128 v[80:83], v92
	ds_read_b128 v[84:87], v92 offset:1024
	ds_read_b128 v[88:91], v92 offset:2048
	ds_read_b128 v[92:95], v92 offset:3072
	ds_read_b128 v[164:167], v184
	ds_read_b128 v[176:179], v184 offset:1024
	ds_read_b128 v[180:183], v184 offset:2048
	ds_read_b128 v[184:187], v184 offset:3072
	s_add_u32 s46, s46, 0x80000
	s_addc_u32 s47, s47, 0
	s_mov_b32 m0, s49
	ds_read_b128 v[188:191], v173 offset:32768
	ds_read_b128 v[192:195], v173 offset:33792
	ds_read_b128 v[196:199], v173 offset:34816
	ds_read_b128 v[200:203], v173 offset:35840
	ds_read_b128 v[204:207], v173 offset:36864
	ds_read_b128 v[208:211], v173 offset:37888
	ds_read_b128 v[212:215], v173 offset:38912
	ds_read_b128 v[216:219], v173 offset:39936
	global_load_lds_dwordx4 v144, s[46:47]
	s_mov_b32 m0, s50
	s_nop 0
	global_load_lds_dwordx4 v150, s[46:47]
	s_waitcnt vmcnt(8)
	s_waitcnt lgkmcnt(0)
	s_setprio 1
	s_barrier
	v_mfma_f32_16x16x32_bf16 v[140:143], v[80:83], v[188:191], v[140:143]
	v_mfma_f32_16x16x32_bf16 v[136:139], v[88:91], v[188:191], v[136:139]
	v_mfma_f32_16x16x32_bf16 v[124:127], v[80:83], v[196:199], v[124:127]
	v_mfma_f32_16x16x32_bf16 v[120:123], v[88:91], v[196:199], v[120:123]
	v_mfma_f32_16x16x32_bf16 v[108:111], v[80:83], v[204:207], v[108:111]
	v_mfma_f32_16x16x32_bf16 v[104:107], v[88:91], v[204:207], v[104:107]
	v_mfma_f32_16x16x32_bf16 v[76:79], v[80:83], v[212:215], v[76:79]
	v_mfma_f32_16x16x32_bf16 v[72:75], v[88:91], v[212:215], v[72:75]
	v_mfma_f32_16x16x32_bf16 v[140:143], v[84:87], v[192:195], v[140:143]
	v_mfma_f32_16x16x32_bf16 v[136:139], v[92:95], v[192:195], v[136:139]
	v_mfma_f32_16x16x32_bf16 v[124:127], v[84:87], v[200:203], v[124:127]
	v_mfma_f32_16x16x32_bf16 v[120:123], v[92:95], v[200:203], v[120:123]
	v_mfma_f32_16x16x32_bf16 v[108:111], v[84:87], v[208:211], v[108:111]
	v_mfma_f32_16x16x32_bf16 v[104:107], v[92:95], v[208:211], v[104:107]
	v_mfma_f32_16x16x32_bf16 v[76:79], v[84:87], v[216:219], v[76:79]
	v_mfma_f32_16x16x32_bf16 v[72:75], v[92:95], v[216:219], v[72:75]
	s_setprio 0
	s_setprio 1
	v_mfma_f32_16x16x32_bf16 v[132:135], v[164:167], v[188:191], v[132:135]
	v_mfma_f32_16x16x32_bf16 v[128:131], v[180:183], v[188:191], v[128:131]
	v_mfma_f32_16x16x32_bf16 v[116:119], v[164:167], v[196:199], v[116:119]
	v_mfma_f32_16x16x32_bf16 v[112:115], v[180:183], v[196:199], v[112:115]
	v_mfma_f32_16x16x32_bf16 v[100:103], v[164:167], v[204:207], v[100:103]
	v_mfma_f32_16x16x32_bf16 v[96:99], v[180:183], v[204:207], v[96:99]
	v_mfma_f32_16x16x32_bf16 v[68:71], v[164:167], v[212:215], v[68:71]
	v_mfma_f32_16x16x32_bf16 v[64:67], v[180:183], v[212:215], v[64:67]
	v_mfma_f32_16x16x32_bf16 v[132:135], v[176:179], v[192:195], v[132:135]
	v_mfma_f32_16x16x32_bf16 v[128:131], v[184:187], v[192:195], v[128:131]
	v_mfma_f32_16x16x32_bf16 v[116:119], v[176:179], v[200:203], v[116:119]
	v_mfma_f32_16x16x32_bf16 v[112:115], v[184:187], v[200:203], v[112:115]
	v_mfma_f32_16x16x32_bf16 v[100:103], v[176:179], v[208:211], v[100:103]
	v_mfma_f32_16x16x32_bf16 v[96:99], v[184:187], v[208:211], v[96:99]
	s_setprio 2
	s_barrier
; #define PG8_STAGE(bufoff, gbase, voff) do { _Pragma("unroll") for (int _i = 0; _i < 2; ++_i) \
;         __builtin_amdgcn_global_load_lds((const unsigned*)((const char*)(gbase) + (voff)[_i]), (PG8_LAS unsigned*)(lds + (bufoff) + ldsw + _i * 8192), 16, 0, 0); } while (0)
; #define PG8_LDA(dst, b, h) do { _Pragma("unroll") for (int m = 0; m < 4; ++m) _Pragma("unroll") for (int k = 0; k < 2; ++k) dst[m][k] = *(const PG8_LAS bf16x8*)(lds + PG8_SA(b, h) + aoff + m * 2048 + k * 1024); } while (0)
; #define PG8_MMA(ai, bj, At, Bt) do { __builtin_amdgcn_s_setprio(1); _Pragma("unroll") for (int m = 0; m < 4; ++m) _Pragma("unroll") for (int n = 0; n < 2; ++n) _Pragma("unroll") for (int k = 0; k < 2; ++k) \
;         acc[ai][bj][m][n] = __builtin_amdgcn_mfma_f32_16x16x32_bf16(Bt[n][k], At[m][k], acc[ai][bj][m][n], 0, 0, 0); __builtin_amdgcn_s_setprio(0); } while (0)
; #define PG8_WAIT_V(n) asm volatile("s_waitcnt vmcnt(" #n ")" ::: "memory")
; #define PG8_WAIT_L(n) asm volatile("s_waitcnt lgkmcnt(" #n ")" ::: "memory")
; #define PG8_BAR __builtin_amdgcn_s_barrier()
; #define PG8_SCHED __builtin_amdgcn_sched_barrier(0)
; template <class Epi, class Sched, bool ALIGN_EPI = false, bool SP2 = false>
; __device__ __forceinline__ void gemm_phase(PG8_LAS unsigned char* lds, const Gemm g, const Sched& S, const Epi& E) {
;     ...
;             PG8_LDA(At, 1, 1); PG8_STAGE(PG8_SB(1, 0), b3, voffB); PG8_STAGE(PG8_SB(1, 1), b3 + hstep, voffB); PG8_STAGE(PG8_SA(1, 0), a3, voffA);
;             PG8_WAIT_V(8); PG8_WAIT_L(0); PG8_BAR; PG8_MMA(1, 0, At, B0); PG8_MMA(1, 1, At, B1); PG8_BAR; PG8_SCHED;
;     ...
;         if constexpr (ALIGN_EPI) { if (wr == 0) PG8_BAR; }
	v_mfma_f32_16x16x32_bf16 v[68:71], v[176:179], v[216:219], v[68:71]
	v_mfma_f32_16x16x32_bf16 v[64:67], v[184:187], v[216:219], v[64:67]
	s_setprio 0
	s_add_i32 s46, s65, s33
	v_lshl_add_u64 v[220:221], v[220:221], 0, s[8:9]
	s_mov_b32 m0, s46
	ds_read_b128 v[188:191], v173 offset:49152
	ds_read_b128 v[192:195], v173 offset:50176
	ds_read_b128 v[196:199], v173 offset:51200
	ds_read_b128 v[200:203], v173 offset:52224
	ds_read_b128 v[204:207], v173 offset:53248
	ds_read_b128 v[208:211], v173 offset:54272
	ds_read_b128 v[212:215], v173 offset:55296
	ds_read_b128 v[216:219], v173 offset:56320
	global_load_lds_dwordx4 v[220:221], off
	s_add_i32 m0, s46, 0x2000
	s_add_u32 s44, s44, 0x80080
	v_lshl_add_u64 v[220:221], v[222:223], 0, s[8:9]
	s_addc_u32 s45, s45, 0
	s_add_i32 s46, s66, s33
	global_load_lds_dwordx4 v[220:221], off
	s_mov_b32 m0, s46
	s_nop 0
	global_load_lds_dwordx4 v148, s[44:45]
	s_add_i32 m0, s46, 0x2000
	s_nop 0
	global_load_lds_dwordx4 v152, s[44:45]
	v_lshl_add_u64 v[220:221], v[224:225], 0, s[8:9]
	s_mov_b32 m0, s52
	s_nop 0
	global_load_lds_dwordx4 v[220:221], off
	v_lshl_add_u64 v[220:221], v[226:227], 0, s[8:9]
	s_mov_b32 m0, s53
	s_nop 0
	global_load_lds_dwordx4 v[220:221], off
	s_waitcnt vmcnt(8)
	s_waitcnt lgkmcnt(0)
	s_setprio 1
	s_barrier
	v_mfma_f32_16x16x32_bf16 v[60:63], v[80:83], v[188:191], v[60:63]
	v_mfma_f32_16x16x32_bf16 v[56:59], v[88:91], v[188:191], v[56:59]
	v_mfma_f32_16x16x32_bf16 v[44:47], v[80:83], v[196:199], v[44:47]
	v_mfma_f32_16x16x32_bf16 v[40:43], v[88:91], v[196:199], v[40:43]
	v_mfma_f32_16x16x32_bf16 v[28:31], v[80:83], v[204:207], v[28:31]
	v_mfma_f32_16x16x32_bf16 v[24:27], v[88:91], v[204:207], v[24:27]
	v_mfma_f32_16x16x32_bf16 v[12:15], v[80:83], v[212:215], v[12:15]
	v_mfma_f32_16x16x32_bf16 v[8:11], v[88:91], v[212:215], v[8:11]
	v_mfma_f32_16x16x32_bf16 v[60:63], v[84:87], v[192:195], v[60:63]
	v_mfma_f32_16x16x32_bf16 v[56:59], v[92:95], v[192:195], v[56:59]
	v_mfma_f32_16x16x32_bf16 v[44:47], v[84:87], v[200:203], v[44:47]
	v_mfma_f32_16x16x32_bf16 v[40:43], v[92:95], v[200:203], v[40:43]
	v_mfma_f32_16x16x32_bf16 v[28:31], v[84:87], v[208:211], v[28:31]
	v_mfma_f32_16x16x32_bf16 v[24:27], v[92:95], v[208:211], v[24:27]
	v_mfma_f32_16x16x32_bf16 v[12:15], v[84:87], v[216:219], v[12:15]
	v_mfma_f32_16x16x32_bf16 v[8:11], v[92:95], v[216:219], v[8:11]
	s_setprio 0
	s_setprio 1
	v_mfma_f32_16x16x32_bf16 v[52:55], v[164:167], v[188:191], v[52:55]
	v_mfma_f32_16x16x32_bf16 v[48:51], v[180:183], v[188:191], v[48:51]
	v_mfma_f32_16x16x32_bf16 v[36:39], v[164:167], v[196:199], v[36:39]
	v_mfma_f32_16x16x32_bf16 v[32:35], v[180:183], v[196:199], v[32:35]
	v_mfma_f32_16x16x32_bf16 v[20:23], v[164:167], v[204:207], v[20:23]
	v_mfma_f32_16x16x32_bf16 v[16:19], v[180:183], v[204:207], v[16:19]
	v_mfma_f32_16x16x32_bf16 v[4:7], v[164:167], v[212:215], v[4:7]
	v_mfma_f32_16x16x32_bf16 v[0:3], v[180:183], v[212:215], v[0:3]
	v_mfma_f32_16x16x32_bf16 v[52:55], v[176:179], v[192:195], v[52:55]
	v_mfma_f32_16x16x32_bf16 v[48:51], v[184:187], v[192:195], v[48:51]
	v_mfma_f32_16x16x32_bf16 v[36:39], v[176:179], v[200:203], v[36:39]
	v_mfma_f32_16x16x32_bf16 v[32:35], v[184:187], v[200:203], v[32:35]
	v_mfma_f32_16x16x32_bf16 v[20:23], v[176:179], v[208:211], v[20:23]
	v_mfma_f32_16x16x32_bf16 v[16:19], v[184:187], v[208:211], v[16:19]
	s_setprio 2
	s_barrier
	v_mfma_f32_16x16x32_bf16 v[4:7], v[176:179], v[216:219], v[4:7]
	v_mfma_f32_16x16x32_bf16 v[0:3], v[184:187], v[216:219], v[0:3]
	s_setprio 0
	s_add_i32 s64, s64, 2
	s_add_u32 s42, s42, 0x100
	s_addc_u32 s43, s43, 0
	s_add_u32 s62, s62, 0x100
	s_addc_u32 s63, s63, 0
	s_cmp_gt_u32 s64, 29
	s_cbranch_scc0 .LBB0_1142
	s_and_b64 vcc, exec, s[10:11]
	s_cbranch_vccz .LBB0_1145
	s_barrier

; #define PG8_STAGE(bufoff, gbase, voff) do { _Pragma("unroll") for (int _i = 0; _i < 2; ++_i) \
;         __builtin_amdgcn_global_load_lds((const unsigned*)((const char*)(gbase) + (voff)[_i]), (PG8_LAS unsigned*)(lds + (bufoff) + ldsw + _i * 8192), 16, 0, 0); } while (0)
; #define PG8_LDA(dst, b, h) do { _Pragma("unroll") for (int m = 0; m < 4; ++m) _Pragma("unroll") for (int k = 0; k < 2; ++k) dst[m][k] = *(const PG8_LAS bf16x8*)(lds + PG8_SA(b, h) + aoff + m * 2048 + k * 1024); } while (0)
; #define PG8_LDB(dst, b, h) do { _Pragma("unroll") for (int n = 0; n < 2; ++n) _Pragma("unroll") for (int k = 0; k < 2; ++k) dst[n][k] = *(const PG8_LAS bf16x8*)(lds + PG8_SB(b, h) + boff + n * 2048 + k * 1024); } while (0)
; #define PG8_MMA(ai, bj, At, Bt) do { __builtin_amdgcn_s_setprio(1); _Pragma("unroll") for (int m = 0; m < 4; ++m) _Pragma("unroll") for (int n = 0; n < 2; ++n) _Pragma("unroll") for (int k = 0; k < 2; ++k) \
;         acc[ai][bj][m][n] = __builtin_amdgcn_mfma_f32_16x16x32_bf16(Bt[n][k], At[m][k], acc[ai][bj][m][n], 0, 0, 0); __builtin_amdgcn_s_setprio(0); } while (0)
; #define PG8_WAIT_V(n) asm volatile("s_waitcnt vmcnt(" #n ")" ::: "memory")
; #define PG8_WAIT_L(n) asm volatile("s_waitcnt lgkmcnt(" #n ")" ::: "memory")
; #define PG8_BAR __builtin_amdgcn_s_barrier()
; #define PG8_SCHED __builtin_amdgcn_sched_barrier(0)
; template <class Epi, class Sched, bool ALIGN_EPI = false, bool SP2 = false>
; __device__ __forceinline__ void gemm_phase(PG8_LAS unsigned char* lds, const Gemm g, const Sched& S, const Epi& E) {
;     ...
;             const char* a1 = cA + (size_t)(t + 1) * kstep;
;             const char* a2 = last ? nA : cA + (size_t)(t + 2) * kstep; const char* b2 = last ? nB : cB + (size_t)(t + 2) * kstep;
;             const char* a3 = a2 + kstep; const char* b3 = b2 + kstep;
;             if constexpr (SP2) {
;             PG8_LDB(B0, 0, 0); PG8_LDB(B1, 0, 1); PG8_SCHED; PG8_LDA(At, 0, 0); PG8_STAGE(PG8_SA(1, 1), a1 + hstep, voffA);
;             PG8_WAIT_V(8); PG8_WAIT_L(0); PG8_BAR; PG8_MMA(0, 0, At, B0); PG8_MMA(0, 1, At, B1); PG8_BAR; PG8_SCHED;
;             PG8_LDA(At, 0, 1); PG8_STAGE(PG8_SB(0, 0), b2, voffB); PG8_STAGE(PG8_SB(0, 1), b2 + hstep, voffB); PG8_STAGE(PG8_SA(0, 0), a2, voffA);
;             PG8_WAIT_V(8); PG8_WAIT_L(0); PG8_BAR; PG8_MMA(1, 0, At, B0); PG8_MMA(1, 1, At, B1); PG8_BAR; PG8_SCHED;
.LBB0_1219:
	ds_read_b128 v[128:131], v167
	ds_read_b128 v[132:135], v167 offset:1024
	ds_read_b128 v[154:157], v167 offset:2048
	ds_read_b128 v[158:161], v167 offset:3072
	ds_read_b128 v[170:173], v168
	ds_read_b128 v[174:177], v168 offset:1024
	ds_read_b128 v[178:181], v168 offset:2048
	ds_read_b128 v[182:185], v168 offset:3072
	s_add_u32 s42, s40, 0xffe00080
	s_addc_u32 s43, s41, -1
	s_cmpk_eq_i32 s63, 0x7c
	s_cselect_b32 s45, s15, s43
	s_cselect_b32 s44, s59, s42
	s_cselect_b32 s43, s13, s62
	s_cselect_b32 s42, s60, s61
	s_add_i32 m0, s39, 0xc000
	ds_read_b128 v[186:189], v169
	ds_read_b128 v[190:193], v169 offset:1024
	ds_read_b128 v[194:197], v169 offset:2048
	ds_read_b128 v[198:201], v169 offset:3072
	ds_read_b128 v[202:205], v169 offset:4096
	ds_read_b128 v[206:209], v169 offset:5120
	ds_read_b128 v[210:213], v169 offset:6144
	ds_read_b128 v[214:217], v169 offset:7168
	global_load_lds_dwordx4 v144, s[40:41]
	s_add_i32 m0, s39, 0xe000
	s_nop 0
	global_load_lds_dwordx4 v148, s[40:41]
	s_waitcnt vmcnt(8)
	s_waitcnt lgkmcnt(0)
	s_setprio 1
	s_barrier
	v_mfma_f32_16x16x32_bf16 v[124:127], v[128:131], v[186:189], v[124:127]
	v_mfma_f32_16x16x32_bf16 v[120:123], v[154:157], v[186:189], v[120:123]
	v_mfma_f32_16x16x32_bf16 v[116:119], v[128:131], v[194:197], v[116:119]
	v_mfma_f32_16x16x32_bf16 v[112:115], v[154:157], v[194:197], v[112:115]
	v_mfma_f32_16x16x32_bf16 v[108:111], v[128:131], v[202:205], v[108:111]
	v_mfma_f32_16x16x32_bf16 v[104:107], v[154:157], v[202:205], v[104:107]
	v_mfma_f32_16x16x32_bf16 v[100:103], v[128:131], v[210:213], v[100:103]
	v_mfma_f32_16x16x32_bf16 v[96:99], v[154:157], v[210:213], v[96:99]
	v_mfma_f32_16x16x32_bf16 v[124:127], v[132:135], v[190:193], v[124:127]
	v_mfma_f32_16x16x32_bf16 v[120:123], v[158:161], v[190:193], v[120:123]
	v_mfma_f32_16x16x32_bf16 v[116:119], v[132:135], v[198:201], v[116:119]
	v_mfma_f32_16x16x32_bf16 v[112:115], v[158:161], v[198:201], v[112:115]
	v_mfma_f32_16x16x32_bf16 v[108:111], v[132:135], v[206:209], v[108:111]
	v_mfma_f32_16x16x32_bf16 v[104:107], v[158:161], v[206:209], v[104:107]
	v_mfma_f32_16x16x32_bf16 v[100:103], v[132:135], v[214:217], v[100:103]
	v_mfma_f32_16x16x32_bf16 v[96:99], v[158:161], v[214:217], v[96:99]
	s_setprio 0
	s_setprio 1
	v_mfma_f32_16x16x32_bf16 v[68:71], v[170:173], v[186:189], v[68:71]
	v_mfma_f32_16x16x32_bf16 v[60:63], v[178:181], v[186:189], v[60:63]
	v_mfma_f32_16x16x32_bf16 v[52:55], v[170:173], v[194:197], v[52:55]
	v_mfma_f32_16x16x32_bf16 v[48:51], v[178:181], v[194:197], v[48:51]
	v_mfma_f32_16x16x32_bf16 v[44:47], v[170:173], v[202:205], v[44:47]
	v_mfma_f32_16x16x32_bf16 v[40:43], v[178:181], v[202:205], v[40:43]
	v_mfma_f32_16x16x32_bf16 v[36:39], v[170:173], v[210:213], v[36:39]
	v_mfma_f32_16x16x32_bf16 v[32:35], v[178:181], v[210:213], v[32:35]
	v_mfma_f32_16x16x32_bf16 v[68:71], v[174:177], v[190:193], v[68:71]
	v_mfma_f32_16x16x32_bf16 v[60:63], v[182:185], v[190:193], v[60:63]
	v_mfma_f32_16x16x32_bf16 v[52:55], v[174:177], v[198:201], v[52:55]
	v_mfma_f32_16x16x32_bf16 v[48:51], v[182:185], v[198:201], v[48:51]
	v_mfma_f32_16x16x32_bf16 v[44:47], v[174:177], v[206:209], v[44:47]
	v_mfma_f32_16x16x32_bf16 v[40:43], v[182:185], v[206:209], v[40:43]
	s_setprio 2
	s_barrier
	v_mfma_f32_16x16x32_bf16 v[36:39], v[174:177], v[214:217], v[36:39]
	v_mfma_f32_16x16x32_bf16 v[32:35], v[182:185], v[214:217], v[32:35]
	s_setprio 0
	s_add_i32 s64, s56, s33
	v_lshl_add_u64 v[162:163], s[42:43], 0, v[138:139]
	s_mov_b32 m0, s64
	ds_read_b128 v[186:189], v169 offset:16384
	ds_read_b128 v[190:193], v169 offset:17408
	ds_read_b128 v[194:197], v169 offset:18432
	ds_read_b128 v[198:201], v169 offset:19456
	ds_read_b128 v[202:205], v169 offset:20480
	ds_read_b128 v[206:209], v169 offset:21504
	ds_read_b128 v[210:213], v169 offset:22528
	ds_read_b128 v[214:217], v169 offset:23552
	global_load_lds_dwordx4 v[162:163], off
	s_add_i32 m0, s64, 0x2000
	s_add_u32 s64, s42, 0x200000
	v_lshl_add_u64 v[218:219], s[42:43], 0, v[142:143]
	s_addc_u32 s65, s43, 0
	s_add_i32 s66, s57, s33
	global_load_lds_dwordx4 v[218:219], off
	s_mov_b32 m0, s66
	v_lshl_add_u64 v[222:223], s[44:45], 0, v[140:141]
	global_load_lds_dwordx4 v138, s[64:65]
	s_add_i32 m0, s66, 0x2000
	s_nop 0
	global_load_lds_dwordx4 v142, s[64:65]
	v_lshl_add_u64 v[220:221], s[44:45], 0, v[136:137]
	s_mov_b32 m0, s39
	s_nop 0
	global_load_lds_dwordx4 v[220:221], off
	s_mov_b32 m0, s46
	s_nop 0
	global_load_lds_dwordx4 v[222:223], off
	s_waitcnt vmcnt(8)
	s_waitcnt lgkmcnt(0)
	s_setprio 1
	s_barrier
	v_mfma_f32_16x16x32_bf16 v[92:95], v[128:131], v[186:189], v[92:95]
	v_mfma_f32_16x16x32_bf16 v[88:91], v[154:157], v[186:189], v[88:91]
	v_mfma_f32_16x16x32_bf16 v[84:87], v[128:131], v[194:197], v[84:87]
	v_mfma_f32_16x16x32_bf16 v[80:83], v[154:157], v[194:197], v[80:83]
	v_mfma_f32_16x16x32_bf16 v[76:79], v[128:131], v[202:205], v[76:79]
	v_mfma_f32_16x16x32_bf16 v[72:75], v[154:157], v[202:205], v[72:75]
	v_mfma_f32_16x16x32_bf16 v[64:67], v[128:131], v[210:213], v[64:67]
	v_mfma_f32_16x16x32_bf16 v[56:59], v[154:157], v[210:213], v[56:59]
	v_mfma_f32_16x16x32_bf16 v[92:95], v[132:135], v[190:193], v[92:95]
	v_mfma_f32_16x16x32_bf16 v[88:91], v[158:161], v[190:193], v[88:91]
	v_mfma_f32_16x16x32_bf16 v[84:87], v[132:135], v[198:201], v[84:87]
	v_mfma_f32_16x16x32_bf16 v[80:83], v[158:161], v[198:201], v[80:83]
	v_mfma_f32_16x16x32_bf16 v[76:79], v[132:135], v[206:209], v[76:79]
	v_mfma_f32_16x16x32_bf16 v[72:75], v[158:161], v[206:209], v[72:75]
	v_mfma_f32_16x16x32_bf16 v[64:67], v[132:135], v[214:217], v[64:67]
	v_mfma_f32_16x16x32_bf16 v[56:59], v[158:161], v[214:217], v[56:59]
	s_setprio 0
	s_setprio 1
	v_mfma_f32_16x16x32_bf16 v[28:31], v[170:173], v[186:189], v[28:31]
	v_mfma_f32_16x16x32_bf16 v[24:27], v[178:181], v[186:189], v[24:27]
	v_mfma_f32_16x16x32_bf16 v[20:23], v[170:173], v[194:197], v[20:23]
	v_mfma_f32_16x16x32_bf16 v[16:19], v[178:181], v[194:197], v[16:19]
	v_mfma_f32_16x16x32_bf16 v[12:15], v[170:173], v[202:205], v[12:15]
	v_mfma_f32_16x16x32_bf16 v[8:11], v[178:181], v[202:205], v[8:11]
	v_mfma_f32_16x16x32_bf16 v[4:7], v[170:173], v[210:213], v[4:7]
	v_mfma_f32_16x16x32_bf16 v[0:3], v[178:181], v[210:213], v[0:3]
	v_mfma_f32_16x16x32_bf16 v[28:31], v[174:177], v[190:193], v[28:31]
	v_mfma_f32_16x16x32_bf16 v[24:27], v[182:185], v[190:193], v[24:27]
	v_mfma_f32_16x16x32_bf16 v[20:23], v[174:177], v[198:201], v[20:23]
	v_mfma_f32_16x16x32_bf16 v[16:19], v[182:185], v[198:201], v[16:19]
	v_mfma_f32_16x16x32_bf16 v[12:15], v[174:177], v[206:209], v[12:15]
	v_mfma_f32_16x16x32_bf16 v[8:11], v[182:185], v[206:209], v[8:11]
	s_setprio 2
	s_barrier
; #define PG8_STAGE(bufoff, gbase, voff) do { _Pragma("unroll") for (int _i = 0; _i < 2; ++_i) \
;         __builtin_amdgcn_global_load_lds((const unsigned*)((const char*)(gbase) + (voff)[_i]), (PG8_LAS unsigned*)(lds + (bufoff) + ldsw + _i * 8192), 16, 0, 0); } while (0)
; #define PG8_LDA(dst, b, h) do { _Pragma("unroll") for (int m = 0; m < 4; ++m) _Pragma("unroll") for (int k = 0; k < 2; ++k) dst[m][k] = *(const PG8_LAS bf16x8*)(lds + PG8_SA(b, h) + aoff + m * 2048 + k * 1024); } while (0)
; #define PG8_LDB(dst, b, h) do { _Pragma("unroll") for (int n = 0; n < 2; ++n) _Pragma("unroll") for (int k = 0; k < 2; ++k) dst[n][k] = *(const PG8_LAS bf16x8*)(lds + PG8_SB(b, h) + boff + n * 2048 + k * 1024); } while (0)
; #define PG8_MMA(ai, bj, At, Bt) do { __builtin_amdgcn_s_setprio(1); _Pragma("unroll") for (int m = 0; m < 4; ++m) _Pragma("unroll") for (int n = 0; n < 2; ++n) _Pragma("unroll") for (int k = 0; k < 2; ++k) \
;         acc[ai][bj][m][n] = __builtin_amdgcn_mfma_f32_16x16x32_bf16(Bt[n][k], At[m][k], acc[ai][bj][m][n], 0, 0, 0); __builtin_amdgcn_s_setprio(0); } while (0)
; #define PG8_WAIT_V(n) asm volatile("s_waitcnt vmcnt(" #n ")" ::: "memory")
; #define PG8_WAIT_L(n) asm volatile("s_waitcnt lgkmcnt(" #n ")" ::: "memory")
; #define PG8_BAR __builtin_amdgcn_s_barrier()
; #define PG8_SCHED __builtin_amdgcn_sched_barrier(0)
; template <class Epi, class Sched, bool ALIGN_EPI = false, bool SP2 = false>
; __device__ __forceinline__ void gemm_phase(PG8_LAS unsigned char* lds, const Gemm g, const Sched& S, const Epi& E) {
;     ...
;             PG8_WAIT_V(8); PG8_WAIT_L(0); PG8_BAR; PG8_MMA(1, 0, At, B0); PG8_MMA(1, 1, At, B1); PG8_BAR; PG8_SCHED;
;             PG8_LDB(B0, 1, 0); PG8_LDB(B1, 1, 1); PG8_SCHED; PG8_LDA(At, 1, 0); PG8_STAGE(PG8_SA(0, 1), a2 + hstep, voffA);
;             PG8_WAIT_V(8); PG8_WAIT_L(0); PG8_BAR; PG8_MMA(0, 0, At, B0); PG8_MMA(0, 1, At, B1); PG8_BAR; PG8_SCHED;
	v_mfma_f32_16x16x32_bf16 v[4:7], v[174:177], v[214:217], v[4:7]
	v_mfma_f32_16x16x32_bf16 v[0:3], v[182:185], v[214:217], v[0:3]
	s_setprio 0
	s_add_i32 s64, 0, 0x18000
	s_add_i32 s65, 0, 0x1c000
	v_add_u32_e32 v158, s64, v165
	v_add_u32_e32 v182, s65, v165
	ds_read_b128 v[128:131], v158
	ds_read_b128 v[132:135], v158 offset:1024
	ds_read_b128 v[154:157], v158 offset:2048
	ds_read_b128 v[158:161], v158 offset:3072
	ds_read_b128 v[170:173], v182
	ds_read_b128 v[174:177], v182 offset:1024
	ds_read_b128 v[178:181], v182 offset:2048
	ds_read_b128 v[182:185], v182 offset:3072
	s_add_u32 s44, s44, 0x200000
	s_addc_u32 s45, s45, 0
	s_mov_b32 m0, s47
	ds_read_b128 v[186:189], v169 offset:32768
	ds_read_b128 v[190:193], v169 offset:33792
	ds_read_b128 v[194:197], v169 offset:34816
	ds_read_b128 v[198:201], v169 offset:35840
	ds_read_b128 v[202:205], v169 offset:36864
	ds_read_b128 v[206:209], v169 offset:37888
	ds_read_b128 v[210:213], v169 offset:38912
	ds_read_b128 v[214:217], v169 offset:39936
	global_load_lds_dwordx4 v136, s[44:45]
	s_mov_b32 m0, s48
	s_nop 0
	global_load_lds_dwordx4 v140, s[44:45]
	s_waitcnt vmcnt(8)
	s_waitcnt lgkmcnt(0)
	s_setprio 1
	s_barrier
	v_mfma_f32_16x16x32_bf16 v[124:127], v[128:131], v[186:189], v[124:127]
	v_mfma_f32_16x16x32_bf16 v[120:123], v[154:157], v[186:189], v[120:123]
	v_mfma_f32_16x16x32_bf16 v[116:119], v[128:131], v[194:197], v[116:119]
	v_mfma_f32_16x16x32_bf16 v[112:115], v[154:157], v[194:197], v[112:115]
	v_mfma_f32_16x16x32_bf16 v[108:111], v[128:131], v[202:205], v[108:111]
	v_mfma_f32_16x16x32_bf16 v[104:107], v[154:157], v[202:205], v[104:107]
	v_mfma_f32_16x16x32_bf16 v[100:103], v[128:131], v[210:213], v[100:103]
	v_mfma_f32_16x16x32_bf16 v[96:99], v[154:157], v[210:213], v[96:99]
	v_mfma_f32_16x16x32_bf16 v[124:127], v[132:135], v[190:193], v[124:127]
	v_mfma_f32_16x16x32_bf16 v[120:123], v[158:161], v[190:193], v[120:123]
	v_mfma_f32_16x16x32_bf16 v[116:119], v[132:135], v[198:201], v[116:119]
	v_mfma_f32_16x16x32_bf16 v[112:115], v[158:161], v[198:201], v[112:115]
	v_mfma_f32_16x16x32_bf16 v[108:111], v[132:135], v[206:209], v[108:111]
	v_mfma_f32_16x16x32_bf16 v[104:107], v[158:161], v[206:209], v[104:107]
	v_mfma_f32_16x16x32_bf16 v[100:103], v[132:135], v[214:217], v[100:103]
	v_mfma_f32_16x16x32_bf16 v[96:99], v[158:161], v[214:217], v[96:99]
	s_setprio 0
	s_setprio 1
	v_mfma_f32_16x16x32_bf16 v[68:71], v[170:173], v[186:189], v[68:71]
	v_mfma_f32_16x16x32_bf16 v[60:63], v[178:181], v[186:189], v[60:63]
	v_mfma_f32_16x16x32_bf16 v[52:55], v[170:173], v[194:197], v[52:55]
	v_mfma_f32_16x16x32_bf16 v[48:51], v[178:181], v[194:197], v[48:51]
	v_mfma_f32_16x16x32_bf16 v[44:47], v[170:173], v[202:205], v[44:47]
	v_mfma_f32_16x16x32_bf16 v[40:43], v[178:181], v[202:205], v[40:43]
	v_mfma_f32_16x16x32_bf16 v[36:39], v[170:173], v[210:213], v[36:39]
	v_mfma_f32_16x16x32_bf16 v[32:35], v[178:181], v[210:213], v[32:35]
	v_mfma_f32_16x16x32_bf16 v[68:71], v[174:177], v[190:193], v[68:71]
	v_mfma_f32_16x16x32_bf16 v[60:63], v[182:185], v[190:193], v[60:63]
	v_mfma_f32_16x16x32_bf16 v[52:55], v[174:177], v[198:201], v[52:55]
	v_mfma_f32_16x16x32_bf16 v[48:51], v[182:185], v[198:201], v[48:51]
	v_mfma_f32_16x16x32_bf16 v[44:47], v[174:177], v[206:209], v[44:47]
	v_mfma_f32_16x16x32_bf16 v[40:43], v[182:185], v[206:209], v[40:43]
	s_setprio 2
	s_barrier
; #define PG8_STAGE(bufoff, gbase, voff) do { _Pragma("unroll") for (int _i = 0; _i < 2; ++_i) \
;         __builtin_amdgcn_global_load_lds((const unsigned*)((const char*)(gbase) + (voff)[_i]), (PG8_LAS unsigned*)(lds + (bufoff) + ldsw + _i * 8192), 16, 0, 0); } while (0)
; #define PG8_LDA(dst, b, h) do { _Pragma("unroll") for (int m = 0; m < 4; ++m) _Pragma("unroll") for (int k = 0; k < 2; ++k) dst[m][k] = *(const PG8_LAS bf16x8*)(lds + PG8_SA(b, h) + aoff + m * 2048 + k * 1024); } while (0)
; #define PG8_MMA(ai, bj, At, Bt) do { __builtin_amdgcn_s_setprio(1); _Pragma("unroll") for (int m = 0; m < 4; ++m) _Pragma("unroll") for (int n = 0; n < 2; ++n) _Pragma("unroll") for (int k = 0; k < 2; ++k) \
;         acc[ai][bj][m][n] = __builtin_amdgcn_mfma_f32_16x16x32_bf16(Bt[n][k], At[m][k], acc[ai][bj][m][n], 0, 0, 0); __builtin_amdgcn_s_setprio(0); } while (0)
; #define PG8_WAIT_V(n) asm volatile("s_waitcnt vmcnt(" #n ")" ::: "memory")
; #define PG8_WAIT_L(n) asm volatile("s_waitcnt lgkmcnt(" #n ")" ::: "memory")
; #define PG8_BAR __builtin_amdgcn_s_barrier()
; #define PG8_SCHED __builtin_amdgcn_sched_barrier(0)
; template <class Epi, class Sched, bool ALIGN_EPI = false, bool SP2 = false>
; __device__ __forceinline__ void gemm_phase(PG8_LAS unsigned char* lds, const Gemm g, const Sched& S, const Epi& E) {
;     ...
;             PG8_WAIT_V(8); PG8_WAIT_L(0); PG8_BAR; PG8_MMA(0, 0, At, B0); PG8_MMA(0, 1, At, B1); PG8_BAR; PG8_SCHED;
;             PG8_LDA(At, 1, 1); PG8_STAGE(PG8_SB(1, 0), b3, voffB); PG8_STAGE(PG8_SB(1, 1), b3 + hstep, voffB); PG8_STAGE(PG8_SA(1, 0), a3, voffA);
;             PG8_WAIT_V(8); PG8_WAIT_L(0); PG8_BAR; PG8_MMA(1, 0, At, B0); PG8_MMA(1, 1, At, B1); PG8_BAR; PG8_SCHED;
	v_mfma_f32_16x16x32_bf16 v[36:39], v[174:177], v[214:217], v[36:39]
	v_mfma_f32_16x16x32_bf16 v[32:35], v[182:185], v[214:217], v[32:35]
	s_setprio 0
	s_add_i32 s44, s64, s33
	v_lshl_add_u64 v[162:163], v[162:163], 0, s[8:9]
	s_mov_b32 m0, s44
	ds_read_b128 v[186:189], v169 offset:49152
	ds_read_b128 v[190:193], v169 offset:50176
	ds_read_b128 v[194:197], v169 offset:51200
	ds_read_b128 v[198:201], v169 offset:52224
	ds_read_b128 v[202:205], v169 offset:53248
	ds_read_b128 v[206:209], v169 offset:54272
	ds_read_b128 v[210:213], v169 offset:55296
	ds_read_b128 v[214:217], v169 offset:56320
	global_load_lds_dwordx4 v[162:163], off
	s_add_i32 m0, s44, 0x2000
	s_add_u32 s42, s42, 0x200080
	v_lshl_add_u64 v[162:163], v[218:219], 0, s[8:9]
	s_addc_u32 s43, s43, 0
	s_add_i32 s44, s65, s33
	global_load_lds_dwordx4 v[162:163], off
	s_mov_b32 m0, s44
	s_nop 0
	global_load_lds_dwordx4 v138, s[42:43]
	s_add_i32 m0, s44, 0x2000
	s_nop 0
	global_load_lds_dwordx4 v142, s[42:43]
	v_lshl_add_u64 v[162:163], v[220:221], 0, s[8:9]
	s_mov_b32 m0, s52
	s_nop 0
	global_load_lds_dwordx4 v[162:163], off
	v_lshl_add_u64 v[162:163], v[222:223], 0, s[8:9]
	s_mov_b32 m0, s53
	s_nop 0
	global_load_lds_dwordx4 v[162:163], off
	s_waitcnt vmcnt(8)
	s_waitcnt lgkmcnt(0)
	s_setprio 1
	s_barrier
	v_mfma_f32_16x16x32_bf16 v[92:95], v[128:131], v[186:189], v[92:95]
	v_mfma_f32_16x16x32_bf16 v[88:91], v[154:157], v[186:189], v[88:91]
	v_mfma_f32_16x16x32_bf16 v[84:87], v[128:131], v[194:197], v[84:87]
	v_mfma_f32_16x16x32_bf16 v[80:83], v[154:157], v[194:197], v[80:83]
	v_mfma_f32_16x16x32_bf16 v[76:79], v[128:131], v[202:205], v[76:79]
	v_mfma_f32_16x16x32_bf16 v[72:75], v[154:157], v[202:205], v[72:75]
	v_mfma_f32_16x16x32_bf16 v[64:67], v[128:131], v[210:213], v[64:67]
	v_mfma_f32_16x16x32_bf16 v[56:59], v[154:157], v[210:213], v[56:59]
	v_mfma_f32_16x16x32_bf16 v[92:95], v[132:135], v[190:193], v[92:95]
	v_mfma_f32_16x16x32_bf16 v[88:91], v[158:161], v[190:193], v[88:91]
	v_mfma_f32_16x16x32_bf16 v[84:87], v[132:135], v[198:201], v[84:87]
	v_mfma_f32_16x16x32_bf16 v[80:83], v[158:161], v[198:201], v[80:83]
	v_mfma_f32_16x16x32_bf16 v[76:79], v[132:135], v[206:209], v[76:79]
	v_mfma_f32_16x16x32_bf16 v[72:75], v[158:161], v[206:209], v[72:75]
	v_mfma_f32_16x16x32_bf16 v[64:67], v[132:135], v[214:217], v[64:67]
	v_mfma_f32_16x16x32_bf16 v[56:59], v[158:161], v[214:217], v[56:59]
	s_setprio 0
	s_setprio 1
	v_mfma_f32_16x16x32_bf16 v[28:31], v[170:173], v[186:189], v[28:31]
	v_mfma_f32_16x16x32_bf16 v[24:27], v[178:181], v[186:189], v[24:27]
	v_mfma_f32_16x16x32_bf16 v[20:23], v[170:173], v[194:197], v[20:23]
	v_mfma_f32_16x16x32_bf16 v[16:19], v[178:181], v[194:197], v[16:19]
	v_mfma_f32_16x16x32_bf16 v[12:15], v[170:173], v[202:205], v[12:15]
	v_mfma_f32_16x16x32_bf16 v[8:11], v[178:181], v[202:205], v[8:11]
	v_mfma_f32_16x16x32_bf16 v[4:7], v[170:173], v[210:213], v[4:7]
	v_mfma_f32_16x16x32_bf16 v[0:3], v[178:181], v[210:213], v[0:3]
	v_mfma_f32_16x16x32_bf16 v[28:31], v[174:177], v[190:193], v[28:31]
	v_mfma_f32_16x16x32_bf16 v[24:27], v[182:185], v[190:193], v[24:27]
	v_mfma_f32_16x16x32_bf16 v[20:23], v[174:177], v[198:201], v[20:23]
	v_mfma_f32_16x16x32_bf16 v[16:19], v[182:185], v[198:201], v[16:19]
	v_mfma_f32_16x16x32_bf16 v[12:15], v[174:177], v[206:209], v[12:15]
	v_mfma_f32_16x16x32_bf16 v[8:11], v[182:185], v[206:209], v[8:11]
	s_setprio 2
	s_barrier
	v_mfma_f32_16x16x32_bf16 v[4:7], v[174:177], v[214:217], v[4:7]
	v_mfma_f32_16x16x32_bf16 v[0:3], v[182:185], v[214:217], v[0:3]
	s_setprio 0
	s_add_i32 s63, s63, 2
	s_add_u32 s40, s40, 0x100
	s_addc_u32 s41, s41, 0
	s_add_u32 s61, s61, 0x100
	s_addc_u32 s62, s62, 0
	s_cmpk_gt_u32 s63, 0x7d
	s_cbranch_scc0 .LBB0_1219
	s_and_b64 vcc, exec, s[10:11]
	s_cbranch_vccz .LBB0_1222
	s_barrier
